# code placement: the 14 GEMM K-loop heads aligned to 64 bytes (.p2align 6)
# baseline (speedup 1.0000x reference)
; #define PG8_STAGE(bufoff, gbase, voff) do { _Pragma("unroll") for (int _i = 0; _i < 2; ++_i) \
;         __builtin_amdgcn_global_load_lds((const unsigned*)((const char*)(gbase) + (voff)[_i]), (PG8_LAS unsigned*)(lds + (bufoff) + ldsw + _i * 8192), 16, 0, 0); } while (0)
; #define PG8_LDA(dst, b, h) do { _Pragma("unroll") for (int m = 0; m < 4; ++m) _Pragma("unroll") for (int k = 0; k < 2; ++k) dst[m][k] = *(const PG8_LAS bf16x8*)(lds + PG8_SA(b, h) + aoff + m * 2048 + k * 1024); } while (0)
; #define PG8_LDB(dst, b, h) do { _Pragma("unroll") for (int n = 0; n < 2; ++n) _Pragma("unroll") for (int k = 0; k < 2; ++k) dst[n][k] = *(const PG8_LAS bf16x8*)(lds + PG8_SB(b, h) + boff + n * 2048 + k * 1024); } while (0)
; #define PG8_WAIT_V(n) asm volatile("s_waitcnt vmcnt(" #n ")" ::: "memory")
; #define PG8_WAIT_L(n) asm volatile("s_waitcnt lgkmcnt(" #n ")" ::: "memory")
; #define PG8_BAR __builtin_amdgcn_s_barrier()
; #define PG8_SCHED __builtin_amdgcn_sched_barrier(0)
; template <class Epi, class Sched, bool ALIGN_EPI = false, bool SP2 = false>
; __device__ __forceinline__ void gemm_phase(PG8_LAS unsigned char* lds, const Gemm g, const Sched& S, const Epi& E) {
;     ...
;         const bool has_next = S.next(ui + 1, nxt);
;         const char* nA = has_next ? (const char*)g.A + (size_t)nxt.pm * tstep : cA; const char* nB = has_next ? (const char*)g.Bt + (size_t)nxt.pn * tstep : cB;
;         for (int t = 0; t < nt; t += 2) {
;             const bool last = (t == nt - 2);
;             const char* a1 = cA + (size_t)(t + 1) * kstep;
;             const char* a2 = last ? nA : cA + (size_t)(t + 2) * kstep; const char* b2 = last ? nB : cB + (size_t)(t + 2) * kstep;
;             const char* a3 = a2 + kstep; const char* b3 = b2 + kstep;
;             if (last && has_next) S.a_ready(nxt, ui + 1);
;             if constexpr (SP2) {
;             PG8_LDB(B0, 0, 0); PG8_LDB(B1, 0, 1); PG8_SCHED; PG8_LDA(At, 0, 0); PG8_STAGE(PG8_SA(1, 1), a1 + hstep, voffA);
;             PG8_WAIT_V(8); PG8_WAIT_L(0); PG8_BAR; PG8_MMA(0, 0, At, B0); PG8_MMA(0, 1, At, B1); PG8_BAR; PG8_SCHED;
;             PG8_LDA(At, 0, 1); PG8_STAGE(PG8_SB(0, 0), b2, voffB); PG8_STAGE(PG8_SB(0, 1), b2 + hstep, voffB); PG8_STAGE(PG8_SA(0, 0), a2, voffA);
;             PG8_WAIT_V(8); PG8_WAIT_L(0); PG8_BAR; PG8_MMA(1, 0, At, B0); PG8_MMA(1, 1, At, B1); PG8_BAR; PG8_SCHED;
.LBB0_336:
	s_ashr_i32 s17, s16, 31
	s_lshl_b64 s[18:19], s[16:17], 19
	s_add_u32 s18, s36, s18
	s_addc_u32 s19, s37, s19
	s_and_b64 s[20:21], s[0:1], exec
	s_cselect_b32 s17, s19, s25
	s_cselect_b32 s50, s18, s24
	s_ashr_i32 s15, s14, 31
	s_lshl_b64 s[20:21], s[14:15], 19
	s_add_u32 s20, s34, s20
	s_addc_u32 s21, s35, s21
	s_and_b64 s[28:29], s[0:1], exec
	s_cselect_b32 s15, s21, s27
	s_cselect_b32 s51, s20, s26
	s_add_u32 s24, s24, 0x40080
	s_addc_u32 s25, s25, 0
	s_add_u32 s52, s26, 0x100
	s_addc_u32 s53, s27, 0
	s_mov_b32 s54, -2
	s_add_u32 s26, s24, 0xfffc0080
	s_addc_u32 s27, s25, -1
	s_cmp_eq_u32 s54, 12
	s_cselect_b32 s29, s17, s27
	s_cselect_b32 s28, s50, s26
	s_cselect_b32 s27, s15, s53
	s_cselect_b32 s26, s51, s52
	s_add_i32 m0, s23, 0xc000
	s_nop 0
	global_load_lds_dwordx4 v136, s[24:25]
	s_add_i32 m0, s23, 0xe000
	s_nop 0
	global_load_lds_dwordx4 v138, s[24:25]
	s_waitcnt vmcnt(8)
	s_waitcnt lgkmcnt(0)
	s_setprio 1
	s_barrier
	v_mfma_f32_16x16x32_bf16 v[124:127], v[152:155], v[184:187], 0
	v_mfma_f32_16x16x32_bf16 v[120:123], v[160:163], v[184:187], 0
	v_mfma_f32_16x16x32_bf16 v[108:111], v[152:155], v[192:195], 0
	v_mfma_f32_16x16x32_bf16 v[104:107], v[160:163], v[192:195], 0
	v_mfma_f32_16x16x32_bf16 v[92:95], v[152:155], v[200:203], 0
	v_mfma_f32_16x16x32_bf16 v[88:91], v[160:163], v[200:203], 0
	v_mfma_f32_16x16x32_bf16 v[76:79], v[152:155], v[208:211], 0
	v_mfma_f32_16x16x32_bf16 v[72:75], v[160:163], v[208:211], 0
	v_mfma_f32_16x16x32_bf16 v[124:127], v[156:159], v[188:191], v[124:127]
	v_mfma_f32_16x16x32_bf16 v[120:123], v[164:167], v[188:191], v[120:123]
	v_mfma_f32_16x16x32_bf16 v[108:111], v[156:159], v[196:199], v[108:111]
	v_mfma_f32_16x16x32_bf16 v[104:107], v[164:167], v[196:199], v[104:107]
	v_mfma_f32_16x16x32_bf16 v[92:95], v[156:159], v[204:207], v[92:95]
	v_mfma_f32_16x16x32_bf16 v[88:91], v[164:167], v[204:207], v[88:91]
	v_mfma_f32_16x16x32_bf16 v[76:79], v[156:159], v[212:215], v[76:79]
	v_mfma_f32_16x16x32_bf16 v[72:75], v[164:167], v[212:215], v[72:75]
	v_mfma_f32_16x16x32_bf16 v[116:119], v[168:171], v[184:187], 0
	v_mfma_f32_16x16x32_bf16 v[112:115], v[176:179], v[184:187], 0
	v_mfma_f32_16x16x32_bf16 v[100:103], v[168:171], v[192:195], 0
	v_mfma_f32_16x16x32_bf16 v[96:99], v[176:179], v[192:195], 0
	v_mfma_f32_16x16x32_bf16 v[84:87], v[168:171], v[200:203], 0
	v_mfma_f32_16x16x32_bf16 v[80:83], v[176:179], v[200:203], 0
	v_mfma_f32_16x16x32_bf16 v[68:71], v[168:171], v[208:211], 0
	v_mfma_f32_16x16x32_bf16 v[64:67], v[176:179], v[208:211], 0
	v_mfma_f32_16x16x32_bf16 v[116:119], v[172:175], v[188:191], v[116:119]
	v_mfma_f32_16x16x32_bf16 v[112:115], v[180:183], v[188:191], v[112:115]
	v_mfma_f32_16x16x32_bf16 v[100:103], v[172:175], v[196:199], v[100:103]
	v_mfma_f32_16x16x32_bf16 v[96:99], v[180:183], v[196:199], v[96:99]
	v_mfma_f32_16x16x32_bf16 v[84:87], v[172:175], v[204:207], v[84:87]
	v_mfma_f32_16x16x32_bf16 v[80:83], v[180:183], v[204:207], v[80:83]
	v_mfma_f32_16x16x32_bf16 v[68:71], v[172:175], v[212:215], v[68:71]
	v_mfma_f32_16x16x32_bf16 v[64:67], v[180:183], v[212:215], v[64:67]
	s_barrier
	s_setprio 0
	s_add_i32 s55, s44, s33
	v_lshl_add_u64 v[216:217], s[26:27], 0, v[132:133]
	s_mov_b32 m0, s55
	ds_read_b128 v[184:187], v150 offset:16384
	ds_read_b128 v[188:191], v150 offset:17408
	ds_read_b128 v[192:195], v150 offset:18432
	ds_read_b128 v[196:199], v150 offset:19456
	ds_read_b128 v[200:203], v150 offset:20480
	ds_read_b128 v[204:207], v150 offset:21504
	ds_read_b128 v[208:211], v150 offset:22528
	ds_read_b128 v[212:215], v150 offset:23552
	global_load_lds_dwordx4 v[216:217], off
	s_add_i32 m0, s55, 0x2000
	s_add_u32 s56, s26, 0x40000
	v_lshl_add_u64 v[218:219], s[26:27], 0, v[128:129]
	s_addc_u32 s57, s27, 0
	s_add_i32 s55, s45, s33
	global_load_lds_dwordx4 v[218:219], off
	s_mov_b32 m0, s55
	v_lshl_add_u64 v[222:223], s[28:29], 0, v[130:131]
	global_load_lds_dwordx4 v132, s[56:57]
	s_add_i32 m0, s55, 0x2000
	s_nop 0
	global_load_lds_dwordx4 v128, s[56:57]
	v_lshl_add_u64 v[220:221], s[28:29], 0, v[134:135]
	s_mov_b32 m0, s23
	s_nop 0
	global_load_lds_dwordx4 v[220:221], off
	s_mov_b32 m0, s39
	s_nop 0
	global_load_lds_dwordx4 v[222:223], off
	s_waitcnt vmcnt(8)
	s_waitcnt lgkmcnt(0)
	s_setprio 1
	s_barrier
	v_mfma_f32_16x16x32_bf16 v[60:63], v[152:155], v[184:187], 0
	v_mfma_f32_16x16x32_bf16 v[56:59], v[160:163], v[184:187], 0
	v_mfma_f32_16x16x32_bf16 v[44:47], v[152:155], v[192:195], 0
	v_mfma_f32_16x16x32_bf16 v[40:43], v[160:163], v[192:195], 0
	v_mfma_f32_16x16x32_bf16 v[28:31], v[152:155], v[200:203], 0
	v_mfma_f32_16x16x32_bf16 v[24:27], v[160:163], v[200:203], 0
	v_mfma_f32_16x16x32_bf16 v[12:15], v[152:155], v[208:211], 0
	v_mfma_f32_16x16x32_bf16 v[8:11], v[160:163], v[208:211], 0
	v_mfma_f32_16x16x32_bf16 v[60:63], v[156:159], v[188:191], v[60:63]
	v_mfma_f32_16x16x32_bf16 v[56:59], v[164:167], v[188:191], v[56:59]
	v_mfma_f32_16x16x32_bf16 v[44:47], v[156:159], v[196:199], v[44:47]
	v_mfma_f32_16x16x32_bf16 v[40:43], v[164:167], v[196:199], v[40:43]
	v_mfma_f32_16x16x32_bf16 v[28:31], v[156:159], v[204:207], v[28:31]
	v_mfma_f32_16x16x32_bf16 v[24:27], v[164:167], v[204:207], v[24:27]
	v_mfma_f32_16x16x32_bf16 v[12:15], v[156:159], v[212:215], v[12:15]
	v_mfma_f32_16x16x32_bf16 v[8:11], v[164:167], v[212:215], v[8:11]
	v_mfma_f32_16x16x32_bf16 v[52:55], v[168:171], v[184:187], 0
	v_mfma_f32_16x16x32_bf16 v[48:51], v[176:179], v[184:187], 0
	v_mfma_f32_16x16x32_bf16 v[36:39], v[168:171], v[192:195], 0
	v_mfma_f32_16x16x32_bf16 v[32:35], v[176:179], v[192:195], 0
	v_mfma_f32_16x16x32_bf16 v[20:23], v[168:171], v[200:203], 0
	v_mfma_f32_16x16x32_bf16 v[16:19], v[176:179], v[200:203], 0
	v_mfma_f32_16x16x32_bf16 v[4:7], v[168:171], v[208:211], 0
	v_mfma_f32_16x16x32_bf16 v[0:3], v[176:179], v[208:211], 0
	v_mfma_f32_16x16x32_bf16 v[52:55], v[172:175], v[188:191], v[52:55]
	v_mfma_f32_16x16x32_bf16 v[48:51], v[180:183], v[188:191], v[48:51]
	v_mfma_f32_16x16x32_bf16 v[36:39], v[172:175], v[196:199], v[36:39]
	v_mfma_f32_16x16x32_bf16 v[32:35], v[180:183], v[196:199], v[32:35]
	v_mfma_f32_16x16x32_bf16 v[20:23], v[172:175], v[204:207], v[20:23]
	v_mfma_f32_16x16x32_bf16 v[16:19], v[180:183], v[204:207], v[16:19]
	v_mfma_f32_16x16x32_bf16 v[4:7], v[172:175], v[212:215], v[4:7]
	v_mfma_f32_16x16x32_bf16 v[0:3], v[180:183], v[212:215], v[0:3]
	s_barrier
; #define PG8_STAGE(bufoff, gbase, voff) do { _Pragma("unroll") for (int _i = 0; _i < 2; ++_i) \
;         __builtin_amdgcn_global_load_lds((const unsigned*)((const char*)(gbase) + (voff)[_i]), (PG8_LAS unsigned*)(lds + (bufoff) + ldsw + _i * 8192), 16, 0, 0); } while (0)
; #define PG8_LDA(dst, b, h) do { _Pragma("unroll") for (int m = 0; m < 4; ++m) _Pragma("unroll") for (int k = 0; k < 2; ++k) dst[m][k] = *(const PG8_LAS bf16x8*)(lds + PG8_SA(b, h) + aoff + m * 2048 + k * 1024); } while (0)
; #define PG8_LDB(dst, b, h) do { _Pragma("unroll") for (int n = 0; n < 2; ++n) _Pragma("unroll") for (int k = 0; k < 2; ++k) dst[n][k] = *(const PG8_LAS bf16x8*)(lds + PG8_SB(b, h) + boff + n * 2048 + k * 1024); } while (0)
; #define PG8_MMA(ai, bj, At, Bt) do { __builtin_amdgcn_s_setprio(1); _Pragma("unroll") for (int m = 0; m < 4; ++m) _Pragma("unroll") for (int n = 0; n < 2; ++n) _Pragma("unroll") for (int k = 0; k < 2; ++k) \
;         acc[ai][bj][m][n] = __builtin_amdgcn_mfma_f32_16x16x32_bf16(Bt[n][k], At[m][k], acc[ai][bj][m][n], 0, 0, 0); __builtin_amdgcn_s_setprio(0); } while (0)
; #define PG8_WAIT_V(n) asm volatile("s_waitcnt vmcnt(" #n ")" ::: "memory")
; #define PG8_WAIT_L(n) asm volatile("s_waitcnt lgkmcnt(" #n ")" ::: "memory")
; #define PG8_BAR __builtin_amdgcn_s_barrier()
; #define PG8_SCHED __builtin_amdgcn_sched_barrier(0)
; template <class Epi, class Sched, bool ALIGN_EPI = false, bool SP2 = false>
; __device__ __forceinline__ void gemm_phase(PG8_LAS unsigned char* lds, const Gemm g, const Sched& S, const Epi& E) {
;     ...
;             PG8_LDB(B0, 1, 0); PG8_LDB(B1, 1, 1); PG8_SCHED; PG8_LDA(At, 1, 0); PG8_STAGE(PG8_SA(0, 1), a2 + hstep, voffA);
;             PG8_WAIT_V(8); PG8_WAIT_L(0); PG8_BAR; PG8_MMA(0, 0, At, B0); PG8_MMA(0, 1, At, B1); PG8_BAR; PG8_SCHED;
;             PG8_LDA(At, 1, 1); PG8_STAGE(PG8_SB(1, 0), b3, voffB); PG8_STAGE(PG8_SB(1, 1), b3 + hstep, voffB); PG8_STAGE(PG8_SA(1, 0), a3, voffA);
;             PG8_WAIT_V(8); PG8_WAIT_L(0); PG8_BAR; PG8_MMA(1, 0, At, B0); PG8_MMA(1, 1, At, B1); PG8_BAR; PG8_SCHED;
	s_setprio 0
	s_add_i32 s55, 0, 0x18000
	v_add_u32_e32 v151, s55, v145
	s_add_i32 s56, 0, 0x1c000
	ds_read_b128 v[152:155], v151
	ds_read_b128 v[156:159], v151 offset:1024
	ds_read_b128 v[160:163], v151 offset:2048
	ds_read_b128 v[164:167], v151 offset:3072
	v_add_u32_e32 v151, s56, v145
	ds_read_b128 v[168:171], v151
	ds_read_b128 v[172:175], v151 offset:1024
	ds_read_b128 v[176:179], v151 offset:2048
	ds_read_b128 v[180:183], v151 offset:3072
	s_add_u32 s28, s28, 0x40000
	s_addc_u32 s29, s29, 0
	s_mov_b32 m0, s40
	ds_read_b128 v[184:187], v150 offset:32768
	ds_read_b128 v[188:191], v150 offset:33792
	ds_read_b128 v[192:195], v150 offset:34816
	ds_read_b128 v[196:199], v150 offset:35840
	ds_read_b128 v[200:203], v150 offset:36864
	ds_read_b128 v[204:207], v150 offset:37888
	ds_read_b128 v[208:211], v150 offset:38912
	ds_read_b128 v[212:215], v150 offset:39936
	global_load_lds_dwordx4 v134, s[28:29]
	s_mov_b32 m0, s41
	s_nop 0
	global_load_lds_dwordx4 v130, s[28:29]
	s_waitcnt vmcnt(8)
	s_waitcnt lgkmcnt(0)
	s_setprio 1
	s_barrier
	v_mfma_f32_16x16x32_bf16 v[124:127], v[152:155], v[184:187], v[124:127]
	v_mfma_f32_16x16x32_bf16 v[120:123], v[160:163], v[184:187], v[120:123]
	v_mfma_f32_16x16x32_bf16 v[108:111], v[152:155], v[192:195], v[108:111]
	v_mfma_f32_16x16x32_bf16 v[104:107], v[160:163], v[192:195], v[104:107]
	v_mfma_f32_16x16x32_bf16 v[92:95], v[152:155], v[200:203], v[92:95]
	v_mfma_f32_16x16x32_bf16 v[88:91], v[160:163], v[200:203], v[88:91]
	v_mfma_f32_16x16x32_bf16 v[76:79], v[152:155], v[208:211], v[76:79]
	v_mfma_f32_16x16x32_bf16 v[72:75], v[160:163], v[208:211], v[72:75]
	v_mfma_f32_16x16x32_bf16 v[124:127], v[156:159], v[188:191], v[124:127]
	v_mfma_f32_16x16x32_bf16 v[120:123], v[164:167], v[188:191], v[120:123]
	v_mfma_f32_16x16x32_bf16 v[108:111], v[156:159], v[196:199], v[108:111]
	v_mfma_f32_16x16x32_bf16 v[104:107], v[164:167], v[196:199], v[104:107]
	v_mfma_f32_16x16x32_bf16 v[92:95], v[156:159], v[204:207], v[92:95]
	v_mfma_f32_16x16x32_bf16 v[88:91], v[164:167], v[204:207], v[88:91]
	v_mfma_f32_16x16x32_bf16 v[76:79], v[156:159], v[212:215], v[76:79]
	v_mfma_f32_16x16x32_bf16 v[72:75], v[164:167], v[212:215], v[72:75]
	v_mfma_f32_16x16x32_bf16 v[116:119], v[168:171], v[184:187], v[116:119]
	v_mfma_f32_16x16x32_bf16 v[112:115], v[176:179], v[184:187], v[112:115]
	v_mfma_f32_16x16x32_bf16 v[100:103], v[168:171], v[192:195], v[100:103]
	v_mfma_f32_16x16x32_bf16 v[96:99], v[176:179], v[192:195], v[96:99]
	v_mfma_f32_16x16x32_bf16 v[84:87], v[168:171], v[200:203], v[84:87]
	v_mfma_f32_16x16x32_bf16 v[80:83], v[176:179], v[200:203], v[80:83]
	v_mfma_f32_16x16x32_bf16 v[68:71], v[168:171], v[208:211], v[68:71]
	v_mfma_f32_16x16x32_bf16 v[64:67], v[176:179], v[208:211], v[64:67]
	v_mfma_f32_16x16x32_bf16 v[116:119], v[172:175], v[188:191], v[116:119]
	v_mfma_f32_16x16x32_bf16 v[112:115], v[180:183], v[188:191], v[112:115]
	v_mfma_f32_16x16x32_bf16 v[100:103], v[172:175], v[196:199], v[100:103]
	v_mfma_f32_16x16x32_bf16 v[96:99], v[180:183], v[196:199], v[96:99]
	v_mfma_f32_16x16x32_bf16 v[84:87], v[172:175], v[204:207], v[84:87]
	v_mfma_f32_16x16x32_bf16 v[80:83], v[180:183], v[204:207], v[80:83]
	v_mfma_f32_16x16x32_bf16 v[68:71], v[172:175], v[212:215], v[68:71]
	v_mfma_f32_16x16x32_bf16 v[64:67], v[180:183], v[212:215], v[64:67]
	s_barrier
	s_setprio 0
	s_add_i32 s28, s55, s33
	v_lshl_add_u64 v[216:217], v[216:217], 0, s[8:9]
	s_mov_b32 m0, s28
	ds_read_b128 v[184:187], v150 offset:49152
	ds_read_b128 v[188:191], v150 offset:50176
	ds_read_b128 v[192:195], v150 offset:51200
	ds_read_b128 v[196:199], v150 offset:52224
	ds_read_b128 v[200:203], v150 offset:53248
	ds_read_b128 v[204:207], v150 offset:54272
	ds_read_b128 v[208:211], v150 offset:55296
	ds_read_b128 v[212:215], v150 offset:56320
	global_load_lds_dwordx4 v[216:217], off
	s_add_i32 m0, s28, 0x2000
	s_add_u32 s26, s26, 0x40080
	v_lshl_add_u64 v[216:217], v[218:219], 0, s[8:9]
	s_addc_u32 s27, s27, 0
	s_add_i32 s28, s56, s33
	global_load_lds_dwordx4 v[216:217], off
	s_mov_b32 m0, s28
	s_nop 0
	global_load_lds_dwordx4 v132, s[26:27]
	s_add_i32 m0, s28, 0x2000
	s_nop 0
	global_load_lds_dwordx4 v128, s[26:27]
	v_lshl_add_u64 v[216:217], v[220:221], 0, s[8:9]
	s_mov_b32 m0, s42
	s_nop 0
	global_load_lds_dwordx4 v[216:217], off
	v_lshl_add_u64 v[216:217], v[222:223], 0, s[8:9]
	s_mov_b32 m0, s43
	s_nop 0
	global_load_lds_dwordx4 v[216:217], off
	s_waitcnt vmcnt(8)
	s_waitcnt lgkmcnt(0)
	s_setprio 1
	s_barrier
	v_mfma_f32_16x16x32_bf16 v[60:63], v[152:155], v[184:187], v[60:63]
	v_mfma_f32_16x16x32_bf16 v[56:59], v[160:163], v[184:187], v[56:59]
	v_mfma_f32_16x16x32_bf16 v[44:47], v[152:155], v[192:195], v[44:47]
	v_mfma_f32_16x16x32_bf16 v[40:43], v[160:163], v[192:195], v[40:43]
	v_mfma_f32_16x16x32_bf16 v[28:31], v[152:155], v[200:203], v[28:31]
	v_mfma_f32_16x16x32_bf16 v[24:27], v[160:163], v[200:203], v[24:27]
	v_mfma_f32_16x16x32_bf16 v[12:15], v[152:155], v[208:211], v[12:15]
	v_mfma_f32_16x16x32_bf16 v[8:11], v[160:163], v[208:211], v[8:11]
	v_mfma_f32_16x16x32_bf16 v[60:63], v[156:159], v[188:191], v[60:63]
	v_mfma_f32_16x16x32_bf16 v[56:59], v[164:167], v[188:191], v[56:59]
	v_mfma_f32_16x16x32_bf16 v[44:47], v[156:159], v[196:199], v[44:47]
	v_mfma_f32_16x16x32_bf16 v[40:43], v[164:167], v[196:199], v[40:43]
	v_mfma_f32_16x16x32_bf16 v[28:31], v[156:159], v[204:207], v[28:31]
	v_mfma_f32_16x16x32_bf16 v[24:27], v[164:167], v[204:207], v[24:27]
	v_mfma_f32_16x16x32_bf16 v[12:15], v[156:159], v[212:215], v[12:15]
	v_mfma_f32_16x16x32_bf16 v[8:11], v[164:167], v[212:215], v[8:11]
	v_mfma_f32_16x16x32_bf16 v[52:55], v[168:171], v[184:187], v[52:55]
	v_mfma_f32_16x16x32_bf16 v[48:51], v[176:179], v[184:187], v[48:51]
	v_mfma_f32_16x16x32_bf16 v[36:39], v[168:171], v[192:195], v[36:39]
	v_mfma_f32_16x16x32_bf16 v[32:35], v[176:179], v[192:195], v[32:35]
	v_mfma_f32_16x16x32_bf16 v[20:23], v[168:171], v[200:203], v[20:23]
	v_mfma_f32_16x16x32_bf16 v[16:19], v[176:179], v[200:203], v[16:19]
	v_mfma_f32_16x16x32_bf16 v[4:7], v[168:171], v[208:211], v[4:7]
	v_mfma_f32_16x16x32_bf16 v[0:3], v[176:179], v[208:211], v[0:3]
	v_mfma_f32_16x16x32_bf16 v[52:55], v[172:175], v[188:191], v[52:55]
	v_mfma_f32_16x16x32_bf16 v[48:51], v[180:183], v[188:191], v[48:51]
	v_mfma_f32_16x16x32_bf16 v[36:39], v[172:175], v[196:199], v[36:39]
	v_mfma_f32_16x16x32_bf16 v[32:35], v[180:183], v[196:199], v[32:35]
	v_mfma_f32_16x16x32_bf16 v[20:23], v[172:175], v[204:207], v[20:23]
	v_mfma_f32_16x16x32_bf16 v[16:19], v[180:183], v[204:207], v[16:19]
	v_mfma_f32_16x16x32_bf16 v[4:7], v[172:175], v[212:215], v[4:7]
	v_mfma_f32_16x16x32_bf16 v[0:3], v[180:183], v[212:215], v[0:3]
	s_barrier
	s_setprio 0
	s_add_i32 s54, s54, 2
	s_add_u32 s24, s24, 0x100
	s_addc_u32 s25, s25, 0
	s_add_u32 s52, s52, 0x100
	s_addc_u32 s53, s53, 0
	s_cmp_gt_u32 s54, 13
	.p2align 6

; #define PG8_STAGE(bufoff, gbase, voff) do { _Pragma("unroll") for (int _i = 0; _i < 2; ++_i) \
;         __builtin_amdgcn_global_load_lds((const unsigned*)((const char*)(gbase) + (voff)[_i]), (PG8_LAS unsigned*)(lds + (bufoff) + ldsw + _i * 8192), 16, 0, 0); } while (0)
; #define PG8_LDA(dst, b, h) do { _Pragma("unroll") for (int m = 0; m < 4; ++m) _Pragma("unroll") for (int k = 0; k < 2; ++k) dst[m][k] = *(const PG8_LAS bf16x8*)(lds + PG8_SA(b, h) + aoff + m * 2048 + k * 1024); } while (0)
; #define PG8_LDB(dst, b, h) do { _Pragma("unroll") for (int n = 0; n < 2; ++n) _Pragma("unroll") for (int k = 0; k < 2; ++k) dst[n][k] = *(const PG8_LAS bf16x8*)(lds + PG8_SB(b, h) + boff + n * 2048 + k * 1024); } while (0)
; #define PG8_WAIT_V(n) asm volatile("s_waitcnt vmcnt(" #n ")" ::: "memory")
; #define PG8_WAIT_L(n) asm volatile("s_waitcnt lgkmcnt(" #n ")" ::: "memory")
; #define PG8_BAR __builtin_amdgcn_s_barrier()
; #define PG8_SCHED __builtin_amdgcn_sched_barrier(0)
; template <class Epi, class Sched, bool ALIGN_EPI = false, bool SP2 = false>
; __device__ __forceinline__ void gemm_phase(PG8_LAS unsigned char* lds, const Gemm g, const Sched& S, const Epi& E) {
;     ...
;         const bool has_next = S.next(ui + 1, nxt);
;         const char* nA = has_next ? (const char*)g.A + (size_t)nxt.pm * tstep : cA; const char* nB = has_next ? (const char*)g.Bt + (size_t)nxt.pn * tstep : cB;
;         for (int t = 0; t < nt; t += 2) {
;             const bool last = (t == nt - 2);
;             const char* a1 = cA + (size_t)(t + 1) * kstep;
;             const char* a2 = last ? nA : cA + (size_t)(t + 2) * kstep; const char* b2 = last ? nB : cB + (size_t)(t + 2) * kstep;
;             const char* a3 = a2 + kstep; const char* b3 = b2 + kstep;
;             if (last && has_next) S.a_ready(nxt, ui + 1);
;             if constexpr (SP2) {
;             PG8_LDB(B0, 0, 0); PG8_LDB(B1, 0, 1); PG8_SCHED; PG8_LDA(At, 0, 0); PG8_STAGE(PG8_SA(1, 1), a1 + hstep, voffA);
;             PG8_WAIT_V(8); PG8_WAIT_L(0); PG8_BAR; PG8_MMA(0, 0, At, B0); PG8_MMA(0, 1, At, B1); PG8_BAR; PG8_SCHED;
;             PG8_LDA(At, 0, 1); PG8_STAGE(PG8_SB(0, 0), b2, voffB); PG8_STAGE(PG8_SB(0, 1), b2 + hstep, voffB); PG8_STAGE(PG8_SA(0, 0), a2, voffA);
;             PG8_WAIT_V(8); PG8_WAIT_L(0); PG8_BAR; PG8_MMA(1, 0, At, B0); PG8_MMA(1, 1, At, B1); PG8_BAR; PG8_SCHED;
.LBB0_417:
	s_add_u32 s24, s24, 0xb0080
	s_addc_u32 s25, s25, 0
	s_add_u32 s51, s26, 0x100
	s_addc_u32 s52, s27, 0
	s_mov_b32 s53, -2
	s_waitcnt lgkmcnt(0)
	s_add_u32 s26, s24, 0xfff50080
	s_addc_u32 s27, s25, -1
	s_cmp_eq_u32 s53, 40
	s_cselect_b32 s29, s7, s27
	s_cselect_b32 s28, s6, s26
	s_cselect_b32 s27, s23, s52
	s_cselect_b32 s26, s22, s51
	s_add_i32 m0, s35, 0xc000
	s_nop 0
	global_load_lds_dwordx4 v200, s[24:25]
	s_add_i32 m0, s35, 0xe000
	s_nop 0
	global_load_lds_dwordx4 v202, s[24:25]
	s_waitcnt vmcnt(8)
	s_waitcnt lgkmcnt(0)
	s_setprio 1
	s_barrier
	v_mfma_f32_16x16x32_bf16 v[132:135], v[120:123], v[160:163], 0
	v_mfma_f32_16x16x32_bf16 v[124:127], v[136:139], v[160:163], 0
	v_mfma_f32_16x16x32_bf16 v[108:111], v[120:123], v[168:171], 0
	v_mfma_f32_16x16x32_bf16 v[104:107], v[136:139], v[168:171], 0
	v_mfma_f32_16x16x32_bf16 v[92:95], v[120:123], v[176:179], 0
	v_mfma_f32_16x16x32_bf16 v[88:91], v[136:139], v[176:179], 0
	v_mfma_f32_16x16x32_bf16 v[76:79], v[120:123], v[184:187], 0
	v_mfma_f32_16x16x32_bf16 v[72:75], v[136:139], v[184:187], 0
	v_mfma_f32_16x16x32_bf16 v[132:135], v[128:131], v[164:167], v[132:135]
	v_mfma_f32_16x16x32_bf16 v[124:127], v[140:143], v[164:167], v[124:127]
	v_mfma_f32_16x16x32_bf16 v[108:111], v[128:131], v[172:175], v[108:111]
	v_mfma_f32_16x16x32_bf16 v[104:107], v[140:143], v[172:175], v[104:107]
	v_mfma_f32_16x16x32_bf16 v[92:95], v[128:131], v[180:183], v[92:95]
	v_mfma_f32_16x16x32_bf16 v[88:91], v[140:143], v[180:183], v[88:91]
	v_mfma_f32_16x16x32_bf16 v[76:79], v[128:131], v[188:191], v[76:79]
	v_mfma_f32_16x16x32_bf16 v[72:75], v[140:143], v[188:191], v[72:75]
	v_mfma_f32_16x16x32_bf16 v[116:119], v[144:147], v[160:163], 0
	v_mfma_f32_16x16x32_bf16 v[112:115], v[152:155], v[160:163], 0
	v_mfma_f32_16x16x32_bf16 v[100:103], v[144:147], v[168:171], 0
	v_mfma_f32_16x16x32_bf16 v[96:99], v[152:155], v[168:171], 0
	v_mfma_f32_16x16x32_bf16 v[84:87], v[144:147], v[176:179], 0
	v_mfma_f32_16x16x32_bf16 v[80:83], v[152:155], v[176:179], 0
	v_mfma_f32_16x16x32_bf16 v[68:71], v[144:147], v[184:187], 0
	v_mfma_f32_16x16x32_bf16 v[64:67], v[152:155], v[184:187], 0
	v_mfma_f32_16x16x32_bf16 v[116:119], v[148:151], v[164:167], v[116:119]
	v_mfma_f32_16x16x32_bf16 v[112:115], v[156:159], v[164:167], v[112:115]
	v_mfma_f32_16x16x32_bf16 v[100:103], v[148:151], v[172:175], v[100:103]
	v_mfma_f32_16x16x32_bf16 v[96:99], v[156:159], v[172:175], v[96:99]
	v_mfma_f32_16x16x32_bf16 v[84:87], v[148:151], v[180:183], v[84:87]
	v_mfma_f32_16x16x32_bf16 v[80:83], v[156:159], v[180:183], v[80:83]
	v_mfma_f32_16x16x32_bf16 v[68:71], v[148:151], v[188:191], v[68:71]
	v_mfma_f32_16x16x32_bf16 v[64:67], v[156:159], v[188:191], v[64:67]
	s_barrier
	s_setprio 0
	s_add_i32 s54, s45, s34
	v_lshl_add_u64 v[204:205], s[26:27], 0, v[194:195]
	s_mov_b32 m0, s54
	ds_read_b128 v[160:163], v247 offset:16384
	ds_read_b128 v[164:167], v247 offset:17408
	ds_read_b128 v[168:171], v247 offset:18432
	ds_read_b128 v[172:175], v247 offset:19456
	ds_read_b128 v[176:179], v247 offset:20480
	ds_read_b128 v[180:183], v247 offset:21504
	ds_read_b128 v[184:187], v247 offset:22528
	ds_read_b128 v[188:191], v247 offset:23552
	global_load_lds_dwordx4 v[204:205], off
	s_add_i32 m0, s54, 0x2000
	s_add_u32 s54, s26, 0xb0000
	v_lshl_add_u64 v[206:207], s[26:27], 0, v[198:199]
	s_addc_u32 s55, s27, 0
	s_add_i32 s56, s46, s34
	global_load_lds_dwordx4 v[206:207], off
	s_mov_b32 m0, s56
	v_lshl_add_u64 v[210:211], s[28:29], 0, v[196:197]
	global_load_lds_dwordx4 v194, s[54:55]
	s_add_i32 m0, s56, 0x2000
	s_nop 0
	global_load_lds_dwordx4 v198, s[54:55]
	v_lshl_add_u64 v[208:209], s[28:29], 0, v[192:193]
	s_mov_b32 m0, s35
	s_nop 0
	global_load_lds_dwordx4 v[208:209], off
	s_mov_b32 m0, s36
	s_nop 0
	global_load_lds_dwordx4 v[210:211], off
	s_waitcnt vmcnt(8)
	s_waitcnt lgkmcnt(0)
	s_setprio 1
	s_barrier
	v_mfma_f32_16x16x32_bf16 v[60:63], v[120:123], v[160:163], 0
	v_mfma_f32_16x16x32_bf16 v[56:59], v[136:139], v[160:163], 0
	v_mfma_f32_16x16x32_bf16 v[44:47], v[120:123], v[168:171], 0
	v_mfma_f32_16x16x32_bf16 v[40:43], v[136:139], v[168:171], 0
	v_mfma_f32_16x16x32_bf16 v[28:31], v[120:123], v[176:179], 0
	v_mfma_f32_16x16x32_bf16 v[24:27], v[136:139], v[176:179], 0
	v_mfma_f32_16x16x32_bf16 v[12:15], v[120:123], v[184:187], 0
	v_mfma_f32_16x16x32_bf16 v[8:11], v[136:139], v[184:187], 0
	v_mfma_f32_16x16x32_bf16 v[60:63], v[128:131], v[164:167], v[60:63]
	v_mfma_f32_16x16x32_bf16 v[56:59], v[140:143], v[164:167], v[56:59]
	v_mfma_f32_16x16x32_bf16 v[44:47], v[128:131], v[172:175], v[44:47]
	v_mfma_f32_16x16x32_bf16 v[40:43], v[140:143], v[172:175], v[40:43]
	v_mfma_f32_16x16x32_bf16 v[28:31], v[128:131], v[180:183], v[28:31]
	v_mfma_f32_16x16x32_bf16 v[24:27], v[140:143], v[180:183], v[24:27]
	v_mfma_f32_16x16x32_bf16 v[12:15], v[128:131], v[188:191], v[12:15]
	v_mfma_f32_16x16x32_bf16 v[8:11], v[140:143], v[188:191], v[8:11]
	v_mfma_f32_16x16x32_bf16 v[52:55], v[144:147], v[160:163], 0
	v_mfma_f32_16x16x32_bf16 v[48:51], v[152:155], v[160:163], 0
	v_mfma_f32_16x16x32_bf16 v[36:39], v[144:147], v[168:171], 0
	v_mfma_f32_16x16x32_bf16 v[32:35], v[152:155], v[168:171], 0
	v_mfma_f32_16x16x32_bf16 v[20:23], v[144:147], v[176:179], 0
	v_mfma_f32_16x16x32_bf16 v[16:19], v[152:155], v[176:179], 0
	v_mfma_f32_16x16x32_bf16 v[4:7], v[144:147], v[184:187], 0
	v_mfma_f32_16x16x32_bf16 v[0:3], v[152:155], v[184:187], 0
	v_mfma_f32_16x16x32_bf16 v[52:55], v[148:151], v[164:167], v[52:55]
	v_mfma_f32_16x16x32_bf16 v[48:51], v[156:159], v[164:167], v[48:51]
	v_mfma_f32_16x16x32_bf16 v[36:39], v[148:151], v[172:175], v[36:39]
	v_mfma_f32_16x16x32_bf16 v[32:35], v[156:159], v[172:175], v[32:35]
	v_mfma_f32_16x16x32_bf16 v[20:23], v[148:151], v[180:183], v[20:23]
	v_mfma_f32_16x16x32_bf16 v[16:19], v[156:159], v[180:183], v[16:19]
	v_mfma_f32_16x16x32_bf16 v[4:7], v[148:151], v[188:191], v[4:7]
	v_mfma_f32_16x16x32_bf16 v[0:3], v[156:159], v[188:191], v[0:3]
	s_barrier
; #define PG8_STAGE(bufoff, gbase, voff) do { _Pragma("unroll") for (int _i = 0; _i < 2; ++_i) \
;         __builtin_amdgcn_global_load_lds((const unsigned*)((const char*)(gbase) + (voff)[_i]), (PG8_LAS unsigned*)(lds + (bufoff) + ldsw + _i * 8192), 16, 0, 0); } while (0)
; #define PG8_LDA(dst, b, h) do { _Pragma("unroll") for (int m = 0; m < 4; ++m) _Pragma("unroll") for (int k = 0; k < 2; ++k) dst[m][k] = *(const PG8_LAS bf16x8*)(lds + PG8_SA(b, h) + aoff + m * 2048 + k * 1024); } while (0)
; #define PG8_LDB(dst, b, h) do { _Pragma("unroll") for (int n = 0; n < 2; ++n) _Pragma("unroll") for (int k = 0; k < 2; ++k) dst[n][k] = *(const PG8_LAS bf16x8*)(lds + PG8_SB(b, h) + boff + n * 2048 + k * 1024); } while (0)
; #define PG8_MMA(ai, bj, At, Bt) do { __builtin_amdgcn_s_setprio(1); _Pragma("unroll") for (int m = 0; m < 4; ++m) _Pragma("unroll") for (int n = 0; n < 2; ++n) _Pragma("unroll") for (int k = 0; k < 2; ++k) \
;         acc[ai][bj][m][n] = __builtin_amdgcn_mfma_f32_16x16x32_bf16(Bt[n][k], At[m][k], acc[ai][bj][m][n], 0, 0, 0); __builtin_amdgcn_s_setprio(0); } while (0)
; #define PG8_WAIT_V(n) asm volatile("s_waitcnt vmcnt(" #n ")" ::: "memory")
; #define PG8_WAIT_L(n) asm volatile("s_waitcnt lgkmcnt(" #n ")" ::: "memory")
; #define PG8_BAR __builtin_amdgcn_s_barrier()
; #define PG8_SCHED __builtin_amdgcn_sched_barrier(0)
; template <class Epi, class Sched, bool ALIGN_EPI = false, bool SP2 = false>
; __device__ __forceinline__ void gemm_phase(PG8_LAS unsigned char* lds, const Gemm g, const Sched& S, const Epi& E) {
;     ...
;             PG8_LDB(B0, 1, 0); PG8_LDB(B1, 1, 1); PG8_SCHED; PG8_LDA(At, 1, 0); PG8_STAGE(PG8_SA(0, 1), a2 + hstep, voffA);
;             PG8_WAIT_V(8); PG8_WAIT_L(0); PG8_BAR; PG8_MMA(0, 0, At, B0); PG8_MMA(0, 1, At, B1); PG8_BAR; PG8_SCHED;
;             PG8_LDA(At, 1, 1); PG8_STAGE(PG8_SB(1, 0), b3, voffB); PG8_STAGE(PG8_SB(1, 1), b3 + hstep, voffB); PG8_STAGE(PG8_SA(1, 0), a3, voffA);
;             PG8_WAIT_V(8); PG8_WAIT_L(0); PG8_BAR; PG8_MMA(1, 0, At, B0); PG8_MMA(1, 1, At, B1); PG8_BAR; PG8_SCHED;
	s_setprio 0
	s_add_i32 s54, 0, 0x18000
	s_add_i32 s55, 0, 0x1c000
	v_add_u32_e32 v140, s54, v243
	v_add_u32_e32 v156, s55, v243
	ds_read_b128 v[120:123], v140
	ds_read_b128 v[128:131], v140 offset:1024
	ds_read_b128 v[136:139], v140 offset:2048
	ds_read_b128 v[140:143], v140 offset:3072
	ds_read_b128 v[144:147], v156
	ds_read_b128 v[148:151], v156 offset:1024
	ds_read_b128 v[152:155], v156 offset:2048
	ds_read_b128 v[156:159], v156 offset:3072
	s_add_u32 s28, s28, 0xb0000
	s_addc_u32 s29, s29, 0
	s_mov_b32 m0, s37
	ds_read_b128 v[160:163], v247 offset:32768
	ds_read_b128 v[164:167], v247 offset:33792
	ds_read_b128 v[168:171], v247 offset:34816
	ds_read_b128 v[172:175], v247 offset:35840
	ds_read_b128 v[176:179], v247 offset:36864
	ds_read_b128 v[180:183], v247 offset:37888
	ds_read_b128 v[184:187], v247 offset:38912
	ds_read_b128 v[188:191], v247 offset:39936
	global_load_lds_dwordx4 v192, s[28:29]
	s_mov_b32 m0, s38
	s_nop 0
	global_load_lds_dwordx4 v196, s[28:29]
	s_waitcnt vmcnt(8)
	s_waitcnt lgkmcnt(0)
	s_setprio 1
	s_barrier
	v_mfma_f32_16x16x32_bf16 v[132:135], v[120:123], v[160:163], v[132:135]
	v_mfma_f32_16x16x32_bf16 v[124:127], v[136:139], v[160:163], v[124:127]
	v_mfma_f32_16x16x32_bf16 v[108:111], v[120:123], v[168:171], v[108:111]
	v_mfma_f32_16x16x32_bf16 v[104:107], v[136:139], v[168:171], v[104:107]
	v_mfma_f32_16x16x32_bf16 v[92:95], v[120:123], v[176:179], v[92:95]
	v_mfma_f32_16x16x32_bf16 v[88:91], v[136:139], v[176:179], v[88:91]
	v_mfma_f32_16x16x32_bf16 v[76:79], v[120:123], v[184:187], v[76:79]
	v_mfma_f32_16x16x32_bf16 v[72:75], v[136:139], v[184:187], v[72:75]
	v_mfma_f32_16x16x32_bf16 v[132:135], v[128:131], v[164:167], v[132:135]
	v_mfma_f32_16x16x32_bf16 v[124:127], v[140:143], v[164:167], v[124:127]
	v_mfma_f32_16x16x32_bf16 v[108:111], v[128:131], v[172:175], v[108:111]
	v_mfma_f32_16x16x32_bf16 v[104:107], v[140:143], v[172:175], v[104:107]
	v_mfma_f32_16x16x32_bf16 v[92:95], v[128:131], v[180:183], v[92:95]
	v_mfma_f32_16x16x32_bf16 v[88:91], v[140:143], v[180:183], v[88:91]
	v_mfma_f32_16x16x32_bf16 v[76:79], v[128:131], v[188:191], v[76:79]
	v_mfma_f32_16x16x32_bf16 v[72:75], v[140:143], v[188:191], v[72:75]
	v_mfma_f32_16x16x32_bf16 v[116:119], v[144:147], v[160:163], v[116:119]
	v_mfma_f32_16x16x32_bf16 v[112:115], v[152:155], v[160:163], v[112:115]
	v_mfma_f32_16x16x32_bf16 v[100:103], v[144:147], v[168:171], v[100:103]
	v_mfma_f32_16x16x32_bf16 v[96:99], v[152:155], v[168:171], v[96:99]
	v_mfma_f32_16x16x32_bf16 v[84:87], v[144:147], v[176:179], v[84:87]
	v_mfma_f32_16x16x32_bf16 v[80:83], v[152:155], v[176:179], v[80:83]
	v_mfma_f32_16x16x32_bf16 v[68:71], v[144:147], v[184:187], v[68:71]
	v_mfma_f32_16x16x32_bf16 v[64:67], v[152:155], v[184:187], v[64:67]
	v_mfma_f32_16x16x32_bf16 v[116:119], v[148:151], v[164:167], v[116:119]
	v_mfma_f32_16x16x32_bf16 v[112:115], v[156:159], v[164:167], v[112:115]
	v_mfma_f32_16x16x32_bf16 v[100:103], v[148:151], v[172:175], v[100:103]
	v_mfma_f32_16x16x32_bf16 v[96:99], v[156:159], v[172:175], v[96:99]
	v_mfma_f32_16x16x32_bf16 v[84:87], v[148:151], v[180:183], v[84:87]
	v_mfma_f32_16x16x32_bf16 v[80:83], v[156:159], v[180:183], v[80:83]
	v_mfma_f32_16x16x32_bf16 v[68:71], v[148:151], v[188:191], v[68:71]
	v_mfma_f32_16x16x32_bf16 v[64:67], v[156:159], v[188:191], v[64:67]
	s_barrier
	s_setprio 0
	s_add_i32 s28, s54, s34
	v_lshl_add_u64 v[204:205], v[204:205], 0, s[18:19]
	s_mov_b32 m0, s28
	ds_read_b128 v[160:163], v247 offset:49152
	ds_read_b128 v[164:167], v247 offset:50176
	ds_read_b128 v[168:171], v247 offset:51200
	ds_read_b128 v[172:175], v247 offset:52224
	ds_read_b128 v[176:179], v247 offset:53248
	ds_read_b128 v[180:183], v247 offset:54272
	ds_read_b128 v[184:187], v247 offset:55296
	ds_read_b128 v[188:191], v247 offset:56320
	global_load_lds_dwordx4 v[204:205], off
	s_add_i32 m0, s28, 0x2000
	s_add_u32 s26, s26, 0xb0080
	v_lshl_add_u64 v[204:205], v[206:207], 0, s[18:19]
	s_addc_u32 s27, s27, 0
	s_add_i32 s28, s55, s34
	global_load_lds_dwordx4 v[204:205], off
	s_mov_b32 m0, s28
	s_nop 0
	global_load_lds_dwordx4 v194, s[26:27]
	s_add_i32 m0, s28, 0x2000
	s_nop 0
	global_load_lds_dwordx4 v198, s[26:27]
	v_lshl_add_u64 v[204:205], v[208:209], 0, s[18:19]
	s_mov_b32 m0, s40
	s_nop 0
	global_load_lds_dwordx4 v[204:205], off
	v_lshl_add_u64 v[204:205], v[210:211], 0, s[18:19]
	s_mov_b32 m0, s41
	s_nop 0
	global_load_lds_dwordx4 v[204:205], off
	s_waitcnt vmcnt(8)
	s_waitcnt lgkmcnt(0)
	s_setprio 1
	s_barrier
	v_mfma_f32_16x16x32_bf16 v[60:63], v[120:123], v[160:163], v[60:63]
	v_mfma_f32_16x16x32_bf16 v[56:59], v[136:139], v[160:163], v[56:59]
	v_mfma_f32_16x16x32_bf16 v[44:47], v[120:123], v[168:171], v[44:47]
	v_mfma_f32_16x16x32_bf16 v[40:43], v[136:139], v[168:171], v[40:43]
	v_mfma_f32_16x16x32_bf16 v[28:31], v[120:123], v[176:179], v[28:31]
	v_mfma_f32_16x16x32_bf16 v[24:27], v[136:139], v[176:179], v[24:27]
	v_mfma_f32_16x16x32_bf16 v[12:15], v[120:123], v[184:187], v[12:15]
	v_mfma_f32_16x16x32_bf16 v[8:11], v[136:139], v[184:187], v[8:11]
	v_mfma_f32_16x16x32_bf16 v[60:63], v[128:131], v[164:167], v[60:63]
	v_mfma_f32_16x16x32_bf16 v[56:59], v[140:143], v[164:167], v[56:59]
	v_mfma_f32_16x16x32_bf16 v[44:47], v[128:131], v[172:175], v[44:47]
	v_mfma_f32_16x16x32_bf16 v[40:43], v[140:143], v[172:175], v[40:43]
	v_mfma_f32_16x16x32_bf16 v[28:31], v[128:131], v[180:183], v[28:31]
	v_mfma_f32_16x16x32_bf16 v[24:27], v[140:143], v[180:183], v[24:27]
	v_mfma_f32_16x16x32_bf16 v[12:15], v[128:131], v[188:191], v[12:15]
	v_mfma_f32_16x16x32_bf16 v[8:11], v[140:143], v[188:191], v[8:11]
	v_mfma_f32_16x16x32_bf16 v[52:55], v[144:147], v[160:163], v[52:55]
	v_mfma_f32_16x16x32_bf16 v[48:51], v[152:155], v[160:163], v[48:51]
	v_mfma_f32_16x16x32_bf16 v[36:39], v[144:147], v[168:171], v[36:39]
	v_mfma_f32_16x16x32_bf16 v[32:35], v[152:155], v[168:171], v[32:35]
	v_mfma_f32_16x16x32_bf16 v[20:23], v[144:147], v[176:179], v[20:23]
	v_mfma_f32_16x16x32_bf16 v[16:19], v[152:155], v[176:179], v[16:19]
	v_mfma_f32_16x16x32_bf16 v[4:7], v[144:147], v[184:187], v[4:7]
	v_mfma_f32_16x16x32_bf16 v[0:3], v[152:155], v[184:187], v[0:3]
	v_mfma_f32_16x16x32_bf16 v[52:55], v[148:151], v[164:167], v[52:55]
	v_mfma_f32_16x16x32_bf16 v[48:51], v[156:159], v[164:167], v[48:51]
	v_mfma_f32_16x16x32_bf16 v[36:39], v[148:151], v[172:175], v[36:39]
	v_mfma_f32_16x16x32_bf16 v[32:35], v[156:159], v[172:175], v[32:35]
	v_mfma_f32_16x16x32_bf16 v[20:23], v[148:151], v[180:183], v[20:23]
	v_mfma_f32_16x16x32_bf16 v[16:19], v[156:159], v[180:183], v[16:19]
	v_mfma_f32_16x16x32_bf16 v[4:7], v[148:151], v[188:191], v[4:7]
	v_mfma_f32_16x16x32_bf16 v[0:3], v[156:159], v[188:191], v[0:3]
	s_barrier
	s_setprio 0
	s_add_i32 s53, s53, 2
	s_add_u32 s24, s24, 0x100
	s_addc_u32 s25, s25, 0
	s_add_u32 s51, s51, 0x100
	s_addc_u32 s52, s52, 0
	s_cmp_gt_u32 s53, 41
	.p2align 6

; #define PG8_STAGE(bufoff, gbase, voff) do { _Pragma("unroll") for (int _i = 0; _i < 2; ++_i) \
;         __builtin_amdgcn_global_load_lds((const unsigned*)((const char*)(gbase) + (voff)[_i]), (PG8_LAS unsigned*)(lds + (bufoff) + ldsw + _i * 8192), 16, 0, 0); } while (0)
; #define PG8_LDA(dst, b, h) do { _Pragma("unroll") for (int m = 0; m < 4; ++m) _Pragma("unroll") for (int k = 0; k < 2; ++k) dst[m][k] = *(const PG8_LAS bf16x8*)(lds + PG8_SA(b, h) + aoff + m * 2048 + k * 1024); } while (0)
; #define PG8_LDB(dst, b, h) do { _Pragma("unroll") for (int n = 0; n < 2; ++n) _Pragma("unroll") for (int k = 0; k < 2; ++k) dst[n][k] = *(const PG8_LAS bf16x8*)(lds + PG8_SB(b, h) + boff + n * 2048 + k * 1024); } while (0)
; #define PG8_WAIT_V(n) asm volatile("s_waitcnt vmcnt(" #n ")" ::: "memory")
; #define PG8_WAIT_L(n) asm volatile("s_waitcnt lgkmcnt(" #n ")" ::: "memory")
; #define PG8_BAR __builtin_amdgcn_s_barrier()
; #define PG8_SCHED __builtin_amdgcn_sched_barrier(0)
; template <class Epi, class Sched, bool ALIGN_EPI = false, bool SP2 = false>
; __device__ __forceinline__ void gemm_phase(PG8_LAS unsigned char* lds, const Gemm g, const Sched& S, const Epi& E) {
;     ...
;         const bool has_next = S.next(ui + 1, nxt);
;         const char* nA = has_next ? (const char*)g.A + (size_t)nxt.pm * tstep : cA; const char* nB = has_next ? (const char*)g.Bt + (size_t)nxt.pn * tstep : cB;
;         for (int t = 0; t < nt; t += 2) {
;             const bool last = (t == nt - 2);
;             const char* a1 = cA + (size_t)(t + 1) * kstep;
;             const char* a2 = last ? nA : cA + (size_t)(t + 2) * kstep; const char* b2 = last ? nB : cB + (size_t)(t + 2) * kstep;
;             const char* a3 = a2 + kstep; const char* b3 = b2 + kstep;
;             if (last && has_next) S.a_ready(nxt, ui + 1);
;             if constexpr (SP2) {
;             PG8_LDB(B0, 0, 0); PG8_LDB(B1, 0, 1); PG8_SCHED; PG8_LDA(At, 0, 0); PG8_STAGE(PG8_SA(1, 1), a1 + hstep, voffA);
;             PG8_WAIT_V(8); PG8_WAIT_L(0); PG8_BAR; PG8_MMA(0, 0, At, B0); PG8_MMA(0, 1, At, B1); PG8_BAR; PG8_SCHED;
;             PG8_LDA(At, 0, 1); PG8_STAGE(PG8_SB(0, 0), b2, voffB); PG8_STAGE(PG8_SB(0, 1), b2 + hstep, voffB); PG8_STAGE(PG8_SA(0, 0), a2, voffA);
;             PG8_WAIT_V(8); PG8_WAIT_L(0); PG8_BAR; PG8_MMA(1, 0, At, B0); PG8_MMA(1, 1, At, B1); PG8_BAR; PG8_SCHED;
.LBB0_508:
	s_ashr_i32 s31, s30, 31
	s_lshl_b64 s[34:35], s[30:31], 19
	s_add_u32 s34, s48, s34
	s_addc_u32 s35, s49, s35
	s_and_b64 s[36:37], s[4:5], exec
	s_cselect_b32 s9, s35, s39
	s_cselect_b32 s14, s34, s38
	s_ashr_i32 s29, s28, 31
	s_lshl_b64 s[36:37], s[28:29], 19
	s_add_u32 s36, s50, s36
	s_addc_u32 s37, s51, s37
	s_and_b64 s[42:43], s[4:5], exec
	s_cselect_b32 s29, s37, s41
	s_cselect_b32 s31, s36, s40
	s_add_u32 s38, s38, 0x40080
	s_addc_u32 s39, s39, 0
	s_add_u32 s44, s40, 0x100
	s_addc_u32 s45, s41, 0
	s_mov_b32 s70, -2
	s_add_u32 s40, s38, 0xfffc0080
	s_addc_u32 s41, s39, -1
	s_cmp_eq_u32 s70, 12
	s_cselect_b32 s43, s9, s41
	s_cselect_b32 s42, s14, s40
	s_cselect_b32 s41, s29, s45
	s_cselect_b32 s40, s31, s44
	v_lshl_add_u64 v[226:227], s[38:39], 0, v[132:133]
	s_add_i32 m0, s52, 0xc000
	s_nop 0
	global_load_lds_dwordx4 v[226:227], off
	v_lshl_add_u64 v[226:227], s[38:39], 0, v[134:135]
	s_add_i32 m0, s52, 0xe000
	s_nop 0
	global_load_lds_dwordx4 v[226:227], off
	s_waitcnt vmcnt(8)
	s_waitcnt lgkmcnt(0)
	s_setprio 1
	s_barrier
	v_mfma_f32_16x16x32_bf16 v[124:127], v[148:151], v[194:197], 0
	v_mfma_f32_16x16x32_bf16 v[120:123], v[170:173], v[194:197], 0
	v_mfma_f32_16x16x32_bf16 v[108:111], v[148:151], v[202:205], 0
	v_mfma_f32_16x16x32_bf16 v[104:107], v[170:173], v[202:205], 0
	v_mfma_f32_16x16x32_bf16 v[92:95], v[148:151], v[210:213], 0
	v_mfma_f32_16x16x32_bf16 v[88:91], v[170:173], v[210:213], 0
	v_mfma_f32_16x16x32_bf16 v[76:79], v[148:151], v[218:221], 0
	v_mfma_f32_16x16x32_bf16 v[72:75], v[170:173], v[218:221], 0
	v_mfma_f32_16x16x32_bf16 v[124:127], v[166:169], v[198:201], v[124:127]
	v_mfma_f32_16x16x32_bf16 v[120:123], v[174:177], v[198:201], v[120:123]
	v_mfma_f32_16x16x32_bf16 v[108:111], v[166:169], v[206:209], v[108:111]
	v_mfma_f32_16x16x32_bf16 v[104:107], v[174:177], v[206:209], v[104:107]
	v_mfma_f32_16x16x32_bf16 v[92:95], v[166:169], v[214:217], v[92:95]
	v_mfma_f32_16x16x32_bf16 v[88:91], v[174:177], v[214:217], v[88:91]
	v_mfma_f32_16x16x32_bf16 v[76:79], v[166:169], v[222:225], v[76:79]
	v_mfma_f32_16x16x32_bf16 v[72:75], v[174:177], v[222:225], v[72:75]
	v_mfma_f32_16x16x32_bf16 v[116:119], v[178:181], v[194:197], 0
	v_mfma_f32_16x16x32_bf16 v[112:115], v[186:189], v[194:197], 0
	v_mfma_f32_16x16x32_bf16 v[100:103], v[178:181], v[202:205], 0
	v_mfma_f32_16x16x32_bf16 v[96:99], v[186:189], v[202:205], 0
	v_mfma_f32_16x16x32_bf16 v[84:87], v[178:181], v[210:213], 0
	v_mfma_f32_16x16x32_bf16 v[80:83], v[186:189], v[210:213], 0
	v_mfma_f32_16x16x32_bf16 v[68:71], v[178:181], v[218:221], 0
	v_mfma_f32_16x16x32_bf16 v[64:67], v[186:189], v[218:221], 0
	v_mfma_f32_16x16x32_bf16 v[116:119], v[182:185], v[198:201], v[116:119]
	v_mfma_f32_16x16x32_bf16 v[112:115], v[190:193], v[198:201], v[112:115]
	v_mfma_f32_16x16x32_bf16 v[100:103], v[182:185], v[206:209], v[100:103]
	v_mfma_f32_16x16x32_bf16 v[96:99], v[190:193], v[206:209], v[96:99]
	v_mfma_f32_16x16x32_bf16 v[84:87], v[182:185], v[214:217], v[84:87]
	v_mfma_f32_16x16x32_bf16 v[80:83], v[190:193], v[214:217], v[80:83]
	v_mfma_f32_16x16x32_bf16 v[68:71], v[182:185], v[222:225], v[68:71]
	v_mfma_f32_16x16x32_bf16 v[64:67], v[190:193], v[222:225], v[64:67]
	s_barrier
	s_setprio 0
	s_add_i32 s71, s61, s33
	v_lshl_add_u64 v[226:227], s[40:41], 0, v[138:139]
	s_mov_b32 m0, s71
	ds_read_b128 v[194:197], v164 offset:16384
	ds_read_b128 v[198:201], v164 offset:17408
	ds_read_b128 v[202:205], v164 offset:18432
	ds_read_b128 v[206:209], v164 offset:19456
	ds_read_b128 v[210:213], v164 offset:20480
	ds_read_b128 v[214:217], v164 offset:21504
	ds_read_b128 v[218:221], v164 offset:22528
	ds_read_b128 v[222:225], v164 offset:23552
	global_load_lds_dwordx4 v[226:227], off
	s_add_i32 m0, s71, 0x2000
	s_add_u32 s72, s40, 0x40000
	v_lshl_add_u64 v[228:229], s[40:41], 0, v[142:143]
	s_addc_u32 s73, s41, 0
	s_add_i32 s71, s62, s33
	global_load_lds_dwordx4 v[228:229], off
	v_lshl_add_u64 v[230:231], s[72:73], 0, v[138:139]
	s_mov_b32 m0, s71
	v_lshl_add_u64 v[232:233], s[42:43], 0, v[140:141]
	global_load_lds_dwordx4 v[230:231], off
	v_lshl_add_u64 v[230:231], s[72:73], 0, v[142:143]
	s_add_i32 m0, s71, 0x2000
	s_nop 0
	global_load_lds_dwordx4 v[230:231], off
	v_lshl_add_u64 v[230:231], s[42:43], 0, v[136:137]
	s_mov_b32 m0, s52
	s_nop 0
	global_load_lds_dwordx4 v[230:231], off
	s_mov_b32 m0, s53
	s_nop 0
	global_load_lds_dwordx4 v[232:233], off
	s_waitcnt vmcnt(8)
	s_waitcnt lgkmcnt(0)
	s_setprio 1
	s_barrier
	v_mfma_f32_16x16x32_bf16 v[60:63], v[148:151], v[194:197], 0
	v_mfma_f32_16x16x32_bf16 v[56:59], v[170:173], v[194:197], 0
	v_mfma_f32_16x16x32_bf16 v[44:47], v[148:151], v[202:205], 0
	v_mfma_f32_16x16x32_bf16 v[40:43], v[170:173], v[202:205], 0
	v_mfma_f32_16x16x32_bf16 v[28:31], v[148:151], v[210:213], 0
	v_mfma_f32_16x16x32_bf16 v[24:27], v[170:173], v[210:213], 0
	v_mfma_f32_16x16x32_bf16 v[12:15], v[148:151], v[218:221], 0
	v_mfma_f32_16x16x32_bf16 v[8:11], v[170:173], v[218:221], 0
	v_mfma_f32_16x16x32_bf16 v[60:63], v[166:169], v[198:201], v[60:63]
	v_mfma_f32_16x16x32_bf16 v[56:59], v[174:177], v[198:201], v[56:59]
	v_mfma_f32_16x16x32_bf16 v[44:47], v[166:169], v[206:209], v[44:47]
	v_mfma_f32_16x16x32_bf16 v[40:43], v[174:177], v[206:209], v[40:43]
	v_mfma_f32_16x16x32_bf16 v[28:31], v[166:169], v[214:217], v[28:31]
	v_mfma_f32_16x16x32_bf16 v[24:27], v[174:177], v[214:217], v[24:27]
	v_mfma_f32_16x16x32_bf16 v[12:15], v[166:169], v[222:225], v[12:15]
	v_mfma_f32_16x16x32_bf16 v[8:11], v[174:177], v[222:225], v[8:11]
	v_mfma_f32_16x16x32_bf16 v[52:55], v[178:181], v[194:197], 0
	v_mfma_f32_16x16x32_bf16 v[48:51], v[186:189], v[194:197], 0
	v_mfma_f32_16x16x32_bf16 v[36:39], v[178:181], v[202:205], 0
	v_mfma_f32_16x16x32_bf16 v[32:35], v[186:189], v[202:205], 0
	v_mfma_f32_16x16x32_bf16 v[20:23], v[178:181], v[210:213], 0
	v_mfma_f32_16x16x32_bf16 v[16:19], v[186:189], v[210:213], 0
	v_mfma_f32_16x16x32_bf16 v[4:7], v[178:181], v[218:221], 0
	v_mfma_f32_16x16x32_bf16 v[0:3], v[186:189], v[218:221], 0
	v_mfma_f32_16x16x32_bf16 v[52:55], v[182:185], v[198:201], v[52:55]
	v_mfma_f32_16x16x32_bf16 v[48:51], v[190:193], v[198:201], v[48:51]
	v_mfma_f32_16x16x32_bf16 v[36:39], v[182:185], v[206:209], v[36:39]
	v_mfma_f32_16x16x32_bf16 v[32:35], v[190:193], v[206:209], v[32:35]
	v_mfma_f32_16x16x32_bf16 v[20:23], v[182:185], v[214:217], v[20:23]
	v_mfma_f32_16x16x32_bf16 v[16:19], v[190:193], v[214:217], v[16:19]
	v_mfma_f32_16x16x32_bf16 v[4:7], v[182:185], v[222:225], v[4:7]
	v_mfma_f32_16x16x32_bf16 v[0:3], v[190:193], v[222:225], v[0:3]
	s_barrier
; #define PG8_STAGE(bufoff, gbase, voff) do { _Pragma("unroll") for (int _i = 0; _i < 2; ++_i) \
;         __builtin_amdgcn_global_load_lds((const unsigned*)((const char*)(gbase) + (voff)[_i]), (PG8_LAS unsigned*)(lds + (bufoff) + ldsw + _i * 8192), 16, 0, 0); } while (0)
; #define PG8_LDA(dst, b, h) do { _Pragma("unroll") for (int m = 0; m < 4; ++m) _Pragma("unroll") for (int k = 0; k < 2; ++k) dst[m][k] = *(const PG8_LAS bf16x8*)(lds + PG8_SA(b, h) + aoff + m * 2048 + k * 1024); } while (0)
; #define PG8_LDB(dst, b, h) do { _Pragma("unroll") for (int n = 0; n < 2; ++n) _Pragma("unroll") for (int k = 0; k < 2; ++k) dst[n][k] = *(const PG8_LAS bf16x8*)(lds + PG8_SB(b, h) + boff + n * 2048 + k * 1024); } while (0)
; #define PG8_MMA(ai, bj, At, Bt) do { __builtin_amdgcn_s_setprio(1); _Pragma("unroll") for (int m = 0; m < 4; ++m) _Pragma("unroll") for (int n = 0; n < 2; ++n) _Pragma("unroll") for (int k = 0; k < 2; ++k) \
;         acc[ai][bj][m][n] = __builtin_amdgcn_mfma_f32_16x16x32_bf16(Bt[n][k], At[m][k], acc[ai][bj][m][n], 0, 0, 0); __builtin_amdgcn_s_setprio(0); } while (0)
; #define PG8_WAIT_V(n) asm volatile("s_waitcnt vmcnt(" #n ")" ::: "memory")
; #define PG8_WAIT_L(n) asm volatile("s_waitcnt lgkmcnt(" #n ")" ::: "memory")
; #define PG8_BAR __builtin_amdgcn_s_barrier()
; #define PG8_SCHED __builtin_amdgcn_sched_barrier(0)
; template <class Epi, class Sched, bool ALIGN_EPI = false, bool SP2 = false>
; __device__ __forceinline__ void gemm_phase(PG8_LAS unsigned char* lds, const Gemm g, const Sched& S, const Epi& E) {
;     ...
;             PG8_LDB(B0, 1, 0); PG8_LDB(B1, 1, 1); PG8_SCHED; PG8_LDA(At, 1, 0); PG8_STAGE(PG8_SA(0, 1), a2 + hstep, voffA);
;             PG8_WAIT_V(8); PG8_WAIT_L(0); PG8_BAR; PG8_MMA(0, 0, At, B0); PG8_MMA(0, 1, At, B1); PG8_BAR; PG8_SCHED;
	s_setprio 0
	s_add_i32 s71, 0, 0x18000
	v_add_u32_e32 v130, s71, v160
	s_add_i32 s72, 0, 0x1c000
	ds_read_b128 v[148:151], v130
	ds_read_b128 v[166:169], v130 offset:1024
	ds_read_b128 v[170:173], v130 offset:2048
	ds_read_b128 v[174:177], v130 offset:3072
	v_add_u32_e32 v130, s72, v160
	ds_read_b128 v[178:181], v130
	ds_read_b128 v[182:185], v130 offset:1024
	ds_read_b128 v[186:189], v130 offset:2048
	ds_read_b128 v[190:193], v130 offset:3072
	s_add_u32 s42, s42, 0x40000
	s_addc_u32 s43, s43, 0
	s_mov_b32 m0, s54
	v_lshl_add_u64 v[234:235], s[42:43], 0, v[136:137]
	ds_read_b128 v[194:197], v164 offset:32768
	ds_read_b128 v[198:201], v164 offset:33792
	ds_read_b128 v[202:205], v164 offset:34816
	ds_read_b128 v[206:209], v164 offset:35840
	ds_read_b128 v[210:213], v164 offset:36864
	ds_read_b128 v[214:217], v164 offset:37888
	ds_read_b128 v[218:221], v164 offset:38912
	ds_read_b128 v[222:225], v164 offset:39936
	global_load_lds_dwordx4 v[234:235], off
	v_lshl_add_u64 v[234:235], s[42:43], 0, v[140:141]
	s_mov_b32 m0, s55
	s_nop 0
	global_load_lds_dwordx4 v[234:235], off
	s_waitcnt vmcnt(8)
	s_waitcnt lgkmcnt(0)
	s_setprio 1
	s_barrier
	v_mfma_f32_16x16x32_bf16 v[124:127], v[148:151], v[194:197], v[124:127]
	v_mfma_f32_16x16x32_bf16 v[120:123], v[170:173], v[194:197], v[120:123]
	v_mfma_f32_16x16x32_bf16 v[108:111], v[148:151], v[202:205], v[108:111]
	v_mfma_f32_16x16x32_bf16 v[104:107], v[170:173], v[202:205], v[104:107]
	v_mfma_f32_16x16x32_bf16 v[92:95], v[148:151], v[210:213], v[92:95]
	v_mfma_f32_16x16x32_bf16 v[88:91], v[170:173], v[210:213], v[88:91]
	v_mfma_f32_16x16x32_bf16 v[76:79], v[148:151], v[218:221], v[76:79]
	v_mfma_f32_16x16x32_bf16 v[72:75], v[170:173], v[218:221], v[72:75]
	v_mfma_f32_16x16x32_bf16 v[124:127], v[166:169], v[198:201], v[124:127]
	v_mfma_f32_16x16x32_bf16 v[120:123], v[174:177], v[198:201], v[120:123]
	v_mfma_f32_16x16x32_bf16 v[108:111], v[166:169], v[206:209], v[108:111]
	v_mfma_f32_16x16x32_bf16 v[104:107], v[174:177], v[206:209], v[104:107]
	v_mfma_f32_16x16x32_bf16 v[92:95], v[166:169], v[214:217], v[92:95]
	v_mfma_f32_16x16x32_bf16 v[88:91], v[174:177], v[214:217], v[88:91]
	v_mfma_f32_16x16x32_bf16 v[76:79], v[166:169], v[222:225], v[76:79]
	v_mfma_f32_16x16x32_bf16 v[72:75], v[174:177], v[222:225], v[72:75]
	v_mfma_f32_16x16x32_bf16 v[116:119], v[178:181], v[194:197], v[116:119]
	v_mfma_f32_16x16x32_bf16 v[112:115], v[186:189], v[194:197], v[112:115]
	v_mfma_f32_16x16x32_bf16 v[100:103], v[178:181], v[202:205], v[100:103]
	v_mfma_f32_16x16x32_bf16 v[96:99], v[186:189], v[202:205], v[96:99]
	v_mfma_f32_16x16x32_bf16 v[84:87], v[178:181], v[210:213], v[84:87]
	v_mfma_f32_16x16x32_bf16 v[80:83], v[186:189], v[210:213], v[80:83]
	v_mfma_f32_16x16x32_bf16 v[68:71], v[178:181], v[218:221], v[68:71]
	v_mfma_f32_16x16x32_bf16 v[64:67], v[186:189], v[218:221], v[64:67]
	v_mfma_f32_16x16x32_bf16 v[116:119], v[182:185], v[198:201], v[116:119]
	v_mfma_f32_16x16x32_bf16 v[112:115], v[190:193], v[198:201], v[112:115]
	v_mfma_f32_16x16x32_bf16 v[100:103], v[182:185], v[206:209], v[100:103]
	v_mfma_f32_16x16x32_bf16 v[96:99], v[190:193], v[206:209], v[96:99]
	v_mfma_f32_16x16x32_bf16 v[84:87], v[182:185], v[214:217], v[84:87]
	v_mfma_f32_16x16x32_bf16 v[80:83], v[190:193], v[214:217], v[80:83]
	v_mfma_f32_16x16x32_bf16 v[68:71], v[182:185], v[222:225], v[68:71]
	v_mfma_f32_16x16x32_bf16 v[64:67], v[190:193], v[222:225], v[64:67]
	s_barrier
; #define PG8_STAGE(bufoff, gbase, voff) do { _Pragma("unroll") for (int _i = 0; _i < 2; ++_i) \
;         __builtin_amdgcn_global_load_lds((const unsigned*)((const char*)(gbase) + (voff)[_i]), (PG8_LAS unsigned*)(lds + (bufoff) + ldsw + _i * 8192), 16, 0, 0); } while (0)
; #define PG8_LDA(dst, b, h) do { _Pragma("unroll") for (int m = 0; m < 4; ++m) _Pragma("unroll") for (int k = 0; k < 2; ++k) dst[m][k] = *(const PG8_LAS bf16x8*)(lds + PG8_SA(b, h) + aoff + m * 2048 + k * 1024); } while (0)
; #define PG8_MMA(ai, bj, At, Bt) do { __builtin_amdgcn_s_setprio(1); _Pragma("unroll") for (int m = 0; m < 4; ++m) _Pragma("unroll") for (int n = 0; n < 2; ++n) _Pragma("unroll") for (int k = 0; k < 2; ++k) \
;         acc[ai][bj][m][n] = __builtin_amdgcn_mfma_f32_16x16x32_bf16(Bt[n][k], At[m][k], acc[ai][bj][m][n], 0, 0, 0); __builtin_amdgcn_s_setprio(0); } while (0)
; #define PG8_WAIT_V(n) asm volatile("s_waitcnt vmcnt(" #n ")" ::: "memory")
; #define PG8_WAIT_L(n) asm volatile("s_waitcnt lgkmcnt(" #n ")" ::: "memory")
; #define PG8_BAR __builtin_amdgcn_s_barrier()
; #define PG8_SCHED __builtin_amdgcn_sched_barrier(0)
; template <class Epi, class Sched, bool ALIGN_EPI = false, bool SP2 = false>
; __device__ __forceinline__ void gemm_phase(PG8_LAS unsigned char* lds, const Gemm g, const Sched& S, const Epi& E) {
;     ...
;             PG8_LDA(At, 1, 1); PG8_STAGE(PG8_SB(1, 0), b3, voffB); PG8_STAGE(PG8_SB(1, 1), b3 + hstep, voffB); PG8_STAGE(PG8_SA(1, 0), a3, voffA);
;             PG8_WAIT_V(8); PG8_WAIT_L(0); PG8_BAR; PG8_MMA(1, 0, At, B0); PG8_MMA(1, 1, At, B1); PG8_BAR; PG8_SCHED;
	s_setprio 0
	s_add_i32 s42, s71, s33
	v_lshl_add_u64 v[226:227], v[226:227], 0, s[24:25]
	s_mov_b32 m0, s42
	ds_read_b128 v[194:197], v164 offset:49152
	ds_read_b128 v[198:201], v164 offset:50176
	ds_read_b128 v[202:205], v164 offset:51200
	ds_read_b128 v[206:209], v164 offset:52224
	ds_read_b128 v[210:213], v164 offset:53248
	ds_read_b128 v[214:217], v164 offset:54272
	ds_read_b128 v[218:221], v164 offset:55296
	ds_read_b128 v[222:225], v164 offset:56320
	global_load_lds_dwordx4 v[226:227], off
	s_add_i32 m0, s42, 0x2000
	s_add_u32 s40, s40, 0x40080
	v_lshl_add_u64 v[226:227], v[228:229], 0, s[24:25]
	s_addc_u32 s41, s41, 0
	s_add_i32 s42, s72, s33
	global_load_lds_dwordx4 v[226:227], off
	v_lshl_add_u64 v[226:227], s[40:41], 0, v[138:139]
	s_mov_b32 m0, s42
	s_nop 0
	global_load_lds_dwordx4 v[226:227], off
	v_lshl_add_u64 v[226:227], s[40:41], 0, v[142:143]
	s_add_i32 m0, s42, 0x2000
	s_nop 0
	global_load_lds_dwordx4 v[226:227], off
	v_lshl_add_u64 v[226:227], v[230:231], 0, s[24:25]
	s_mov_b32 m0, s57
	s_nop 0
	global_load_lds_dwordx4 v[226:227], off
	v_lshl_add_u64 v[226:227], v[232:233], 0, s[24:25]
	s_mov_b32 m0, s58
	s_nop 0
	global_load_lds_dwordx4 v[226:227], off
	s_waitcnt vmcnt(8)
	s_waitcnt lgkmcnt(0)
	s_setprio 1
	s_barrier
	v_mfma_f32_16x16x32_bf16 v[60:63], v[148:151], v[194:197], v[60:63]
	v_mfma_f32_16x16x32_bf16 v[56:59], v[170:173], v[194:197], v[56:59]
	v_mfma_f32_16x16x32_bf16 v[44:47], v[148:151], v[202:205], v[44:47]
	v_mfma_f32_16x16x32_bf16 v[40:43], v[170:173], v[202:205], v[40:43]
	v_mfma_f32_16x16x32_bf16 v[28:31], v[148:151], v[210:213], v[28:31]
	v_mfma_f32_16x16x32_bf16 v[24:27], v[170:173], v[210:213], v[24:27]
	v_mfma_f32_16x16x32_bf16 v[12:15], v[148:151], v[218:221], v[12:15]
	v_mfma_f32_16x16x32_bf16 v[8:11], v[170:173], v[218:221], v[8:11]
	v_mfma_f32_16x16x32_bf16 v[60:63], v[166:169], v[198:201], v[60:63]
	v_mfma_f32_16x16x32_bf16 v[56:59], v[174:177], v[198:201], v[56:59]
	v_mfma_f32_16x16x32_bf16 v[44:47], v[166:169], v[206:209], v[44:47]
	v_mfma_f32_16x16x32_bf16 v[40:43], v[174:177], v[206:209], v[40:43]
	v_mfma_f32_16x16x32_bf16 v[28:31], v[166:169], v[214:217], v[28:31]
	v_mfma_f32_16x16x32_bf16 v[24:27], v[174:177], v[214:217], v[24:27]
	v_mfma_f32_16x16x32_bf16 v[12:15], v[166:169], v[222:225], v[12:15]
	v_mfma_f32_16x16x32_bf16 v[8:11], v[174:177], v[222:225], v[8:11]
	v_mfma_f32_16x16x32_bf16 v[52:55], v[178:181], v[194:197], v[52:55]
	v_mfma_f32_16x16x32_bf16 v[48:51], v[186:189], v[194:197], v[48:51]
	v_mfma_f32_16x16x32_bf16 v[36:39], v[178:181], v[202:205], v[36:39]
	v_mfma_f32_16x16x32_bf16 v[32:35], v[186:189], v[202:205], v[32:35]
	v_mfma_f32_16x16x32_bf16 v[20:23], v[178:181], v[210:213], v[20:23]
	v_mfma_f32_16x16x32_bf16 v[16:19], v[186:189], v[210:213], v[16:19]
	v_mfma_f32_16x16x32_bf16 v[4:7], v[178:181], v[218:221], v[4:7]
	v_mfma_f32_16x16x32_bf16 v[0:3], v[186:189], v[218:221], v[0:3]
	v_mfma_f32_16x16x32_bf16 v[52:55], v[182:185], v[198:201], v[52:55]
	v_mfma_f32_16x16x32_bf16 v[48:51], v[190:193], v[198:201], v[48:51]
	v_mfma_f32_16x16x32_bf16 v[36:39], v[182:185], v[206:209], v[36:39]
	v_mfma_f32_16x16x32_bf16 v[32:35], v[190:193], v[206:209], v[32:35]
	v_mfma_f32_16x16x32_bf16 v[20:23], v[182:185], v[214:217], v[20:23]
	v_mfma_f32_16x16x32_bf16 v[16:19], v[190:193], v[214:217], v[16:19]
	v_mfma_f32_16x16x32_bf16 v[4:7], v[182:185], v[222:225], v[4:7]
	v_mfma_f32_16x16x32_bf16 v[0:3], v[190:193], v[222:225], v[0:3]
	s_barrier
	s_setprio 0
	s_add_i32 s70, s70, 2
	s_add_u32 s38, s38, 0x100
	s_addc_u32 s39, s39, 0
	s_add_u32 s44, s44, 0x100
	s_addc_u32 s45, s45, 0
	s_cmp_gt_u32 s70, 13
	.p2align 6

; #define PG8_STAGE(bufoff, gbase, voff) do { _Pragma("unroll") for (int _i = 0; _i < 2; ++_i) \
;         __builtin_amdgcn_global_load_lds((const unsigned*)((const char*)(gbase) + (voff)[_i]), (PG8_LAS unsigned*)(lds + (bufoff) + ldsw + _i * 8192), 16, 0, 0); } while (0)
; #define PG8_LDA(dst, b, h) do { _Pragma("unroll") for (int m = 0; m < 4; ++m) _Pragma("unroll") for (int k = 0; k < 2; ++k) dst[m][k] = *(const PG8_LAS bf16x8*)(lds + PG8_SA(b, h) + aoff + m * 2048 + k * 1024); } while (0)
; #define PG8_LDB(dst, b, h) do { _Pragma("unroll") for (int n = 0; n < 2; ++n) _Pragma("unroll") for (int k = 0; k < 2; ++k) dst[n][k] = *(const PG8_LAS bf16x8*)(lds + PG8_SB(b, h) + boff + n * 2048 + k * 1024); } while (0)
; #define PG8_WAIT_V(n) asm volatile("s_waitcnt vmcnt(" #n ")" ::: "memory")
; #define PG8_WAIT_L(n) asm volatile("s_waitcnt lgkmcnt(" #n ")" ::: "memory")
; #define PG8_BAR __builtin_amdgcn_s_barrier()
; #define PG8_SCHED __builtin_amdgcn_sched_barrier(0)
; template <class Epi, class Sched, bool ALIGN_EPI = false, bool SP2 = false>
; __device__ __forceinline__ void gemm_phase(PG8_LAS unsigned char* lds, const Gemm g, const Sched& S, const Epi& E) {
;     ...
;         const bool has_next = S.next(ui + 1, nxt);
;         const char* nA = has_next ? (const char*)g.A + (size_t)nxt.pm * tstep : cA; const char* nB = has_next ? (const char*)g.Bt + (size_t)nxt.pn * tstep : cB;
;         for (int t = 0; t < nt; t += 2) {
;             const bool last = (t == nt - 2);
;             const char* a1 = cA + (size_t)(t + 1) * kstep;
;             const char* a2 = last ? nA : cA + (size_t)(t + 2) * kstep; const char* b2 = last ? nB : cB + (size_t)(t + 2) * kstep;
;             const char* a3 = a2 + kstep; const char* b3 = b2 + kstep;
;             if (last && has_next) S.a_ready(nxt, ui + 1);
;             if constexpr (SP2) {
;             PG8_LDB(B0, 0, 0); PG8_LDB(B1, 0, 1); PG8_SCHED; PG8_LDA(At, 0, 0); PG8_STAGE(PG8_SA(1, 1), a1 + hstep, voffA);
;             PG8_WAIT_V(8); PG8_WAIT_L(0); PG8_BAR; PG8_MMA(0, 0, At, B0); PG8_MMA(0, 1, At, B1); PG8_BAR; PG8_SCHED;
;             PG8_LDA(At, 0, 1); PG8_STAGE(PG8_SB(0, 0), b2, voffB); PG8_STAGE(PG8_SB(0, 1), b2 + hstep, voffB); PG8_STAGE(PG8_SA(0, 0), a2, voffA);
;             PG8_WAIT_V(8); PG8_WAIT_L(0); PG8_BAR; PG8_MMA(1, 0, At, B0); PG8_MMA(1, 1, At, B1); PG8_BAR; PG8_SCHED;
.LBB0_606:
	s_ashr_i32 s21, s20, 31
	s_lshl_b64 s[22:23], s[20:21], 19
	s_add_u32 s22, s36, s22
	s_addc_u32 s23, s37, s23
	s_and_b64 s[24:25], s[4:5], exec
	s_cselect_b32 s21, s23, s29
	s_cselect_b32 s55, s22, s28
	s_ashr_i32 s19, s18, 31
	s_lshl_b64 s[24:25], s[18:19], 19
	s_add_u32 s24, s48, s24
	s_addc_u32 s25, s49, s25
	s_and_b64 s[34:35], s[4:5], exec
	s_cselect_b32 s19, s25, s31
	s_cselect_b32 s56, s24, s30
	s_add_u32 s28, s28, 0x40080
	s_addc_u32 s29, s29, 0
	s_add_u32 s57, s30, 0x100
	s_addc_u32 s58, s31, 0
	s_mov_b32 s59, -2
	s_add_u32 s30, s28, 0xfffc0080
	s_addc_u32 s31, s29, -1
	s_cmp_eq_u32 s59, 12
	s_cselect_b32 s35, s21, s31
	s_cselect_b32 s34, s55, s30
	s_cselect_b32 s31, s19, s58
	s_cselect_b32 s30, s56, s57
	v_lshl_add_u64 v[160:161], s[28:29], 0, v[152:153]
	s_add_i32 m0, s38, 0xc000
	s_nop 0
	global_load_lds_dwordx4 v[160:161], off
	v_lshl_add_u64 v[160:161], s[28:29], 0, v[154:155]
	s_add_i32 m0, s38, 0xe000
	s_nop 0
	global_load_lds_dwordx4 v[160:161], off
	s_waitcnt vmcnt(8)
	s_waitcnt lgkmcnt(0)
	s_setprio 1
	s_barrier
	v_mfma_f32_16x16x32_bf16 v[124:127], v[128:131], v[198:201], 0
	v_mfma_f32_16x16x32_bf16 v[120:123], v[174:177], v[198:201], 0
	v_mfma_f32_16x16x32_bf16 v[116:119], v[128:131], v[206:209], 0
	v_mfma_f32_16x16x32_bf16 v[112:115], v[174:177], v[206:209], 0
	v_mfma_f32_16x16x32_bf16 v[108:111], v[128:131], v[214:217], 0
	v_mfma_f32_16x16x32_bf16 v[104:107], v[174:177], v[214:217], 0
	v_mfma_f32_16x16x32_bf16 v[100:103], v[128:131], v[222:225], 0
	v_mfma_f32_16x16x32_bf16 v[96:99], v[174:177], v[222:225], 0
	v_mfma_f32_16x16x32_bf16 v[124:127], v[132:135], v[202:205], v[124:127]
	v_mfma_f32_16x16x32_bf16 v[120:123], v[178:181], v[202:205], v[120:123]
	v_mfma_f32_16x16x32_bf16 v[116:119], v[132:135], v[210:213], v[116:119]
	v_mfma_f32_16x16x32_bf16 v[112:115], v[178:181], v[210:213], v[112:115]
	v_mfma_f32_16x16x32_bf16 v[108:111], v[132:135], v[218:221], v[108:111]
	v_mfma_f32_16x16x32_bf16 v[104:107], v[178:181], v[218:221], v[104:107]
	v_mfma_f32_16x16x32_bf16 v[100:103], v[132:135], v[226:229], v[100:103]
	v_mfma_f32_16x16x32_bf16 v[96:99], v[178:181], v[226:229], v[96:99]
	v_mfma_f32_16x16x32_bf16 v[60:63], v[182:185], v[198:201], 0
	v_mfma_f32_16x16x32_bf16 v[56:59], v[190:193], v[198:201], 0
	v_mfma_f32_16x16x32_bf16 v[52:55], v[182:185], v[206:209], 0
	v_mfma_f32_16x16x32_bf16 v[48:51], v[190:193], v[206:209], 0
	v_mfma_f32_16x16x32_bf16 v[44:47], v[182:185], v[214:217], 0
	v_mfma_f32_16x16x32_bf16 v[40:43], v[190:193], v[214:217], 0
	v_mfma_f32_16x16x32_bf16 v[36:39], v[182:185], v[222:225], 0
	v_mfma_f32_16x16x32_bf16 v[32:35], v[190:193], v[222:225], 0
	v_mfma_f32_16x16x32_bf16 v[60:63], v[186:189], v[202:205], v[60:63]
	v_mfma_f32_16x16x32_bf16 v[56:59], v[194:197], v[202:205], v[56:59]
	v_mfma_f32_16x16x32_bf16 v[52:55], v[186:189], v[210:213], v[52:55]
	v_mfma_f32_16x16x32_bf16 v[48:51], v[194:197], v[210:213], v[48:51]
	v_mfma_f32_16x16x32_bf16 v[44:47], v[186:189], v[218:221], v[44:47]
	v_mfma_f32_16x16x32_bf16 v[40:43], v[194:197], v[218:221], v[40:43]
	v_mfma_f32_16x16x32_bf16 v[36:39], v[186:189], v[226:229], v[36:39]
	v_mfma_f32_16x16x32_bf16 v[32:35], v[194:197], v[226:229], v[32:35]
	s_barrier
	s_setprio 0
	s_add_i32 s60, s45, s33
	v_lshl_add_u64 v[160:161], s[30:31], 0, v[138:139]
	s_mov_b32 m0, s60
	ds_read_b128 v[198:201], v172 offset:16384
	ds_read_b128 v[202:205], v172 offset:17408
	ds_read_b128 v[206:209], v172 offset:18432
	ds_read_b128 v[210:213], v172 offset:19456
	ds_read_b128 v[214:217], v172 offset:20480
	ds_read_b128 v[218:221], v172 offset:21504
	ds_read_b128 v[222:225], v172 offset:22528
	ds_read_b128 v[226:229], v172 offset:23552
	global_load_lds_dwordx4 v[160:161], off
	s_add_i32 m0, s60, 0x2000
	s_add_u32 s60, s30, 0x40000
	v_lshl_add_u64 v[230:231], s[30:31], 0, v[142:143]
	s_addc_u32 s61, s31, 0
	s_add_i32 s62, s50, s33
	global_load_lds_dwordx4 v[230:231], off
	v_lshl_add_u64 v[232:233], s[60:61], 0, v[138:139]
	s_mov_b32 m0, s62
	v_lshl_add_u64 v[234:235], s[34:35], 0, v[140:141]
	global_load_lds_dwordx4 v[232:233], off
	v_lshl_add_u64 v[232:233], s[60:61], 0, v[142:143]
	s_add_i32 m0, s62, 0x2000
	s_nop 0
	global_load_lds_dwordx4 v[232:233], off
	v_lshl_add_u64 v[232:233], s[34:35], 0, v[136:137]
	s_mov_b32 m0, s38
	s_nop 0
	global_load_lds_dwordx4 v[232:233], off
	s_mov_b32 m0, s39
	s_nop 0
	global_load_lds_dwordx4 v[234:235], off
	s_waitcnt vmcnt(8)
	s_waitcnt lgkmcnt(0)
	s_setprio 1
	s_barrier
	v_mfma_f32_16x16x32_bf16 v[92:95], v[128:131], v[198:201], 0
	v_mfma_f32_16x16x32_bf16 v[88:91], v[174:177], v[198:201], 0
	v_mfma_f32_16x16x32_bf16 v[84:87], v[128:131], v[206:209], 0
	v_mfma_f32_16x16x32_bf16 v[80:83], v[174:177], v[206:209], 0
	v_mfma_f32_16x16x32_bf16 v[76:79], v[128:131], v[214:217], 0
	v_mfma_f32_16x16x32_bf16 v[72:75], v[174:177], v[214:217], 0
	v_mfma_f32_16x16x32_bf16 v[68:71], v[128:131], v[222:225], 0
	v_mfma_f32_16x16x32_bf16 v[64:67], v[174:177], v[222:225], 0
	v_mfma_f32_16x16x32_bf16 v[92:95], v[132:135], v[202:205], v[92:95]
	v_mfma_f32_16x16x32_bf16 v[88:91], v[178:181], v[202:205], v[88:91]
	v_mfma_f32_16x16x32_bf16 v[84:87], v[132:135], v[210:213], v[84:87]
	v_mfma_f32_16x16x32_bf16 v[80:83], v[178:181], v[210:213], v[80:83]
	v_mfma_f32_16x16x32_bf16 v[76:79], v[132:135], v[218:221], v[76:79]
	v_mfma_f32_16x16x32_bf16 v[72:75], v[178:181], v[218:221], v[72:75]
	v_mfma_f32_16x16x32_bf16 v[68:71], v[132:135], v[226:229], v[68:71]
	v_mfma_f32_16x16x32_bf16 v[64:67], v[178:181], v[226:229], v[64:67]
	v_mfma_f32_16x16x32_bf16 v[28:31], v[182:185], v[198:201], 0
	v_mfma_f32_16x16x32_bf16 v[24:27], v[190:193], v[198:201], 0
	v_mfma_f32_16x16x32_bf16 v[20:23], v[182:185], v[206:209], 0
	v_mfma_f32_16x16x32_bf16 v[16:19], v[190:193], v[206:209], 0
	v_mfma_f32_16x16x32_bf16 v[12:15], v[182:185], v[214:217], 0
	v_mfma_f32_16x16x32_bf16 v[8:11], v[190:193], v[214:217], 0
	v_mfma_f32_16x16x32_bf16 v[4:7], v[182:185], v[222:225], 0
	v_mfma_f32_16x16x32_bf16 v[0:3], v[190:193], v[222:225], 0
	v_mfma_f32_16x16x32_bf16 v[28:31], v[186:189], v[202:205], v[28:31]
	v_mfma_f32_16x16x32_bf16 v[24:27], v[194:197], v[202:205], v[24:27]
	v_mfma_f32_16x16x32_bf16 v[20:23], v[186:189], v[210:213], v[20:23]
	v_mfma_f32_16x16x32_bf16 v[16:19], v[194:197], v[210:213], v[16:19]
	v_mfma_f32_16x16x32_bf16 v[12:15], v[186:189], v[218:221], v[12:15]
	v_mfma_f32_16x16x32_bf16 v[8:11], v[194:197], v[218:221], v[8:11]
	v_mfma_f32_16x16x32_bf16 v[4:7], v[186:189], v[226:229], v[4:7]
	v_mfma_f32_16x16x32_bf16 v[0:3], v[194:197], v[226:229], v[0:3]
	s_barrier
; #define PG8_STAGE(bufoff, gbase, voff) do { _Pragma("unroll") for (int _i = 0; _i < 2; ++_i) \
;         __builtin_amdgcn_global_load_lds((const unsigned*)((const char*)(gbase) + (voff)[_i]), (PG8_LAS unsigned*)(lds + (bufoff) + ldsw + _i * 8192), 16, 0, 0); } while (0)
; #define PG8_LDA(dst, b, h) do { _Pragma("unroll") for (int m = 0; m < 4; ++m) _Pragma("unroll") for (int k = 0; k < 2; ++k) dst[m][k] = *(const PG8_LAS bf16x8*)(lds + PG8_SA(b, h) + aoff + m * 2048 + k * 1024); } while (0)
; #define PG8_LDB(dst, b, h) do { _Pragma("unroll") for (int n = 0; n < 2; ++n) _Pragma("unroll") for (int k = 0; k < 2; ++k) dst[n][k] = *(const PG8_LAS bf16x8*)(lds + PG8_SB(b, h) + boff + n * 2048 + k * 1024); } while (0)
; #define PG8_MMA(ai, bj, At, Bt) do { __builtin_amdgcn_s_setprio(1); _Pragma("unroll") for (int m = 0; m < 4; ++m) _Pragma("unroll") for (int n = 0; n < 2; ++n) _Pragma("unroll") for (int k = 0; k < 2; ++k) \
;         acc[ai][bj][m][n] = __builtin_amdgcn_mfma_f32_16x16x32_bf16(Bt[n][k], At[m][k], acc[ai][bj][m][n], 0, 0, 0); __builtin_amdgcn_s_setprio(0); } while (0)
; #define PG8_WAIT_V(n) asm volatile("s_waitcnt vmcnt(" #n ")" ::: "memory")
; #define PG8_WAIT_L(n) asm volatile("s_waitcnt lgkmcnt(" #n ")" ::: "memory")
; #define PG8_BAR __builtin_amdgcn_s_barrier()
; #define PG8_SCHED __builtin_amdgcn_sched_barrier(0)
; template <class Epi, class Sched, bool ALIGN_EPI = false, bool SP2 = false>
; __device__ __forceinline__ void gemm_phase(PG8_LAS unsigned char* lds, const Gemm g, const Sched& S, const Epi& E) {
;     ...
;             PG8_LDB(B0, 1, 0); PG8_LDB(B1, 1, 1); PG8_SCHED; PG8_LDA(At, 1, 0); PG8_STAGE(PG8_SA(0, 1), a2 + hstep, voffA);
;             PG8_WAIT_V(8); PG8_WAIT_L(0); PG8_BAR; PG8_MMA(0, 0, At, B0); PG8_MMA(0, 1, At, B1); PG8_BAR; PG8_SCHED;
	s_setprio 0
	s_add_i32 s60, 0, 0x18000
	s_add_i32 s61, 0, 0x1c000
	v_add_u32_e32 v178, s60, v163
	v_add_u32_e32 v194, s61, v163
	ds_read_b128 v[128:131], v178
	ds_read_b128 v[132:135], v178 offset:1024
	ds_read_b128 v[174:177], v178 offset:2048
	ds_read_b128 v[178:181], v178 offset:3072
	ds_read_b128 v[182:185], v194
	ds_read_b128 v[186:189], v194 offset:1024
	ds_read_b128 v[190:193], v194 offset:2048
	ds_read_b128 v[194:197], v194 offset:3072
	s_add_u32 s34, s34, 0x40000
	s_addc_u32 s35, s35, 0
	s_mov_b32 m0, s40
	v_lshl_add_u64 v[236:237], s[34:35], 0, v[136:137]
	ds_read_b128 v[198:201], v172 offset:32768
	ds_read_b128 v[202:205], v172 offset:33792
	ds_read_b128 v[206:209], v172 offset:34816
	ds_read_b128 v[210:213], v172 offset:35840
	ds_read_b128 v[214:217], v172 offset:36864
	ds_read_b128 v[218:221], v172 offset:37888
	ds_read_b128 v[222:225], v172 offset:38912
	ds_read_b128 v[226:229], v172 offset:39936
	global_load_lds_dwordx4 v[236:237], off
	v_lshl_add_u64 v[236:237], s[34:35], 0, v[140:141]
	s_mov_b32 m0, s41
	s_nop 0
	global_load_lds_dwordx4 v[236:237], off
	s_waitcnt vmcnt(8)
	s_waitcnt lgkmcnt(0)
	s_setprio 1
	s_barrier
	v_mfma_f32_16x16x32_bf16 v[124:127], v[128:131], v[198:201], v[124:127]
	v_mfma_f32_16x16x32_bf16 v[120:123], v[174:177], v[198:201], v[120:123]
	v_mfma_f32_16x16x32_bf16 v[116:119], v[128:131], v[206:209], v[116:119]
	v_mfma_f32_16x16x32_bf16 v[112:115], v[174:177], v[206:209], v[112:115]
	v_mfma_f32_16x16x32_bf16 v[108:111], v[128:131], v[214:217], v[108:111]
	v_mfma_f32_16x16x32_bf16 v[104:107], v[174:177], v[214:217], v[104:107]
	v_mfma_f32_16x16x32_bf16 v[100:103], v[128:131], v[222:225], v[100:103]
	v_mfma_f32_16x16x32_bf16 v[96:99], v[174:177], v[222:225], v[96:99]
	v_mfma_f32_16x16x32_bf16 v[124:127], v[132:135], v[202:205], v[124:127]
	v_mfma_f32_16x16x32_bf16 v[120:123], v[178:181], v[202:205], v[120:123]
	v_mfma_f32_16x16x32_bf16 v[116:119], v[132:135], v[210:213], v[116:119]
	v_mfma_f32_16x16x32_bf16 v[112:115], v[178:181], v[210:213], v[112:115]
	v_mfma_f32_16x16x32_bf16 v[108:111], v[132:135], v[218:221], v[108:111]
	v_mfma_f32_16x16x32_bf16 v[104:107], v[178:181], v[218:221], v[104:107]
	v_mfma_f32_16x16x32_bf16 v[100:103], v[132:135], v[226:229], v[100:103]
	v_mfma_f32_16x16x32_bf16 v[96:99], v[178:181], v[226:229], v[96:99]
	v_mfma_f32_16x16x32_bf16 v[60:63], v[182:185], v[198:201], v[60:63]
	v_mfma_f32_16x16x32_bf16 v[56:59], v[190:193], v[198:201], v[56:59]
	v_mfma_f32_16x16x32_bf16 v[52:55], v[182:185], v[206:209], v[52:55]
	v_mfma_f32_16x16x32_bf16 v[48:51], v[190:193], v[206:209], v[48:51]
	v_mfma_f32_16x16x32_bf16 v[44:47], v[182:185], v[214:217], v[44:47]
	v_mfma_f32_16x16x32_bf16 v[40:43], v[190:193], v[214:217], v[40:43]
	v_mfma_f32_16x16x32_bf16 v[36:39], v[182:185], v[222:225], v[36:39]
	v_mfma_f32_16x16x32_bf16 v[32:35], v[190:193], v[222:225], v[32:35]
	v_mfma_f32_16x16x32_bf16 v[60:63], v[186:189], v[202:205], v[60:63]
	v_mfma_f32_16x16x32_bf16 v[56:59], v[194:197], v[202:205], v[56:59]
	v_mfma_f32_16x16x32_bf16 v[52:55], v[186:189], v[210:213], v[52:55]
	v_mfma_f32_16x16x32_bf16 v[48:51], v[194:197], v[210:213], v[48:51]
	v_mfma_f32_16x16x32_bf16 v[44:47], v[186:189], v[218:221], v[44:47]
	v_mfma_f32_16x16x32_bf16 v[40:43], v[194:197], v[218:221], v[40:43]
	v_mfma_f32_16x16x32_bf16 v[36:39], v[186:189], v[226:229], v[36:39]
	v_mfma_f32_16x16x32_bf16 v[32:35], v[194:197], v[226:229], v[32:35]
	s_barrier
; #define PG8_STAGE(bufoff, gbase, voff) do { _Pragma("unroll") for (int _i = 0; _i < 2; ++_i) \
;         __builtin_amdgcn_global_load_lds((const unsigned*)((const char*)(gbase) + (voff)[_i]), (PG8_LAS unsigned*)(lds + (bufoff) + ldsw + _i * 8192), 16, 0, 0); } while (0)
; #define PG8_LDA(dst, b, h) do { _Pragma("unroll") for (int m = 0; m < 4; ++m) _Pragma("unroll") for (int k = 0; k < 2; ++k) dst[m][k] = *(const PG8_LAS bf16x8*)(lds + PG8_SA(b, h) + aoff + m * 2048 + k * 1024); } while (0)
; #define PG8_MMA(ai, bj, At, Bt) do { __builtin_amdgcn_s_setprio(1); _Pragma("unroll") for (int m = 0; m < 4; ++m) _Pragma("unroll") for (int n = 0; n < 2; ++n) _Pragma("unroll") for (int k = 0; k < 2; ++k) \
;         acc[ai][bj][m][n] = __builtin_amdgcn_mfma_f32_16x16x32_bf16(Bt[n][k], At[m][k], acc[ai][bj][m][n], 0, 0, 0); __builtin_amdgcn_s_setprio(0); } while (0)
; #define PG8_WAIT_V(n) asm volatile("s_waitcnt vmcnt(" #n ")" ::: "memory")
; #define PG8_WAIT_L(n) asm volatile("s_waitcnt lgkmcnt(" #n ")" ::: "memory")
; #define PG8_BAR __builtin_amdgcn_s_barrier()
; #define PG8_SCHED __builtin_amdgcn_sched_barrier(0)
; template <class Epi, class Sched, bool ALIGN_EPI = false, bool SP2 = false>
; __device__ __forceinline__ void gemm_phase(PG8_LAS unsigned char* lds, const Gemm g, const Sched& S, const Epi& E) {
;     ...
;         for (int t = 0; t < nt; t += 2) {
;     ...
;             PG8_LDA(At, 1, 1); PG8_STAGE(PG8_SB(1, 0), b3, voffB); PG8_STAGE(PG8_SB(1, 1), b3 + hstep, voffB); PG8_STAGE(PG8_SA(1, 0), a3, voffA);
;             PG8_WAIT_V(8); PG8_WAIT_L(0); PG8_BAR; PG8_MMA(1, 0, At, B0); PG8_MMA(1, 1, At, B1); PG8_BAR; PG8_SCHED;
	s_setprio 0
	s_add_i32 s34, s60, s33
	v_lshl_add_u64 v[160:161], v[160:161], 0, s[16:17]
	s_mov_b32 m0, s34
	ds_read_b128 v[198:201], v172 offset:49152
	ds_read_b128 v[202:205], v172 offset:50176
	ds_read_b128 v[206:209], v172 offset:51200
	ds_read_b128 v[210:213], v172 offset:52224
	ds_read_b128 v[214:217], v172 offset:53248
	ds_read_b128 v[218:221], v172 offset:54272
	ds_read_b128 v[222:225], v172 offset:55296
	ds_read_b128 v[226:229], v172 offset:56320
	global_load_lds_dwordx4 v[160:161], off
	s_add_i32 m0, s34, 0x2000
	s_add_u32 s30, s30, 0x40080
	v_lshl_add_u64 v[160:161], v[230:231], 0, s[16:17]
	s_addc_u32 s31, s31, 0
	s_add_i32 s34, s61, s33
	global_load_lds_dwordx4 v[160:161], off
	v_lshl_add_u64 v[160:161], s[30:31], 0, v[138:139]
	s_mov_b32 m0, s34
	s_nop 0
	global_load_lds_dwordx4 v[160:161], off
	v_lshl_add_u64 v[160:161], s[30:31], 0, v[142:143]
	s_add_i32 m0, s34, 0x2000
	s_nop 0
	global_load_lds_dwordx4 v[160:161], off
	v_lshl_add_u64 v[160:161], v[232:233], 0, s[16:17]
	s_mov_b32 m0, s42
	s_nop 0
	global_load_lds_dwordx4 v[160:161], off
	v_lshl_add_u64 v[160:161], v[234:235], 0, s[16:17]
	s_mov_b32 m0, s43
	s_nop 0
	global_load_lds_dwordx4 v[160:161], off
	s_waitcnt vmcnt(8)
	s_waitcnt lgkmcnt(0)
	s_setprio 1
	s_barrier
	v_mfma_f32_16x16x32_bf16 v[92:95], v[128:131], v[198:201], v[92:95]
	v_mfma_f32_16x16x32_bf16 v[88:91], v[174:177], v[198:201], v[88:91]
	v_mfma_f32_16x16x32_bf16 v[84:87], v[128:131], v[206:209], v[84:87]
	v_mfma_f32_16x16x32_bf16 v[80:83], v[174:177], v[206:209], v[80:83]
	v_mfma_f32_16x16x32_bf16 v[76:79], v[128:131], v[214:217], v[76:79]
	v_mfma_f32_16x16x32_bf16 v[72:75], v[174:177], v[214:217], v[72:75]
	v_mfma_f32_16x16x32_bf16 v[68:71], v[128:131], v[222:225], v[68:71]
	v_mfma_f32_16x16x32_bf16 v[64:67], v[174:177], v[222:225], v[64:67]
	v_mfma_f32_16x16x32_bf16 v[92:95], v[132:135], v[202:205], v[92:95]
	v_mfma_f32_16x16x32_bf16 v[88:91], v[178:181], v[202:205], v[88:91]
	v_mfma_f32_16x16x32_bf16 v[84:87], v[132:135], v[210:213], v[84:87]
	v_mfma_f32_16x16x32_bf16 v[80:83], v[178:181], v[210:213], v[80:83]
	v_mfma_f32_16x16x32_bf16 v[76:79], v[132:135], v[218:221], v[76:79]
	v_mfma_f32_16x16x32_bf16 v[72:75], v[178:181], v[218:221], v[72:75]
	v_mfma_f32_16x16x32_bf16 v[68:71], v[132:135], v[226:229], v[68:71]
	v_mfma_f32_16x16x32_bf16 v[64:67], v[178:181], v[226:229], v[64:67]
	v_mfma_f32_16x16x32_bf16 v[28:31], v[182:185], v[198:201], v[28:31]
	v_mfma_f32_16x16x32_bf16 v[24:27], v[190:193], v[198:201], v[24:27]
	v_mfma_f32_16x16x32_bf16 v[20:23], v[182:185], v[206:209], v[20:23]
	v_mfma_f32_16x16x32_bf16 v[16:19], v[190:193], v[206:209], v[16:19]
	v_mfma_f32_16x16x32_bf16 v[12:15], v[182:185], v[214:217], v[12:15]
	v_mfma_f32_16x16x32_bf16 v[8:11], v[190:193], v[214:217], v[8:11]
	v_mfma_f32_16x16x32_bf16 v[4:7], v[182:185], v[222:225], v[4:7]
	v_mfma_f32_16x16x32_bf16 v[0:3], v[190:193], v[222:225], v[0:3]
	v_mfma_f32_16x16x32_bf16 v[28:31], v[186:189], v[202:205], v[28:31]
	v_mfma_f32_16x16x32_bf16 v[24:27], v[194:197], v[202:205], v[24:27]
	v_mfma_f32_16x16x32_bf16 v[20:23], v[186:189], v[210:213], v[20:23]
	v_mfma_f32_16x16x32_bf16 v[16:19], v[194:197], v[210:213], v[16:19]
	v_mfma_f32_16x16x32_bf16 v[12:15], v[186:189], v[218:221], v[12:15]
	v_mfma_f32_16x16x32_bf16 v[8:11], v[194:197], v[218:221], v[8:11]
	v_mfma_f32_16x16x32_bf16 v[4:7], v[186:189], v[226:229], v[4:7]
	v_mfma_f32_16x16x32_bf16 v[0:3], v[194:197], v[226:229], v[0:3]
	s_barrier
	s_setprio 0
	s_add_i32 s59, s59, 2
	s_add_u32 s28, s28, 0x100
	s_addc_u32 s29, s29, 0
	s_add_u32 s57, s57, 0x100
	s_addc_u32 s58, s58, 0
	s_cmp_gt_u32 s59, 13
	.p2align 6

; #define PG8_STAGE(bufoff, gbase, voff) do { _Pragma("unroll") for (int _i = 0; _i < 2; ++_i) \
;         __builtin_amdgcn_global_load_lds((const unsigned*)((const char*)(gbase) + (voff)[_i]), (PG8_LAS unsigned*)(lds + (bufoff) + ldsw + _i * 8192), 16, 0, 0); } while (0)
; #define PG8_LDA(dst, b, h) do { _Pragma("unroll") for (int m = 0; m < 4; ++m) _Pragma("unroll") for (int k = 0; k < 2; ++k) dst[m][k] = *(const PG8_LAS bf16x8*)(lds + PG8_SA(b, h) + aoff + m * 2048 + k * 1024); } while (0)
; #define PG8_LDB(dst, b, h) do { _Pragma("unroll") for (int n = 0; n < 2; ++n) _Pragma("unroll") for (int k = 0; k < 2; ++k) dst[n][k] = *(const PG8_LAS bf16x8*)(lds + PG8_SB(b, h) + boff + n * 2048 + k * 1024); } while (0)
; #define PG8_WAIT_V(n) asm volatile("s_waitcnt vmcnt(" #n ")" ::: "memory")
; #define PG8_WAIT_L(n) asm volatile("s_waitcnt lgkmcnt(" #n ")" ::: "memory")
; #define PG8_BAR __builtin_amdgcn_s_barrier()
; #define PG8_SCHED __builtin_amdgcn_sched_barrier(0)
; template <class Epi, class Sched, bool ALIGN_EPI = false, bool SP2 = false>
; __device__ __forceinline__ void gemm_phase(PG8_LAS unsigned char* lds, const Gemm g, const Sched& S, const Epi& E) {
;     ...
;         const char* nA = has_next ? (const char*)g.A + (size_t)nxt.pm * tstep : cA; const char* nB = has_next ? (const char*)g.Bt + (size_t)nxt.pn * tstep : cB;
;         for (int t = 0; t < nt; t += 2) {
;             const bool last = (t == nt - 2);
;             const char* a1 = cA + (size_t)(t + 1) * kstep;
;             const char* a2 = last ? nA : cA + (size_t)(t + 2) * kstep; const char* b2 = last ? nB : cB + (size_t)(t + 2) * kstep;
;             const char* a3 = a2 + kstep; const char* b3 = b2 + kstep;
;             if (last && has_next) S.a_ready(nxt, ui + 1);
;             if constexpr (SP2) {
;             PG8_LDB(B0, 0, 0); PG8_LDB(B1, 0, 1); PG8_SCHED; PG8_LDA(At, 0, 0); PG8_STAGE(PG8_SA(1, 1), a1 + hstep, voffA);
;             PG8_WAIT_V(8); PG8_WAIT_L(0); PG8_BAR; PG8_MMA(0, 0, At, B0); PG8_MMA(0, 1, At, B1); PG8_BAR; PG8_SCHED;
;             PG8_LDA(At, 0, 1); PG8_STAGE(PG8_SB(0, 0), b2, voffB); PG8_STAGE(PG8_SB(0, 1), b2 + hstep, voffB); PG8_STAGE(PG8_SA(0, 0), a2, voffA);
;             PG8_WAIT_V(8); PG8_WAIT_L(0); PG8_BAR; PG8_MMA(1, 0, At, B0); PG8_MMA(1, 1, At, B1); PG8_BAR; PG8_SCHED;
.LBB0_959:
	s_ashr_i32 s23, s22, 31
	s_lshl_b64 s[24:25], s[22:23], 19
	s_add_u32 s24, s3, s24
	s_addc_u32 s25, s33, s25
	s_and_b64 s[26:27], s[4:5], exec
	s_cselect_b32 s23, s25, s31
	s_cselect_b32 s29, s24, s30
	s_ashr_i32 s21, s20, 31
	s_lshl_b64 s[26:27], s[20:21], 19
	s_add_u32 s26, s38, s26
	s_addc_u32 s27, s39, s27
	s_and_b64 s[36:37], s[4:5], exec
	s_cselect_b32 s21, s27, s35
	s_cselect_b32 s54, s26, s34
	s_add_u32 s30, s30, 0x40080
	s_addc_u32 s31, s31, 0
	s_add_u32 s55, s34, 0x100
	s_addc_u32 s56, s35, 0
	s_mov_b32 s57, -2
	s_add_u32 s34, s30, 0xfffc0080
	s_addc_u32 s35, s31, -1
	s_cmp_eq_u32 s57, 12
	s_cselect_b32 s37, s23, s35
	s_cselect_b32 s36, s29, s34
	s_cselect_b32 s35, s21, s56
	s_cselect_b32 s34, s54, s55
	s_add_i32 m0, s41, 0xc000
	s_nop 0
	global_load_lds_dwordx4 v200, s[30:31]
	s_add_i32 m0, s41, 0xe000
	s_nop 0
	global_load_lds_dwordx4 v202, s[30:31]
	s_waitcnt vmcnt(8)
	s_waitcnt lgkmcnt(0)
	s_setprio 1
	s_barrier
	v_mfma_f32_16x16x32_bf16 v[132:135], v[120:123], v[160:163], 0
	v_mfma_f32_16x16x32_bf16 v[124:127], v[136:139], v[160:163], 0
	v_mfma_f32_16x16x32_bf16 v[108:111], v[120:123], v[168:171], 0
	v_mfma_f32_16x16x32_bf16 v[104:107], v[136:139], v[168:171], 0
	v_mfma_f32_16x16x32_bf16 v[92:95], v[120:123], v[176:179], 0
	v_mfma_f32_16x16x32_bf16 v[88:91], v[136:139], v[176:179], 0
	v_mfma_f32_16x16x32_bf16 v[76:79], v[120:123], v[184:187], 0
	v_mfma_f32_16x16x32_bf16 v[72:75], v[136:139], v[184:187], 0
	v_mfma_f32_16x16x32_bf16 v[132:135], v[128:131], v[164:167], v[132:135]
	v_mfma_f32_16x16x32_bf16 v[124:127], v[140:143], v[164:167], v[124:127]
	v_mfma_f32_16x16x32_bf16 v[108:111], v[128:131], v[172:175], v[108:111]
	v_mfma_f32_16x16x32_bf16 v[104:107], v[140:143], v[172:175], v[104:107]
	v_mfma_f32_16x16x32_bf16 v[92:95], v[128:131], v[180:183], v[92:95]
	v_mfma_f32_16x16x32_bf16 v[88:91], v[140:143], v[180:183], v[88:91]
	v_mfma_f32_16x16x32_bf16 v[76:79], v[128:131], v[188:191], v[76:79]
	v_mfma_f32_16x16x32_bf16 v[72:75], v[140:143], v[188:191], v[72:75]
	v_mfma_f32_16x16x32_bf16 v[116:119], v[144:147], v[160:163], 0
	v_mfma_f32_16x16x32_bf16 v[112:115], v[152:155], v[160:163], 0
	v_mfma_f32_16x16x32_bf16 v[100:103], v[144:147], v[168:171], 0
	v_mfma_f32_16x16x32_bf16 v[96:99], v[152:155], v[168:171], 0
	v_mfma_f32_16x16x32_bf16 v[84:87], v[144:147], v[176:179], 0
	v_mfma_f32_16x16x32_bf16 v[80:83], v[152:155], v[176:179], 0
	v_mfma_f32_16x16x32_bf16 v[68:71], v[144:147], v[184:187], 0
	v_mfma_f32_16x16x32_bf16 v[64:67], v[152:155], v[184:187], 0
	v_mfma_f32_16x16x32_bf16 v[116:119], v[148:151], v[164:167], v[116:119]
	v_mfma_f32_16x16x32_bf16 v[112:115], v[156:159], v[164:167], v[112:115]
	v_mfma_f32_16x16x32_bf16 v[100:103], v[148:151], v[172:175], v[100:103]
	v_mfma_f32_16x16x32_bf16 v[96:99], v[156:159], v[172:175], v[96:99]
	v_mfma_f32_16x16x32_bf16 v[84:87], v[148:151], v[180:183], v[84:87]
	v_mfma_f32_16x16x32_bf16 v[80:83], v[156:159], v[180:183], v[80:83]
	v_mfma_f32_16x16x32_bf16 v[68:71], v[148:151], v[188:191], v[68:71]
	v_mfma_f32_16x16x32_bf16 v[64:67], v[156:159], v[188:191], v[64:67]
	s_barrier
	s_setprio 0
	s_add_i32 s58, s51, s40
	v_lshl_add_u64 v[204:205], s[34:35], 0, v[194:195]
	s_mov_b32 m0, s58
	ds_read_b128 v[160:163], v247 offset:16384
	ds_read_b128 v[164:167], v247 offset:17408
	ds_read_b128 v[168:171], v247 offset:18432
	ds_read_b128 v[172:175], v247 offset:19456
	ds_read_b128 v[176:179], v247 offset:20480
	ds_read_b128 v[180:183], v247 offset:21504
	ds_read_b128 v[184:187], v247 offset:22528
	ds_read_b128 v[188:191], v247 offset:23552
	global_load_lds_dwordx4 v[204:205], off
	s_add_i32 m0, s58, 0x2000
	s_add_u32 s58, s34, 0x40000
	v_lshl_add_u64 v[206:207], s[34:35], 0, v[198:199]
	s_addc_u32 s59, s35, 0
	s_add_i32 s60, s52, s40
	global_load_lds_dwordx4 v[206:207], off
	s_mov_b32 m0, s60
	v_lshl_add_u64 v[210:211], s[36:37], 0, v[196:197]
	global_load_lds_dwordx4 v194, s[58:59]
	s_add_i32 m0, s60, 0x2000
	s_nop 0
	global_load_lds_dwordx4 v198, s[58:59]
	v_lshl_add_u64 v[208:209], s[36:37], 0, v[192:193]
	s_mov_b32 m0, s41
	s_nop 0
	global_load_lds_dwordx4 v[208:209], off
	s_mov_b32 m0, s42
	s_nop 0
	global_load_lds_dwordx4 v[210:211], off
	s_waitcnt vmcnt(8)
	s_waitcnt lgkmcnt(0)
	s_setprio 1
	s_barrier
	v_mfma_f32_16x16x32_bf16 v[60:63], v[120:123], v[160:163], 0
	v_mfma_f32_16x16x32_bf16 v[56:59], v[136:139], v[160:163], 0
	v_mfma_f32_16x16x32_bf16 v[44:47], v[120:123], v[168:171], 0
	v_mfma_f32_16x16x32_bf16 v[40:43], v[136:139], v[168:171], 0
	v_mfma_f32_16x16x32_bf16 v[28:31], v[120:123], v[176:179], 0
	v_mfma_f32_16x16x32_bf16 v[24:27], v[136:139], v[176:179], 0
	v_mfma_f32_16x16x32_bf16 v[12:15], v[120:123], v[184:187], 0
	v_mfma_f32_16x16x32_bf16 v[8:11], v[136:139], v[184:187], 0
	v_mfma_f32_16x16x32_bf16 v[60:63], v[128:131], v[164:167], v[60:63]
	v_mfma_f32_16x16x32_bf16 v[56:59], v[140:143], v[164:167], v[56:59]
	v_mfma_f32_16x16x32_bf16 v[44:47], v[128:131], v[172:175], v[44:47]
	v_mfma_f32_16x16x32_bf16 v[40:43], v[140:143], v[172:175], v[40:43]
	v_mfma_f32_16x16x32_bf16 v[28:31], v[128:131], v[180:183], v[28:31]
	v_mfma_f32_16x16x32_bf16 v[24:27], v[140:143], v[180:183], v[24:27]
	v_mfma_f32_16x16x32_bf16 v[12:15], v[128:131], v[188:191], v[12:15]
	v_mfma_f32_16x16x32_bf16 v[8:11], v[140:143], v[188:191], v[8:11]
	v_mfma_f32_16x16x32_bf16 v[52:55], v[144:147], v[160:163], 0
	v_mfma_f32_16x16x32_bf16 v[48:51], v[152:155], v[160:163], 0
	v_mfma_f32_16x16x32_bf16 v[36:39], v[144:147], v[168:171], 0
	v_mfma_f32_16x16x32_bf16 v[32:35], v[152:155], v[168:171], 0
	v_mfma_f32_16x16x32_bf16 v[20:23], v[144:147], v[176:179], 0
	v_mfma_f32_16x16x32_bf16 v[16:19], v[152:155], v[176:179], 0
	v_mfma_f32_16x16x32_bf16 v[4:7], v[144:147], v[184:187], 0
	v_mfma_f32_16x16x32_bf16 v[0:3], v[152:155], v[184:187], 0
	v_mfma_f32_16x16x32_bf16 v[52:55], v[148:151], v[164:167], v[52:55]
	v_mfma_f32_16x16x32_bf16 v[48:51], v[156:159], v[164:167], v[48:51]
	v_mfma_f32_16x16x32_bf16 v[36:39], v[148:151], v[172:175], v[36:39]
	v_mfma_f32_16x16x32_bf16 v[32:35], v[156:159], v[172:175], v[32:35]
	v_mfma_f32_16x16x32_bf16 v[20:23], v[148:151], v[180:183], v[20:23]
	v_mfma_f32_16x16x32_bf16 v[16:19], v[156:159], v[180:183], v[16:19]
	v_mfma_f32_16x16x32_bf16 v[4:7], v[148:151], v[188:191], v[4:7]
	v_mfma_f32_16x16x32_bf16 v[0:3], v[156:159], v[188:191], v[0:3]
	s_barrier
; #define PG8_STAGE(bufoff, gbase, voff) do { _Pragma("unroll") for (int _i = 0; _i < 2; ++_i) \
;         __builtin_amdgcn_global_load_lds((const unsigned*)((const char*)(gbase) + (voff)[_i]), (PG8_LAS unsigned*)(lds + (bufoff) + ldsw + _i * 8192), 16, 0, 0); } while (0)
; #define PG8_LDA(dst, b, h) do { _Pragma("unroll") for (int m = 0; m < 4; ++m) _Pragma("unroll") for (int k = 0; k < 2; ++k) dst[m][k] = *(const PG8_LAS bf16x8*)(lds + PG8_SA(b, h) + aoff + m * 2048 + k * 1024); } while (0)
; #define PG8_LDB(dst, b, h) do { _Pragma("unroll") for (int n = 0; n < 2; ++n) _Pragma("unroll") for (int k = 0; k < 2; ++k) dst[n][k] = *(const PG8_LAS bf16x8*)(lds + PG8_SB(b, h) + boff + n * 2048 + k * 1024); } while (0)
; #define PG8_MMA(ai, bj, At, Bt) do { __builtin_amdgcn_s_setprio(1); _Pragma("unroll") for (int m = 0; m < 4; ++m) _Pragma("unroll") for (int n = 0; n < 2; ++n) _Pragma("unroll") for (int k = 0; k < 2; ++k) \
;         acc[ai][bj][m][n] = __builtin_amdgcn_mfma_f32_16x16x32_bf16(Bt[n][k], At[m][k], acc[ai][bj][m][n], 0, 0, 0); __builtin_amdgcn_s_setprio(0); } while (0)
; #define PG8_WAIT_V(n) asm volatile("s_waitcnt vmcnt(" #n ")" ::: "memory")
; #define PG8_WAIT_L(n) asm volatile("s_waitcnt lgkmcnt(" #n ")" ::: "memory")
; #define PG8_BAR __builtin_amdgcn_s_barrier()
; #define PG8_SCHED __builtin_amdgcn_sched_barrier(0)
; template <class Epi, class Sched, bool ALIGN_EPI = false, bool SP2 = false>
; __device__ __forceinline__ void gemm_phase(PG8_LAS unsigned char* lds, const Gemm g, const Sched& S, const Epi& E) {
;     ...
;             PG8_LDB(B0, 1, 0); PG8_LDB(B1, 1, 1); PG8_SCHED; PG8_LDA(At, 1, 0); PG8_STAGE(PG8_SA(0, 1), a2 + hstep, voffA);
;             PG8_WAIT_V(8); PG8_WAIT_L(0); PG8_BAR; PG8_MMA(0, 0, At, B0); PG8_MMA(0, 1, At, B1); PG8_BAR; PG8_SCHED;
;             PG8_LDA(At, 1, 1); PG8_STAGE(PG8_SB(1, 0), b3, voffB); PG8_STAGE(PG8_SB(1, 1), b3 + hstep, voffB); PG8_STAGE(PG8_SA(1, 0), a3, voffA);
;             PG8_WAIT_V(8); PG8_WAIT_L(0); PG8_BAR; PG8_MMA(1, 0, At, B0); PG8_MMA(1, 1, At, B1); PG8_BAR; PG8_SCHED;
	s_setprio 0
	s_add_i32 s58, 0, 0x18000
	s_add_i32 s59, 0, 0x1c000
	v_add_u32_e32 v140, s58, v243
	v_add_u32_e32 v156, s59, v243
	ds_read_b128 v[120:123], v140
	ds_read_b128 v[128:131], v140 offset:1024
	ds_read_b128 v[136:139], v140 offset:2048
	ds_read_b128 v[140:143], v140 offset:3072
	ds_read_b128 v[144:147], v156
	ds_read_b128 v[148:151], v156 offset:1024
	ds_read_b128 v[152:155], v156 offset:2048
	ds_read_b128 v[156:159], v156 offset:3072
	s_add_u32 s36, s36, 0x40000
	s_addc_u32 s37, s37, 0
	s_mov_b32 m0, s43
	ds_read_b128 v[160:163], v247 offset:32768
	ds_read_b128 v[164:167], v247 offset:33792
	ds_read_b128 v[168:171], v247 offset:34816
	ds_read_b128 v[172:175], v247 offset:35840
	ds_read_b128 v[176:179], v247 offset:36864
	ds_read_b128 v[180:183], v247 offset:37888
	ds_read_b128 v[184:187], v247 offset:38912
	ds_read_b128 v[188:191], v247 offset:39936
	global_load_lds_dwordx4 v192, s[36:37]
	s_mov_b32 m0, s44
	s_nop 0
	global_load_lds_dwordx4 v196, s[36:37]
	s_waitcnt vmcnt(8)
	s_waitcnt lgkmcnt(0)
	s_setprio 1
	s_barrier
	v_mfma_f32_16x16x32_bf16 v[132:135], v[120:123], v[160:163], v[132:135]
	v_mfma_f32_16x16x32_bf16 v[124:127], v[136:139], v[160:163], v[124:127]
	v_mfma_f32_16x16x32_bf16 v[108:111], v[120:123], v[168:171], v[108:111]
	v_mfma_f32_16x16x32_bf16 v[104:107], v[136:139], v[168:171], v[104:107]
	v_mfma_f32_16x16x32_bf16 v[92:95], v[120:123], v[176:179], v[92:95]
	v_mfma_f32_16x16x32_bf16 v[88:91], v[136:139], v[176:179], v[88:91]
	v_mfma_f32_16x16x32_bf16 v[76:79], v[120:123], v[184:187], v[76:79]
	v_mfma_f32_16x16x32_bf16 v[72:75], v[136:139], v[184:187], v[72:75]
	v_mfma_f32_16x16x32_bf16 v[132:135], v[128:131], v[164:167], v[132:135]
	v_mfma_f32_16x16x32_bf16 v[124:127], v[140:143], v[164:167], v[124:127]
	v_mfma_f32_16x16x32_bf16 v[108:111], v[128:131], v[172:175], v[108:111]
	v_mfma_f32_16x16x32_bf16 v[104:107], v[140:143], v[172:175], v[104:107]
	v_mfma_f32_16x16x32_bf16 v[92:95], v[128:131], v[180:183], v[92:95]
	v_mfma_f32_16x16x32_bf16 v[88:91], v[140:143], v[180:183], v[88:91]
	v_mfma_f32_16x16x32_bf16 v[76:79], v[128:131], v[188:191], v[76:79]
	v_mfma_f32_16x16x32_bf16 v[72:75], v[140:143], v[188:191], v[72:75]
	v_mfma_f32_16x16x32_bf16 v[116:119], v[144:147], v[160:163], v[116:119]
	v_mfma_f32_16x16x32_bf16 v[112:115], v[152:155], v[160:163], v[112:115]
	v_mfma_f32_16x16x32_bf16 v[100:103], v[144:147], v[168:171], v[100:103]
	v_mfma_f32_16x16x32_bf16 v[96:99], v[152:155], v[168:171], v[96:99]
	v_mfma_f32_16x16x32_bf16 v[84:87], v[144:147], v[176:179], v[84:87]
	v_mfma_f32_16x16x32_bf16 v[80:83], v[152:155], v[176:179], v[80:83]
	v_mfma_f32_16x16x32_bf16 v[68:71], v[144:147], v[184:187], v[68:71]
	v_mfma_f32_16x16x32_bf16 v[64:67], v[152:155], v[184:187], v[64:67]
	v_mfma_f32_16x16x32_bf16 v[116:119], v[148:151], v[164:167], v[116:119]
	v_mfma_f32_16x16x32_bf16 v[112:115], v[156:159], v[164:167], v[112:115]
	v_mfma_f32_16x16x32_bf16 v[100:103], v[148:151], v[172:175], v[100:103]
	v_mfma_f32_16x16x32_bf16 v[96:99], v[156:159], v[172:175], v[96:99]
	v_mfma_f32_16x16x32_bf16 v[84:87], v[148:151], v[180:183], v[84:87]
	v_mfma_f32_16x16x32_bf16 v[80:83], v[156:159], v[180:183], v[80:83]
	v_mfma_f32_16x16x32_bf16 v[68:71], v[148:151], v[188:191], v[68:71]
	v_mfma_f32_16x16x32_bf16 v[64:67], v[156:159], v[188:191], v[64:67]
	s_barrier
	s_setprio 0
	s_add_i32 s36, s58, s40
	v_lshl_add_u64 v[204:205], v[204:205], 0, s[16:17]
	s_mov_b32 m0, s36
	ds_read_b128 v[160:163], v247 offset:49152
	ds_read_b128 v[164:167], v247 offset:50176
	ds_read_b128 v[168:171], v247 offset:51200
	ds_read_b128 v[172:175], v247 offset:52224
	ds_read_b128 v[176:179], v247 offset:53248
	ds_read_b128 v[180:183], v247 offset:54272
	ds_read_b128 v[184:187], v247 offset:55296
	ds_read_b128 v[188:191], v247 offset:56320
	global_load_lds_dwordx4 v[204:205], off
	s_add_i32 m0, s36, 0x2000
	s_add_u32 s34, s34, 0x40080
	v_lshl_add_u64 v[204:205], v[206:207], 0, s[16:17]
	s_addc_u32 s35, s35, 0
	s_add_i32 s36, s59, s40
	global_load_lds_dwordx4 v[204:205], off
	s_mov_b32 m0, s36
	s_nop 0
	global_load_lds_dwordx4 v194, s[34:35]
	s_add_i32 m0, s36, 0x2000
	s_nop 0
	global_load_lds_dwordx4 v198, s[34:35]
	v_lshl_add_u64 v[204:205], v[208:209], 0, s[16:17]
	s_mov_b32 m0, s46
	s_nop 0
	global_load_lds_dwordx4 v[204:205], off
	v_lshl_add_u64 v[204:205], v[210:211], 0, s[16:17]
	s_mov_b32 m0, s47
	s_nop 0
	global_load_lds_dwordx4 v[204:205], off
	s_waitcnt vmcnt(8)
	s_waitcnt lgkmcnt(0)
	s_setprio 1
	s_barrier
	v_mfma_f32_16x16x32_bf16 v[60:63], v[120:123], v[160:163], v[60:63]
	v_mfma_f32_16x16x32_bf16 v[56:59], v[136:139], v[160:163], v[56:59]
	v_mfma_f32_16x16x32_bf16 v[44:47], v[120:123], v[168:171], v[44:47]
	v_mfma_f32_16x16x32_bf16 v[40:43], v[136:139], v[168:171], v[40:43]
	v_mfma_f32_16x16x32_bf16 v[28:31], v[120:123], v[176:179], v[28:31]
	v_mfma_f32_16x16x32_bf16 v[24:27], v[136:139], v[176:179], v[24:27]
	v_mfma_f32_16x16x32_bf16 v[12:15], v[120:123], v[184:187], v[12:15]
	v_mfma_f32_16x16x32_bf16 v[8:11], v[136:139], v[184:187], v[8:11]
	v_mfma_f32_16x16x32_bf16 v[60:63], v[128:131], v[164:167], v[60:63]
	v_mfma_f32_16x16x32_bf16 v[56:59], v[140:143], v[164:167], v[56:59]
	v_mfma_f32_16x16x32_bf16 v[44:47], v[128:131], v[172:175], v[44:47]
	v_mfma_f32_16x16x32_bf16 v[40:43], v[140:143], v[172:175], v[40:43]
	v_mfma_f32_16x16x32_bf16 v[28:31], v[128:131], v[180:183], v[28:31]
	v_mfma_f32_16x16x32_bf16 v[24:27], v[140:143], v[180:183], v[24:27]
	v_mfma_f32_16x16x32_bf16 v[12:15], v[128:131], v[188:191], v[12:15]
	v_mfma_f32_16x16x32_bf16 v[8:11], v[140:143], v[188:191], v[8:11]
	v_mfma_f32_16x16x32_bf16 v[52:55], v[144:147], v[160:163], v[52:55]
	v_mfma_f32_16x16x32_bf16 v[48:51], v[152:155], v[160:163], v[48:51]
	v_mfma_f32_16x16x32_bf16 v[36:39], v[144:147], v[168:171], v[36:39]
	v_mfma_f32_16x16x32_bf16 v[32:35], v[152:155], v[168:171], v[32:35]
	v_mfma_f32_16x16x32_bf16 v[20:23], v[144:147], v[176:179], v[20:23]
	v_mfma_f32_16x16x32_bf16 v[16:19], v[152:155], v[176:179], v[16:19]
	v_mfma_f32_16x16x32_bf16 v[4:7], v[144:147], v[184:187], v[4:7]
	v_mfma_f32_16x16x32_bf16 v[0:3], v[152:155], v[184:187], v[0:3]
	v_mfma_f32_16x16x32_bf16 v[52:55], v[148:151], v[164:167], v[52:55]
	v_mfma_f32_16x16x32_bf16 v[48:51], v[156:159], v[164:167], v[48:51]
	v_mfma_f32_16x16x32_bf16 v[36:39], v[148:151], v[172:175], v[36:39]
	v_mfma_f32_16x16x32_bf16 v[32:35], v[156:159], v[172:175], v[32:35]
	v_mfma_f32_16x16x32_bf16 v[20:23], v[148:151], v[180:183], v[20:23]
	v_mfma_f32_16x16x32_bf16 v[16:19], v[156:159], v[180:183], v[16:19]
	v_mfma_f32_16x16x32_bf16 v[4:7], v[148:151], v[188:191], v[4:7]
	v_mfma_f32_16x16x32_bf16 v[0:3], v[156:159], v[188:191], v[0:3]
	s_barrier
	s_setprio 0
	s_add_i32 s57, s57, 2
	s_add_u32 s30, s30, 0x100
	s_addc_u32 s31, s31, 0
	s_add_u32 s55, s55, 0x100
	s_addc_u32 s56, s56, 0
	s_cmp_gt_u32 s57, 13
	.p2align 6

; #define PG8_STAGE(bufoff, gbase, voff) do { _Pragma("unroll") for (int _i = 0; _i < 2; ++_i) \
;         __builtin_amdgcn_global_load_lds((const unsigned*)((const char*)(gbase) + (voff)[_i]), (PG8_LAS unsigned*)(lds + (bufoff) + ldsw + _i * 8192), 16, 0, 0); } while (0)
; #define PG8_LDA(dst, b, h) do { _Pragma("unroll") for (int m = 0; m < 4; ++m) _Pragma("unroll") for (int k = 0; k < 2; ++k) dst[m][k] = *(const PG8_LAS bf16x8*)(lds + PG8_SA(b, h) + aoff + m * 2048 + k * 1024); } while (0)
; #define PG8_LDB(dst, b, h) do { _Pragma("unroll") for (int n = 0; n < 2; ++n) _Pragma("unroll") for (int k = 0; k < 2; ++k) dst[n][k] = *(const PG8_LAS bf16x8*)(lds + PG8_SB(b, h) + boff + n * 2048 + k * 1024); } while (0)
; #define PG8_WAIT_V(n) asm volatile("s_waitcnt vmcnt(" #n ")" ::: "memory")
; #define PG8_WAIT_L(n) asm volatile("s_waitcnt lgkmcnt(" #n ")" ::: "memory")
; #define PG8_BAR __builtin_amdgcn_s_barrier()
; #define PG8_SCHED __builtin_amdgcn_sched_barrier(0)
; template <class Epi, class Sched, bool ALIGN_EPI = false, bool SP2 = false>
; __device__ __forceinline__ void gemm_phase(PG8_LAS unsigned char* lds, const Gemm g, const Sched& S, const Epi& E) {
;     ...
;         const char* nA = has_next ? (const char*)g.A + (size_t)nxt.pm * tstep : cA; const char* nB = has_next ? (const char*)g.Bt + (size_t)nxt.pn * tstep : cB;
;         for (int t = 0; t < nt; t += 2) {
;             const bool last = (t == nt - 2);
;             const char* a1 = cA + (size_t)(t + 1) * kstep;
;             const char* a2 = last ? nA : cA + (size_t)(t + 2) * kstep; const char* b2 = last ? nB : cB + (size_t)(t + 2) * kstep;
;             const char* a3 = a2 + kstep; const char* b3 = b2 + kstep;
;             if (last && has_next) S.a_ready(nxt, ui + 1);
;             if constexpr (SP2) {
;             PG8_LDB(B0, 0, 0); PG8_LDB(B1, 0, 1); PG8_SCHED; PG8_LDA(At, 0, 0); PG8_STAGE(PG8_SA(1, 1), a1 + hstep, voffA);
;             PG8_WAIT_V(8); PG8_WAIT_L(0); PG8_BAR; PG8_MMA(0, 0, At, B0); PG8_MMA(0, 1, At, B1); PG8_BAR; PG8_SCHED;
;             PG8_LDA(At, 0, 1); PG8_STAGE(PG8_SB(0, 0), b2, voffB); PG8_STAGE(PG8_SB(0, 1), b2 + hstep, voffB); PG8_STAGE(PG8_SA(0, 0), a2, voffA);
;             PG8_WAIT_V(8); PG8_WAIT_L(0); PG8_BAR; PG8_MMA(1, 0, At, B0); PG8_MMA(1, 1, At, B1); PG8_BAR; PG8_SCHED;
.LBB0_1048:
	s_ashr_i32 s17, s16, 31
	s_lshl_b64 s[18:19], s[16:17], 19
	s_add_u32 s18, s34, s18
	s_addc_u32 s19, s35, s19
	s_and_b64 s[20:21], s[0:1], exec
	s_cselect_b32 s17, s19, s25
	s_cselect_b32 s50, s18, s24
	s_ashr_i32 s15, s14, 31
	s_lshl_b64 s[20:21], s[14:15], 19
	s_add_u32 s20, s36, s20
	s_addc_u32 s21, s37, s21
	s_and_b64 s[28:29], s[0:1], exec
	s_cselect_b32 s15, s21, s27
	s_cselect_b32 s51, s20, s26
	s_add_u32 s24, s24, 0x40080
	s_addc_u32 s25, s25, 0
	s_add_u32 s52, s26, 0x100
	s_addc_u32 s53, s27, 0
	s_mov_b32 s54, -2
	s_add_u32 s26, s24, 0xfffc0080
	s_addc_u32 s27, s25, -1
	s_cmp_eq_u32 s54, 12
	s_cselect_b32 s29, s17, s27
	s_cselect_b32 s28, s50, s26
	s_cselect_b32 s27, s15, s53
	s_cselect_b32 s26, s51, s52
	s_add_i32 m0, s23, 0xc000
	s_nop 0
	global_load_lds_dwordx4 v136, s[24:25]
	s_add_i32 m0, s23, 0xe000
	s_nop 0
	global_load_lds_dwordx4 v138, s[24:25]
	s_waitcnt vmcnt(8)
	s_waitcnt lgkmcnt(0)
	s_setprio 1
	s_barrier
	v_mfma_f32_16x16x32_bf16 v[124:127], v[152:155], v[184:187], 0
	v_mfma_f32_16x16x32_bf16 v[120:123], v[160:163], v[184:187], 0
	v_mfma_f32_16x16x32_bf16 v[108:111], v[152:155], v[192:195], 0
	v_mfma_f32_16x16x32_bf16 v[104:107], v[160:163], v[192:195], 0
	v_mfma_f32_16x16x32_bf16 v[92:95], v[152:155], v[200:203], 0
	v_mfma_f32_16x16x32_bf16 v[88:91], v[160:163], v[200:203], 0
	v_mfma_f32_16x16x32_bf16 v[76:79], v[152:155], v[208:211], 0
	v_mfma_f32_16x16x32_bf16 v[72:75], v[160:163], v[208:211], 0
	v_mfma_f32_16x16x32_bf16 v[124:127], v[156:159], v[188:191], v[124:127]
	v_mfma_f32_16x16x32_bf16 v[120:123], v[164:167], v[188:191], v[120:123]
	v_mfma_f32_16x16x32_bf16 v[108:111], v[156:159], v[196:199], v[108:111]
	v_mfma_f32_16x16x32_bf16 v[104:107], v[164:167], v[196:199], v[104:107]
	v_mfma_f32_16x16x32_bf16 v[92:95], v[156:159], v[204:207], v[92:95]
	v_mfma_f32_16x16x32_bf16 v[88:91], v[164:167], v[204:207], v[88:91]
	v_mfma_f32_16x16x32_bf16 v[76:79], v[156:159], v[212:215], v[76:79]
	v_mfma_f32_16x16x32_bf16 v[72:75], v[164:167], v[212:215], v[72:75]
	v_mfma_f32_16x16x32_bf16 v[116:119], v[168:171], v[184:187], 0
	v_mfma_f32_16x16x32_bf16 v[112:115], v[176:179], v[184:187], 0
	v_mfma_f32_16x16x32_bf16 v[100:103], v[168:171], v[192:195], 0
	v_mfma_f32_16x16x32_bf16 v[96:99], v[176:179], v[192:195], 0
	v_mfma_f32_16x16x32_bf16 v[84:87], v[168:171], v[200:203], 0
	v_mfma_f32_16x16x32_bf16 v[80:83], v[176:179], v[200:203], 0
	v_mfma_f32_16x16x32_bf16 v[68:71], v[168:171], v[208:211], 0
	v_mfma_f32_16x16x32_bf16 v[64:67], v[176:179], v[208:211], 0
	v_mfma_f32_16x16x32_bf16 v[116:119], v[172:175], v[188:191], v[116:119]
	v_mfma_f32_16x16x32_bf16 v[112:115], v[180:183], v[188:191], v[112:115]
	v_mfma_f32_16x16x32_bf16 v[100:103], v[172:175], v[196:199], v[100:103]
	v_mfma_f32_16x16x32_bf16 v[96:99], v[180:183], v[196:199], v[96:99]
	v_mfma_f32_16x16x32_bf16 v[84:87], v[172:175], v[204:207], v[84:87]
	v_mfma_f32_16x16x32_bf16 v[80:83], v[180:183], v[204:207], v[80:83]
	v_mfma_f32_16x16x32_bf16 v[68:71], v[172:175], v[212:215], v[68:71]
	v_mfma_f32_16x16x32_bf16 v[64:67], v[180:183], v[212:215], v[64:67]
	s_barrier
	s_setprio 0
	s_add_i32 s55, s44, s33
	v_lshl_add_u64 v[216:217], s[26:27], 0, v[132:133]
	s_mov_b32 m0, s55
	ds_read_b128 v[184:187], v150 offset:16384
	ds_read_b128 v[188:191], v150 offset:17408
	ds_read_b128 v[192:195], v150 offset:18432
	ds_read_b128 v[196:199], v150 offset:19456
	ds_read_b128 v[200:203], v150 offset:20480
	ds_read_b128 v[204:207], v150 offset:21504
	ds_read_b128 v[208:211], v150 offset:22528
	ds_read_b128 v[212:215], v150 offset:23552
	global_load_lds_dwordx4 v[216:217], off
	s_add_i32 m0, s55, 0x2000
	s_add_u32 s56, s26, 0x40000
	v_lshl_add_u64 v[218:219], s[26:27], 0, v[128:129]
	s_addc_u32 s57, s27, 0
	s_add_i32 s55, s45, s33
	global_load_lds_dwordx4 v[218:219], off
	s_mov_b32 m0, s55
	v_lshl_add_u64 v[222:223], s[28:29], 0, v[130:131]
	global_load_lds_dwordx4 v132, s[56:57]
	s_add_i32 m0, s55, 0x2000
	s_nop 0
	global_load_lds_dwordx4 v128, s[56:57]
	v_lshl_add_u64 v[220:221], s[28:29], 0, v[134:135]
	s_mov_b32 m0, s23
	s_nop 0
	global_load_lds_dwordx4 v[220:221], off
	s_mov_b32 m0, s39
	s_nop 0
	global_load_lds_dwordx4 v[222:223], off
	s_waitcnt vmcnt(8)
	s_waitcnt lgkmcnt(0)
	s_setprio 1
	s_barrier
	v_mfma_f32_16x16x32_bf16 v[60:63], v[152:155], v[184:187], 0
	v_mfma_f32_16x16x32_bf16 v[56:59], v[160:163], v[184:187], 0
	v_mfma_f32_16x16x32_bf16 v[44:47], v[152:155], v[192:195], 0
	v_mfma_f32_16x16x32_bf16 v[40:43], v[160:163], v[192:195], 0
	v_mfma_f32_16x16x32_bf16 v[28:31], v[152:155], v[200:203], 0
	v_mfma_f32_16x16x32_bf16 v[24:27], v[160:163], v[200:203], 0
	v_mfma_f32_16x16x32_bf16 v[12:15], v[152:155], v[208:211], 0
	v_mfma_f32_16x16x32_bf16 v[8:11], v[160:163], v[208:211], 0
	v_mfma_f32_16x16x32_bf16 v[60:63], v[156:159], v[188:191], v[60:63]
	v_mfma_f32_16x16x32_bf16 v[56:59], v[164:167], v[188:191], v[56:59]
	v_mfma_f32_16x16x32_bf16 v[44:47], v[156:159], v[196:199], v[44:47]
	v_mfma_f32_16x16x32_bf16 v[40:43], v[164:167], v[196:199], v[40:43]
	v_mfma_f32_16x16x32_bf16 v[28:31], v[156:159], v[204:207], v[28:31]
	v_mfma_f32_16x16x32_bf16 v[24:27], v[164:167], v[204:207], v[24:27]
	v_mfma_f32_16x16x32_bf16 v[12:15], v[156:159], v[212:215], v[12:15]
	v_mfma_f32_16x16x32_bf16 v[8:11], v[164:167], v[212:215], v[8:11]
	v_mfma_f32_16x16x32_bf16 v[52:55], v[168:171], v[184:187], 0
	v_mfma_f32_16x16x32_bf16 v[48:51], v[176:179], v[184:187], 0
	v_mfma_f32_16x16x32_bf16 v[36:39], v[168:171], v[192:195], 0
	v_mfma_f32_16x16x32_bf16 v[32:35], v[176:179], v[192:195], 0
	v_mfma_f32_16x16x32_bf16 v[20:23], v[168:171], v[200:203], 0
	v_mfma_f32_16x16x32_bf16 v[16:19], v[176:179], v[200:203], 0
	v_mfma_f32_16x16x32_bf16 v[4:7], v[168:171], v[208:211], 0
	v_mfma_f32_16x16x32_bf16 v[0:3], v[176:179], v[208:211], 0
	v_mfma_f32_16x16x32_bf16 v[52:55], v[172:175], v[188:191], v[52:55]
	v_mfma_f32_16x16x32_bf16 v[48:51], v[180:183], v[188:191], v[48:51]
	v_mfma_f32_16x16x32_bf16 v[36:39], v[172:175], v[196:199], v[36:39]
	v_mfma_f32_16x16x32_bf16 v[32:35], v[180:183], v[196:199], v[32:35]
	v_mfma_f32_16x16x32_bf16 v[20:23], v[172:175], v[204:207], v[20:23]
	v_mfma_f32_16x16x32_bf16 v[16:19], v[180:183], v[204:207], v[16:19]
	v_mfma_f32_16x16x32_bf16 v[4:7], v[172:175], v[212:215], v[4:7]
	v_mfma_f32_16x16x32_bf16 v[0:3], v[180:183], v[212:215], v[0:3]
	s_barrier
; #define PG8_STAGE(bufoff, gbase, voff) do { _Pragma("unroll") for (int _i = 0; _i < 2; ++_i) \
;         __builtin_amdgcn_global_load_lds((const unsigned*)((const char*)(gbase) + (voff)[_i]), (PG8_LAS unsigned*)(lds + (bufoff) + ldsw + _i * 8192), 16, 0, 0); } while (0)
; #define PG8_LDA(dst, b, h) do { _Pragma("unroll") for (int m = 0; m < 4; ++m) _Pragma("unroll") for (int k = 0; k < 2; ++k) dst[m][k] = *(const PG8_LAS bf16x8*)(lds + PG8_SA(b, h) + aoff + m * 2048 + k * 1024); } while (0)
; #define PG8_LDB(dst, b, h) do { _Pragma("unroll") for (int n = 0; n < 2; ++n) _Pragma("unroll") for (int k = 0; k < 2; ++k) dst[n][k] = *(const PG8_LAS bf16x8*)(lds + PG8_SB(b, h) + boff + n * 2048 + k * 1024); } while (0)
; #define PG8_MMA(ai, bj, At, Bt) do { __builtin_amdgcn_s_setprio(1); _Pragma("unroll") for (int m = 0; m < 4; ++m) _Pragma("unroll") for (int n = 0; n < 2; ++n) _Pragma("unroll") for (int k = 0; k < 2; ++k) \
;         acc[ai][bj][m][n] = __builtin_amdgcn_mfma_f32_16x16x32_bf16(Bt[n][k], At[m][k], acc[ai][bj][m][n], 0, 0, 0); __builtin_amdgcn_s_setprio(0); } while (0)
; #define PG8_WAIT_V(n) asm volatile("s_waitcnt vmcnt(" #n ")" ::: "memory")
; #define PG8_WAIT_L(n) asm volatile("s_waitcnt lgkmcnt(" #n ")" ::: "memory")
; #define PG8_BAR __builtin_amdgcn_s_barrier()
; #define PG8_SCHED __builtin_amdgcn_sched_barrier(0)
; template <class Epi, class Sched, bool ALIGN_EPI = false, bool SP2 = false>
; __device__ __forceinline__ void gemm_phase(PG8_LAS unsigned char* lds, const Gemm g, const Sched& S, const Epi& E) {
;     ...
;             PG8_LDB(B0, 1, 0); PG8_LDB(B1, 1, 1); PG8_SCHED; PG8_LDA(At, 1, 0); PG8_STAGE(PG8_SA(0, 1), a2 + hstep, voffA);
;             PG8_WAIT_V(8); PG8_WAIT_L(0); PG8_BAR; PG8_MMA(0, 0, At, B0); PG8_MMA(0, 1, At, B1); PG8_BAR; PG8_SCHED;
;             PG8_LDA(At, 1, 1); PG8_STAGE(PG8_SB(1, 0), b3, voffB); PG8_STAGE(PG8_SB(1, 1), b3 + hstep, voffB); PG8_STAGE(PG8_SA(1, 0), a3, voffA);
;             PG8_WAIT_V(8); PG8_WAIT_L(0); PG8_BAR; PG8_MMA(1, 0, At, B0); PG8_MMA(1, 1, At, B1); PG8_BAR; PG8_SCHED;
	s_setprio 0
	s_add_i32 s55, 0, 0x18000
	v_add_u32_e32 v151, s55, v145
	s_add_i32 s56, 0, 0x1c000
	ds_read_b128 v[152:155], v151
	ds_read_b128 v[156:159], v151 offset:1024
	ds_read_b128 v[160:163], v151 offset:2048
	ds_read_b128 v[164:167], v151 offset:3072
	v_add_u32_e32 v151, s56, v145
	ds_read_b128 v[168:171], v151
	ds_read_b128 v[172:175], v151 offset:1024
	ds_read_b128 v[176:179], v151 offset:2048
	ds_read_b128 v[180:183], v151 offset:3072
	s_add_u32 s28, s28, 0x40000
	s_addc_u32 s29, s29, 0
	s_mov_b32 m0, s40
	ds_read_b128 v[184:187], v150 offset:32768
	ds_read_b128 v[188:191], v150 offset:33792
	ds_read_b128 v[192:195], v150 offset:34816
	ds_read_b128 v[196:199], v150 offset:35840
	ds_read_b128 v[200:203], v150 offset:36864
	ds_read_b128 v[204:207], v150 offset:37888
	ds_read_b128 v[208:211], v150 offset:38912
	ds_read_b128 v[212:215], v150 offset:39936
	global_load_lds_dwordx4 v134, s[28:29]
	s_mov_b32 m0, s41
	s_nop 0
	global_load_lds_dwordx4 v130, s[28:29]
	s_waitcnt vmcnt(8)
	s_waitcnt lgkmcnt(0)
	s_setprio 1
	s_barrier
	v_mfma_f32_16x16x32_bf16 v[124:127], v[152:155], v[184:187], v[124:127]
	v_mfma_f32_16x16x32_bf16 v[120:123], v[160:163], v[184:187], v[120:123]
	v_mfma_f32_16x16x32_bf16 v[108:111], v[152:155], v[192:195], v[108:111]
	v_mfma_f32_16x16x32_bf16 v[104:107], v[160:163], v[192:195], v[104:107]
	v_mfma_f32_16x16x32_bf16 v[92:95], v[152:155], v[200:203], v[92:95]
	v_mfma_f32_16x16x32_bf16 v[88:91], v[160:163], v[200:203], v[88:91]
	v_mfma_f32_16x16x32_bf16 v[76:79], v[152:155], v[208:211], v[76:79]
	v_mfma_f32_16x16x32_bf16 v[72:75], v[160:163], v[208:211], v[72:75]
	v_mfma_f32_16x16x32_bf16 v[124:127], v[156:159], v[188:191], v[124:127]
	v_mfma_f32_16x16x32_bf16 v[120:123], v[164:167], v[188:191], v[120:123]
	v_mfma_f32_16x16x32_bf16 v[108:111], v[156:159], v[196:199], v[108:111]
	v_mfma_f32_16x16x32_bf16 v[104:107], v[164:167], v[196:199], v[104:107]
	v_mfma_f32_16x16x32_bf16 v[92:95], v[156:159], v[204:207], v[92:95]
	v_mfma_f32_16x16x32_bf16 v[88:91], v[164:167], v[204:207], v[88:91]
	v_mfma_f32_16x16x32_bf16 v[76:79], v[156:159], v[212:215], v[76:79]
	v_mfma_f32_16x16x32_bf16 v[72:75], v[164:167], v[212:215], v[72:75]
	v_mfma_f32_16x16x32_bf16 v[116:119], v[168:171], v[184:187], v[116:119]
	v_mfma_f32_16x16x32_bf16 v[112:115], v[176:179], v[184:187], v[112:115]
	v_mfma_f32_16x16x32_bf16 v[100:103], v[168:171], v[192:195], v[100:103]
	v_mfma_f32_16x16x32_bf16 v[96:99], v[176:179], v[192:195], v[96:99]
	v_mfma_f32_16x16x32_bf16 v[84:87], v[168:171], v[200:203], v[84:87]
	v_mfma_f32_16x16x32_bf16 v[80:83], v[176:179], v[200:203], v[80:83]
	v_mfma_f32_16x16x32_bf16 v[68:71], v[168:171], v[208:211], v[68:71]
	v_mfma_f32_16x16x32_bf16 v[64:67], v[176:179], v[208:211], v[64:67]
	v_mfma_f32_16x16x32_bf16 v[116:119], v[172:175], v[188:191], v[116:119]
	v_mfma_f32_16x16x32_bf16 v[112:115], v[180:183], v[188:191], v[112:115]
	v_mfma_f32_16x16x32_bf16 v[100:103], v[172:175], v[196:199], v[100:103]
	v_mfma_f32_16x16x32_bf16 v[96:99], v[180:183], v[196:199], v[96:99]
	v_mfma_f32_16x16x32_bf16 v[84:87], v[172:175], v[204:207], v[84:87]
	v_mfma_f32_16x16x32_bf16 v[80:83], v[180:183], v[204:207], v[80:83]
	v_mfma_f32_16x16x32_bf16 v[68:71], v[172:175], v[212:215], v[68:71]
	v_mfma_f32_16x16x32_bf16 v[64:67], v[180:183], v[212:215], v[64:67]
	s_barrier
	s_setprio 0
	s_add_i32 s28, s55, s33
	v_lshl_add_u64 v[216:217], v[216:217], 0, s[8:9]
	s_mov_b32 m0, s28
	ds_read_b128 v[184:187], v150 offset:49152
	ds_read_b128 v[188:191], v150 offset:50176
	ds_read_b128 v[192:195], v150 offset:51200
	ds_read_b128 v[196:199], v150 offset:52224
	ds_read_b128 v[200:203], v150 offset:53248
	ds_read_b128 v[204:207], v150 offset:54272
	ds_read_b128 v[208:211], v150 offset:55296
	ds_read_b128 v[212:215], v150 offset:56320
	global_load_lds_dwordx4 v[216:217], off
	s_add_i32 m0, s28, 0x2000
	s_add_u32 s26, s26, 0x40080
	v_lshl_add_u64 v[216:217], v[218:219], 0, s[8:9]
	s_addc_u32 s27, s27, 0
	s_add_i32 s28, s56, s33
	global_load_lds_dwordx4 v[216:217], off
	s_mov_b32 m0, s28
	s_nop 0
	global_load_lds_dwordx4 v132, s[26:27]
	s_add_i32 m0, s28, 0x2000
	s_nop 0
	global_load_lds_dwordx4 v128, s[26:27]
	v_lshl_add_u64 v[216:217], v[220:221], 0, s[8:9]
	s_mov_b32 m0, s42
	s_nop 0
	global_load_lds_dwordx4 v[216:217], off
	v_lshl_add_u64 v[216:217], v[222:223], 0, s[8:9]
	s_mov_b32 m0, s43
	s_nop 0
	global_load_lds_dwordx4 v[216:217], off
	s_waitcnt vmcnt(8)
	s_waitcnt lgkmcnt(0)
	s_setprio 1
	s_barrier
	v_mfma_f32_16x16x32_bf16 v[60:63], v[152:155], v[184:187], v[60:63]
	v_mfma_f32_16x16x32_bf16 v[56:59], v[160:163], v[184:187], v[56:59]
	v_mfma_f32_16x16x32_bf16 v[44:47], v[152:155], v[192:195], v[44:47]
	v_mfma_f32_16x16x32_bf16 v[40:43], v[160:163], v[192:195], v[40:43]
	v_mfma_f32_16x16x32_bf16 v[28:31], v[152:155], v[200:203], v[28:31]
	v_mfma_f32_16x16x32_bf16 v[24:27], v[160:163], v[200:203], v[24:27]
	v_mfma_f32_16x16x32_bf16 v[12:15], v[152:155], v[208:211], v[12:15]
	v_mfma_f32_16x16x32_bf16 v[8:11], v[160:163], v[208:211], v[8:11]
	v_mfma_f32_16x16x32_bf16 v[60:63], v[156:159], v[188:191], v[60:63]
	v_mfma_f32_16x16x32_bf16 v[56:59], v[164:167], v[188:191], v[56:59]
	v_mfma_f32_16x16x32_bf16 v[44:47], v[156:159], v[196:199], v[44:47]
	v_mfma_f32_16x16x32_bf16 v[40:43], v[164:167], v[196:199], v[40:43]
	v_mfma_f32_16x16x32_bf16 v[28:31], v[156:159], v[204:207], v[28:31]
	v_mfma_f32_16x16x32_bf16 v[24:27], v[164:167], v[204:207], v[24:27]
	v_mfma_f32_16x16x32_bf16 v[12:15], v[156:159], v[212:215], v[12:15]
	v_mfma_f32_16x16x32_bf16 v[8:11], v[164:167], v[212:215], v[8:11]
	v_mfma_f32_16x16x32_bf16 v[52:55], v[168:171], v[184:187], v[52:55]
	v_mfma_f32_16x16x32_bf16 v[48:51], v[176:179], v[184:187], v[48:51]
	v_mfma_f32_16x16x32_bf16 v[36:39], v[168:171], v[192:195], v[36:39]
	v_mfma_f32_16x16x32_bf16 v[32:35], v[176:179], v[192:195], v[32:35]
	v_mfma_f32_16x16x32_bf16 v[20:23], v[168:171], v[200:203], v[20:23]
	v_mfma_f32_16x16x32_bf16 v[16:19], v[176:179], v[200:203], v[16:19]
	v_mfma_f32_16x16x32_bf16 v[4:7], v[168:171], v[208:211], v[4:7]
	v_mfma_f32_16x16x32_bf16 v[0:3], v[176:179], v[208:211], v[0:3]
	v_mfma_f32_16x16x32_bf16 v[52:55], v[172:175], v[188:191], v[52:55]
	v_mfma_f32_16x16x32_bf16 v[48:51], v[180:183], v[188:191], v[48:51]
	v_mfma_f32_16x16x32_bf16 v[36:39], v[172:175], v[196:199], v[36:39]
	v_mfma_f32_16x16x32_bf16 v[32:35], v[180:183], v[196:199], v[32:35]
	v_mfma_f32_16x16x32_bf16 v[20:23], v[172:175], v[204:207], v[20:23]
	v_mfma_f32_16x16x32_bf16 v[16:19], v[180:183], v[204:207], v[16:19]
	v_mfma_f32_16x16x32_bf16 v[4:7], v[172:175], v[212:215], v[4:7]
	v_mfma_f32_16x16x32_bf16 v[0:3], v[180:183], v[212:215], v[0:3]
	s_barrier
	s_setprio 0
	s_add_i32 s54, s54, 2
	s_add_u32 s24, s24, 0x100
	s_addc_u32 s25, s25, 0
	s_add_u32 s52, s52, 0x100
	s_addc_u32 s53, s53, 0
	s_cmp_gt_u32 s54, 13
	.p2align 6

; #define PG8_STAGE(bufoff, gbase, voff) do { _Pragma("unroll") for (int _i = 0; _i < 2; ++_i) \
;         __builtin_amdgcn_global_load_lds((const unsigned*)((const char*)(gbase) + (voff)[_i]), (PG8_LAS unsigned*)(lds + (bufoff) + ldsw + _i * 8192), 16, 0, 0); } while (0)
; #define PG8_LDA(dst, b, h) do { _Pragma("unroll") for (int m = 0; m < 4; ++m) _Pragma("unroll") for (int k = 0; k < 2; ++k) dst[m][k] = *(const PG8_LAS bf16x8*)(lds + PG8_SA(b, h) + aoff + m * 2048 + k * 1024); } while (0)
; #define PG8_LDB(dst, b, h) do { _Pragma("unroll") for (int n = 0; n < 2; ++n) _Pragma("unroll") for (int k = 0; k < 2; ++k) dst[n][k] = *(const PG8_LAS bf16x8*)(lds + PG8_SB(b, h) + boff + n * 2048 + k * 1024); } while (0)
; #define PG8_MMA(ai, bj, At, Bt) do { __builtin_amdgcn_s_setprio(1); _Pragma("unroll") for (int m = 0; m < 4; ++m) _Pragma("unroll") for (int n = 0; n < 2; ++n) _Pragma("unroll") for (int k = 0; k < 2; ++k) \
;         acc[ai][bj][m][n] = __builtin_amdgcn_mfma_f32_16x16x32_bf16(Bt[n][k], At[m][k], acc[ai][bj][m][n], 0, 0, 0); __builtin_amdgcn_s_setprio(0); } while (0)
; #define PG8_WAIT_V(n) asm volatile("s_waitcnt vmcnt(" #n ")" ::: "memory")
; #define PG8_WAIT_L(n) asm volatile("s_waitcnt lgkmcnt(" #n ")" ::: "memory")
; template <class Epi, class Sched, bool ALIGN_EPI = false, bool SP2 = false>
; __device__ __forceinline__ void gemm_phase(PG8_LAS unsigned char* lds, const Gemm g, const Sched& S, const Epi& E) {
;     ...
;             const bool last = (t == nt - 2);
;             const char* a1 = cA + (size_t)(t + 1) * kstep;
;             const char* a2 = last ? nA : cA + (size_t)(t + 2) * kstep; const char* b2 = last ? nB : cB + (size_t)(t + 2) * kstep;
;             const char* a3 = a2 + kstep; const char* b3 = b2 + kstep;
;             if (last && has_next) S.a_ready(nxt, ui + 1);
;             if constexpr (SP2) {
;             PG8_LDB(B0, 0, 0); PG8_LDB(B1, 0, 1); PG8_SCHED; PG8_LDA(At, 0, 0); PG8_STAGE(PG8_SA(1, 1), a1 + hstep, voffA);
;             PG8_WAIT_V(8); PG8_WAIT_L(0); PG8_BAR; PG8_MMA(0, 0, At, B0); PG8_MMA(0, 1, At, B1); PG8_BAR; PG8_SCHED;
;             PG8_LDA(At, 0, 1); PG8_STAGE(PG8_SB(0, 0), b2, voffB); PG8_STAGE(PG8_SB(0, 1), b2 + hstep, voffB); PG8_STAGE(PG8_SA(0, 0), a2, voffA);
;             PG8_WAIT_V(8); PG8_WAIT_L(0); PG8_BAR; PG8_MMA(1, 0, At, B0); PG8_MMA(1, 1, At, B1); PG8_BAR; PG8_SCHED;
.LBB0_1129:
	s_add_u32 s24, s24, 0xb0080
	s_addc_u32 s25, s25, 0
	s_add_u32 s51, s26, 0x100
	s_addc_u32 s52, s27, 0
	s_mov_b32 s53, -2
	s_add_u32 s26, s24, 0xfff50080
	s_addc_u32 s27, s25, -1
	s_cmp_eq_u32 s53, 40
	s_cselect_b32 s29, s7, s27
	s_cselect_b32 s28, s6, s26
	s_cselect_b32 s27, s23, s52
	s_cselect_b32 s26, s22, s51
	s_add_i32 m0, s35, 0xc000
	s_nop 0
	global_load_lds_dwordx4 v200, s[24:25]
	s_add_i32 m0, s35, 0xe000
	s_nop 0
	global_load_lds_dwordx4 v202, s[24:25]
	s_waitcnt vmcnt(8)
	s_waitcnt lgkmcnt(0)
	s_setprio 1
	s_barrier
	v_mfma_f32_16x16x32_bf16 v[132:135], v[120:123], v[160:163], 0
	v_mfma_f32_16x16x32_bf16 v[124:127], v[136:139], v[160:163], 0
	v_mfma_f32_16x16x32_bf16 v[108:111], v[120:123], v[168:171], 0
	v_mfma_f32_16x16x32_bf16 v[104:107], v[136:139], v[168:171], 0
	v_mfma_f32_16x16x32_bf16 v[92:95], v[120:123], v[176:179], 0
	v_mfma_f32_16x16x32_bf16 v[88:91], v[136:139], v[176:179], 0
	v_mfma_f32_16x16x32_bf16 v[76:79], v[120:123], v[184:187], 0
	v_mfma_f32_16x16x32_bf16 v[72:75], v[136:139], v[184:187], 0
	v_mfma_f32_16x16x32_bf16 v[132:135], v[128:131], v[164:167], v[132:135]
	v_mfma_f32_16x16x32_bf16 v[124:127], v[140:143], v[164:167], v[124:127]
	v_mfma_f32_16x16x32_bf16 v[108:111], v[128:131], v[172:175], v[108:111]
	v_mfma_f32_16x16x32_bf16 v[104:107], v[140:143], v[172:175], v[104:107]
	v_mfma_f32_16x16x32_bf16 v[92:95], v[128:131], v[180:183], v[92:95]
	v_mfma_f32_16x16x32_bf16 v[88:91], v[140:143], v[180:183], v[88:91]
	v_mfma_f32_16x16x32_bf16 v[76:79], v[128:131], v[188:191], v[76:79]
	v_mfma_f32_16x16x32_bf16 v[72:75], v[140:143], v[188:191], v[72:75]
	v_mfma_f32_16x16x32_bf16 v[116:119], v[144:147], v[160:163], 0
	v_mfma_f32_16x16x32_bf16 v[112:115], v[152:155], v[160:163], 0
	v_mfma_f32_16x16x32_bf16 v[100:103], v[144:147], v[168:171], 0
	v_mfma_f32_16x16x32_bf16 v[96:99], v[152:155], v[168:171], 0
	v_mfma_f32_16x16x32_bf16 v[84:87], v[144:147], v[176:179], 0
	v_mfma_f32_16x16x32_bf16 v[80:83], v[152:155], v[176:179], 0
	v_mfma_f32_16x16x32_bf16 v[68:71], v[144:147], v[184:187], 0
	v_mfma_f32_16x16x32_bf16 v[64:67], v[152:155], v[184:187], 0
	v_mfma_f32_16x16x32_bf16 v[116:119], v[148:151], v[164:167], v[116:119]
	v_mfma_f32_16x16x32_bf16 v[112:115], v[156:159], v[164:167], v[112:115]
	v_mfma_f32_16x16x32_bf16 v[100:103], v[148:151], v[172:175], v[100:103]
	v_mfma_f32_16x16x32_bf16 v[96:99], v[156:159], v[172:175], v[96:99]
	v_mfma_f32_16x16x32_bf16 v[84:87], v[148:151], v[180:183], v[84:87]
	v_mfma_f32_16x16x32_bf16 v[80:83], v[156:159], v[180:183], v[80:83]
	v_mfma_f32_16x16x32_bf16 v[68:71], v[148:151], v[188:191], v[68:71]
	v_mfma_f32_16x16x32_bf16 v[64:67], v[156:159], v[188:191], v[64:67]
	s_barrier
	s_setprio 0
	s_add_i32 s54, s45, s34
	v_lshl_add_u64 v[204:205], s[26:27], 0, v[194:195]
	s_mov_b32 m0, s54
	ds_read_b128 v[160:163], v247 offset:16384
	ds_read_b128 v[164:167], v247 offset:17408
	ds_read_b128 v[168:171], v247 offset:18432
	ds_read_b128 v[172:175], v247 offset:19456
	ds_read_b128 v[176:179], v247 offset:20480
	ds_read_b128 v[180:183], v247 offset:21504
	ds_read_b128 v[184:187], v247 offset:22528
	ds_read_b128 v[188:191], v247 offset:23552
	global_load_lds_dwordx4 v[204:205], off
	s_add_i32 m0, s54, 0x2000
	s_add_u32 s54, s26, 0xb0000
	v_lshl_add_u64 v[206:207], s[26:27], 0, v[198:199]
	s_addc_u32 s55, s27, 0
	s_add_i32 s56, s46, s34
	global_load_lds_dwordx4 v[206:207], off
	s_mov_b32 m0, s56
	v_lshl_add_u64 v[210:211], s[28:29], 0, v[196:197]
	global_load_lds_dwordx4 v194, s[54:55]
	s_add_i32 m0, s56, 0x2000
	s_nop 0
	global_load_lds_dwordx4 v198, s[54:55]
	v_lshl_add_u64 v[208:209], s[28:29], 0, v[192:193]
	s_mov_b32 m0, s35
	s_nop 0
	global_load_lds_dwordx4 v[208:209], off
	s_mov_b32 m0, s36
	s_nop 0
	global_load_lds_dwordx4 v[210:211], off
	s_waitcnt vmcnt(8)
	s_waitcnt lgkmcnt(0)
	s_setprio 1
	s_barrier
	v_mfma_f32_16x16x32_bf16 v[60:63], v[120:123], v[160:163], 0
	v_mfma_f32_16x16x32_bf16 v[56:59], v[136:139], v[160:163], 0
	v_mfma_f32_16x16x32_bf16 v[44:47], v[120:123], v[168:171], 0
	v_mfma_f32_16x16x32_bf16 v[40:43], v[136:139], v[168:171], 0
	v_mfma_f32_16x16x32_bf16 v[28:31], v[120:123], v[176:179], 0
	v_mfma_f32_16x16x32_bf16 v[24:27], v[136:139], v[176:179], 0
	v_mfma_f32_16x16x32_bf16 v[12:15], v[120:123], v[184:187], 0
	v_mfma_f32_16x16x32_bf16 v[8:11], v[136:139], v[184:187], 0
	v_mfma_f32_16x16x32_bf16 v[60:63], v[128:131], v[164:167], v[60:63]
	v_mfma_f32_16x16x32_bf16 v[56:59], v[140:143], v[164:167], v[56:59]
	v_mfma_f32_16x16x32_bf16 v[44:47], v[128:131], v[172:175], v[44:47]
	v_mfma_f32_16x16x32_bf16 v[40:43], v[140:143], v[172:175], v[40:43]
	v_mfma_f32_16x16x32_bf16 v[28:31], v[128:131], v[180:183], v[28:31]
	v_mfma_f32_16x16x32_bf16 v[24:27], v[140:143], v[180:183], v[24:27]
	v_mfma_f32_16x16x32_bf16 v[12:15], v[128:131], v[188:191], v[12:15]
	v_mfma_f32_16x16x32_bf16 v[8:11], v[140:143], v[188:191], v[8:11]
	v_mfma_f32_16x16x32_bf16 v[52:55], v[144:147], v[160:163], 0
	v_mfma_f32_16x16x32_bf16 v[48:51], v[152:155], v[160:163], 0
	v_mfma_f32_16x16x32_bf16 v[36:39], v[144:147], v[168:171], 0
	v_mfma_f32_16x16x32_bf16 v[32:35], v[152:155], v[168:171], 0
	v_mfma_f32_16x16x32_bf16 v[20:23], v[144:147], v[176:179], 0
	v_mfma_f32_16x16x32_bf16 v[16:19], v[152:155], v[176:179], 0
	v_mfma_f32_16x16x32_bf16 v[4:7], v[144:147], v[184:187], 0
	v_mfma_f32_16x16x32_bf16 v[0:3], v[152:155], v[184:187], 0
	v_mfma_f32_16x16x32_bf16 v[52:55], v[148:151], v[164:167], v[52:55]
	v_mfma_f32_16x16x32_bf16 v[48:51], v[156:159], v[164:167], v[48:51]
	v_mfma_f32_16x16x32_bf16 v[36:39], v[148:151], v[172:175], v[36:39]
	v_mfma_f32_16x16x32_bf16 v[32:35], v[156:159], v[172:175], v[32:35]
	v_mfma_f32_16x16x32_bf16 v[20:23], v[148:151], v[180:183], v[20:23]
	v_mfma_f32_16x16x32_bf16 v[16:19], v[156:159], v[180:183], v[16:19]
	v_mfma_f32_16x16x32_bf16 v[4:7], v[148:151], v[188:191], v[4:7]
	v_mfma_f32_16x16x32_bf16 v[0:3], v[156:159], v[188:191], v[0:3]
	s_barrier
; #define PG8_STAGE(bufoff, gbase, voff) do { _Pragma("unroll") for (int _i = 0; _i < 2; ++_i) \
;         __builtin_amdgcn_global_load_lds((const unsigned*)((const char*)(gbase) + (voff)[_i]), (PG8_LAS unsigned*)(lds + (bufoff) + ldsw + _i * 8192), 16, 0, 0); } while (0)
; #define PG8_LDA(dst, b, h) do { _Pragma("unroll") for (int m = 0; m < 4; ++m) _Pragma("unroll") for (int k = 0; k < 2; ++k) dst[m][k] = *(const PG8_LAS bf16x8*)(lds + PG8_SA(b, h) + aoff + m * 2048 + k * 1024); } while (0)
; #define PG8_LDB(dst, b, h) do { _Pragma("unroll") for (int n = 0; n < 2; ++n) _Pragma("unroll") for (int k = 0; k < 2; ++k) dst[n][k] = *(const PG8_LAS bf16x8*)(lds + PG8_SB(b, h) + boff + n * 2048 + k * 1024); } while (0)
; #define PG8_MMA(ai, bj, At, Bt) do { __builtin_amdgcn_s_setprio(1); _Pragma("unroll") for (int m = 0; m < 4; ++m) _Pragma("unroll") for (int n = 0; n < 2; ++n) _Pragma("unroll") for (int k = 0; k < 2; ++k) \
;         acc[ai][bj][m][n] = __builtin_amdgcn_mfma_f32_16x16x32_bf16(Bt[n][k], At[m][k], acc[ai][bj][m][n], 0, 0, 0); __builtin_amdgcn_s_setprio(0); } while (0)
; #define PG8_WAIT_V(n) asm volatile("s_waitcnt vmcnt(" #n ")" ::: "memory")
; #define PG8_WAIT_L(n) asm volatile("s_waitcnt lgkmcnt(" #n ")" ::: "memory")
; #define PG8_BAR __builtin_amdgcn_s_barrier()
; #define PG8_SCHED __builtin_amdgcn_sched_barrier(0)
; template <class Epi, class Sched, bool ALIGN_EPI = false, bool SP2 = false>
; __device__ __forceinline__ void gemm_phase(PG8_LAS unsigned char* lds, const Gemm g, const Sched& S, const Epi& E) {
;     ...
;             PG8_LDB(B0, 1, 0); PG8_LDB(B1, 1, 1); PG8_SCHED; PG8_LDA(At, 1, 0); PG8_STAGE(PG8_SA(0, 1), a2 + hstep, voffA);
;             PG8_WAIT_V(8); PG8_WAIT_L(0); PG8_BAR; PG8_MMA(0, 0, At, B0); PG8_MMA(0, 1, At, B1); PG8_BAR; PG8_SCHED;
;             PG8_LDA(At, 1, 1); PG8_STAGE(PG8_SB(1, 0), b3, voffB); PG8_STAGE(PG8_SB(1, 1), b3 + hstep, voffB); PG8_STAGE(PG8_SA(1, 0), a3, voffA);
;             PG8_WAIT_V(8); PG8_WAIT_L(0); PG8_BAR; PG8_MMA(1, 0, At, B0); PG8_MMA(1, 1, At, B1); PG8_BAR; PG8_SCHED;
	s_setprio 0
	s_add_i32 s54, 0, 0x18000
	s_add_i32 s55, 0, 0x1c000
	v_add_u32_e32 v140, s54, v243
	v_add_u32_e32 v156, s55, v243
	ds_read_b128 v[120:123], v140
	ds_read_b128 v[128:131], v140 offset:1024
	ds_read_b128 v[136:139], v140 offset:2048
	ds_read_b128 v[140:143], v140 offset:3072
	ds_read_b128 v[144:147], v156
	ds_read_b128 v[148:151], v156 offset:1024
	ds_read_b128 v[152:155], v156 offset:2048
	ds_read_b128 v[156:159], v156 offset:3072
	s_add_u32 s28, s28, 0xb0000
	s_addc_u32 s29, s29, 0
	s_mov_b32 m0, s37
	ds_read_b128 v[160:163], v247 offset:32768
	ds_read_b128 v[164:167], v247 offset:33792
	ds_read_b128 v[168:171], v247 offset:34816
	ds_read_b128 v[172:175], v247 offset:35840
	ds_read_b128 v[176:179], v247 offset:36864
	ds_read_b128 v[180:183], v247 offset:37888
	ds_read_b128 v[184:187], v247 offset:38912
	ds_read_b128 v[188:191], v247 offset:39936
	global_load_lds_dwordx4 v192, s[28:29]
	s_mov_b32 m0, s38
	s_nop 0
	global_load_lds_dwordx4 v196, s[28:29]
	s_waitcnt vmcnt(8)
	s_waitcnt lgkmcnt(0)
	s_setprio 1
	s_barrier
	v_mfma_f32_16x16x32_bf16 v[132:135], v[120:123], v[160:163], v[132:135]
	v_mfma_f32_16x16x32_bf16 v[124:127], v[136:139], v[160:163], v[124:127]
	v_mfma_f32_16x16x32_bf16 v[108:111], v[120:123], v[168:171], v[108:111]
	v_mfma_f32_16x16x32_bf16 v[104:107], v[136:139], v[168:171], v[104:107]
	v_mfma_f32_16x16x32_bf16 v[92:95], v[120:123], v[176:179], v[92:95]
	v_mfma_f32_16x16x32_bf16 v[88:91], v[136:139], v[176:179], v[88:91]
	v_mfma_f32_16x16x32_bf16 v[76:79], v[120:123], v[184:187], v[76:79]
	v_mfma_f32_16x16x32_bf16 v[72:75], v[136:139], v[184:187], v[72:75]
	v_mfma_f32_16x16x32_bf16 v[132:135], v[128:131], v[164:167], v[132:135]
	v_mfma_f32_16x16x32_bf16 v[124:127], v[140:143], v[164:167], v[124:127]
	v_mfma_f32_16x16x32_bf16 v[108:111], v[128:131], v[172:175], v[108:111]
	v_mfma_f32_16x16x32_bf16 v[104:107], v[140:143], v[172:175], v[104:107]
	v_mfma_f32_16x16x32_bf16 v[92:95], v[128:131], v[180:183], v[92:95]
	v_mfma_f32_16x16x32_bf16 v[88:91], v[140:143], v[180:183], v[88:91]
	v_mfma_f32_16x16x32_bf16 v[76:79], v[128:131], v[188:191], v[76:79]
	v_mfma_f32_16x16x32_bf16 v[72:75], v[140:143], v[188:191], v[72:75]
	v_mfma_f32_16x16x32_bf16 v[116:119], v[144:147], v[160:163], v[116:119]
	v_mfma_f32_16x16x32_bf16 v[112:115], v[152:155], v[160:163], v[112:115]
	v_mfma_f32_16x16x32_bf16 v[100:103], v[144:147], v[168:171], v[100:103]
	v_mfma_f32_16x16x32_bf16 v[96:99], v[152:155], v[168:171], v[96:99]
	v_mfma_f32_16x16x32_bf16 v[84:87], v[144:147], v[176:179], v[84:87]
	v_mfma_f32_16x16x32_bf16 v[80:83], v[152:155], v[176:179], v[80:83]
	v_mfma_f32_16x16x32_bf16 v[68:71], v[144:147], v[184:187], v[68:71]
	v_mfma_f32_16x16x32_bf16 v[64:67], v[152:155], v[184:187], v[64:67]
	v_mfma_f32_16x16x32_bf16 v[116:119], v[148:151], v[164:167], v[116:119]
	v_mfma_f32_16x16x32_bf16 v[112:115], v[156:159], v[164:167], v[112:115]
	v_mfma_f32_16x16x32_bf16 v[100:103], v[148:151], v[172:175], v[100:103]
	v_mfma_f32_16x16x32_bf16 v[96:99], v[156:159], v[172:175], v[96:99]
	v_mfma_f32_16x16x32_bf16 v[84:87], v[148:151], v[180:183], v[84:87]
	v_mfma_f32_16x16x32_bf16 v[80:83], v[156:159], v[180:183], v[80:83]
	v_mfma_f32_16x16x32_bf16 v[68:71], v[148:151], v[188:191], v[68:71]
	v_mfma_f32_16x16x32_bf16 v[64:67], v[156:159], v[188:191], v[64:67]
	s_barrier
	s_setprio 0
	s_add_i32 s28, s54, s34
	v_lshl_add_u64 v[204:205], v[204:205], 0, s[18:19]
	s_mov_b32 m0, s28
	ds_read_b128 v[160:163], v247 offset:49152
	ds_read_b128 v[164:167], v247 offset:50176
	ds_read_b128 v[168:171], v247 offset:51200
	ds_read_b128 v[172:175], v247 offset:52224
	ds_read_b128 v[176:179], v247 offset:53248
	ds_read_b128 v[180:183], v247 offset:54272
	ds_read_b128 v[184:187], v247 offset:55296
	ds_read_b128 v[188:191], v247 offset:56320
	global_load_lds_dwordx4 v[204:205], off
	s_add_i32 m0, s28, 0x2000
	s_add_u32 s26, s26, 0xb0080
	v_lshl_add_u64 v[204:205], v[206:207], 0, s[18:19]
	s_addc_u32 s27, s27, 0
	s_add_i32 s28, s55, s34
	global_load_lds_dwordx4 v[204:205], off
	s_mov_b32 m0, s28
	s_nop 0
	global_load_lds_dwordx4 v194, s[26:27]
	s_add_i32 m0, s28, 0x2000
	s_nop 0
	global_load_lds_dwordx4 v198, s[26:27]
	v_lshl_add_u64 v[204:205], v[208:209], 0, s[18:19]
	s_mov_b32 m0, s40
	s_nop 0
	global_load_lds_dwordx4 v[204:205], off
	v_lshl_add_u64 v[204:205], v[210:211], 0, s[18:19]
	s_mov_b32 m0, s41
	s_nop 0
	global_load_lds_dwordx4 v[204:205], off
	s_waitcnt vmcnt(8)
	s_waitcnt lgkmcnt(0)
	s_setprio 1
	s_barrier
	v_mfma_f32_16x16x32_bf16 v[60:63], v[120:123], v[160:163], v[60:63]
	v_mfma_f32_16x16x32_bf16 v[56:59], v[136:139], v[160:163], v[56:59]
	v_mfma_f32_16x16x32_bf16 v[44:47], v[120:123], v[168:171], v[44:47]
	v_mfma_f32_16x16x32_bf16 v[40:43], v[136:139], v[168:171], v[40:43]
	v_mfma_f32_16x16x32_bf16 v[28:31], v[120:123], v[176:179], v[28:31]
	v_mfma_f32_16x16x32_bf16 v[24:27], v[136:139], v[176:179], v[24:27]
	v_mfma_f32_16x16x32_bf16 v[12:15], v[120:123], v[184:187], v[12:15]
	v_mfma_f32_16x16x32_bf16 v[8:11], v[136:139], v[184:187], v[8:11]
	v_mfma_f32_16x16x32_bf16 v[60:63], v[128:131], v[164:167], v[60:63]
	v_mfma_f32_16x16x32_bf16 v[56:59], v[140:143], v[164:167], v[56:59]
	v_mfma_f32_16x16x32_bf16 v[44:47], v[128:131], v[172:175], v[44:47]
	v_mfma_f32_16x16x32_bf16 v[40:43], v[140:143], v[172:175], v[40:43]
	v_mfma_f32_16x16x32_bf16 v[28:31], v[128:131], v[180:183], v[28:31]
	v_mfma_f32_16x16x32_bf16 v[24:27], v[140:143], v[180:183], v[24:27]
	v_mfma_f32_16x16x32_bf16 v[12:15], v[128:131], v[188:191], v[12:15]
	v_mfma_f32_16x16x32_bf16 v[8:11], v[140:143], v[188:191], v[8:11]
	v_mfma_f32_16x16x32_bf16 v[52:55], v[144:147], v[160:163], v[52:55]
	v_mfma_f32_16x16x32_bf16 v[48:51], v[152:155], v[160:163], v[48:51]
	v_mfma_f32_16x16x32_bf16 v[36:39], v[144:147], v[168:171], v[36:39]
	v_mfma_f32_16x16x32_bf16 v[32:35], v[152:155], v[168:171], v[32:35]
	v_mfma_f32_16x16x32_bf16 v[20:23], v[144:147], v[176:179], v[20:23]
	v_mfma_f32_16x16x32_bf16 v[16:19], v[152:155], v[176:179], v[16:19]
	v_mfma_f32_16x16x32_bf16 v[4:7], v[144:147], v[184:187], v[4:7]
	v_mfma_f32_16x16x32_bf16 v[0:3], v[152:155], v[184:187], v[0:3]
	v_mfma_f32_16x16x32_bf16 v[52:55], v[148:151], v[164:167], v[52:55]
	v_mfma_f32_16x16x32_bf16 v[48:51], v[156:159], v[164:167], v[48:51]
	v_mfma_f32_16x16x32_bf16 v[36:39], v[148:151], v[172:175], v[36:39]
	v_mfma_f32_16x16x32_bf16 v[32:35], v[156:159], v[172:175], v[32:35]
	v_mfma_f32_16x16x32_bf16 v[20:23], v[148:151], v[180:183], v[20:23]
	v_mfma_f32_16x16x32_bf16 v[16:19], v[156:159], v[180:183], v[16:19]
	v_mfma_f32_16x16x32_bf16 v[4:7], v[148:151], v[188:191], v[4:7]
	v_mfma_f32_16x16x32_bf16 v[0:3], v[156:159], v[188:191], v[0:3]
	s_barrier
	s_setprio 0
	s_add_i32 s53, s53, 2
	s_add_u32 s24, s24, 0x100
	s_addc_u32 s25, s25, 0
	s_add_u32 s51, s51, 0x100
	s_addc_u32 s52, s52, 0
	s_cmp_gt_u32 s53, 41
	.p2align 6

; #define PG8_STAGE(bufoff, gbase, voff) do { _Pragma("unroll") for (int _i = 0; _i < 2; ++_i) \
;         __builtin_amdgcn_global_load_lds((const unsigned*)((const char*)(gbase) + (voff)[_i]), (PG8_LAS unsigned*)(lds + (bufoff) + ldsw + _i * 8192), 16, 0, 0); } while (0)
; #define PG8_LDA(dst, b, h) do { _Pragma("unroll") for (int m = 0; m < 4; ++m) _Pragma("unroll") for (int k = 0; k < 2; ++k) dst[m][k] = *(const PG8_LAS bf16x8*)(lds + PG8_SA(b, h) + aoff + m * 2048 + k * 1024); } while (0)
; #define PG8_LDB(dst, b, h) do { _Pragma("unroll") for (int n = 0; n < 2; ++n) _Pragma("unroll") for (int k = 0; k < 2; ++k) dst[n][k] = *(const PG8_LAS bf16x8*)(lds + PG8_SB(b, h) + boff + n * 2048 + k * 1024); } while (0)
; #define PG8_WAIT_V(n) asm volatile("s_waitcnt vmcnt(" #n ")" ::: "memory")
; #define PG8_WAIT_L(n) asm volatile("s_waitcnt lgkmcnt(" #n ")" ::: "memory")
; #define PG8_BAR __builtin_amdgcn_s_barrier()
; #define PG8_SCHED __builtin_amdgcn_sched_barrier(0)
; template <class Epi, class Sched, bool ALIGN_EPI = false, bool SP2 = false>
; __device__ __forceinline__ void gemm_phase(PG8_LAS unsigned char* lds, const Gemm g, const Sched& S, const Epi& E) {
;     ...
;         const char* nA = has_next ? (const char*)g.A + (size_t)nxt.pm * tstep : cA; const char* nB = has_next ? (const char*)g.Bt + (size_t)nxt.pn * tstep : cB;
;         for (int t = 0; t < nt; t += 2) {
;             const bool last = (t == nt - 2);
;             const char* a1 = cA + (size_t)(t + 1) * kstep;
;             const char* a2 = last ? nA : cA + (size_t)(t + 2) * kstep; const char* b2 = last ? nB : cB + (size_t)(t + 2) * kstep;
;             const char* a3 = a2 + kstep; const char* b3 = b2 + kstep;
;             if (last && has_next) S.a_ready(nxt, ui + 1);
;             if constexpr (SP2) {
;             PG8_LDB(B0, 0, 0); PG8_LDB(B1, 0, 1); PG8_SCHED; PG8_LDA(At, 0, 0); PG8_STAGE(PG8_SA(1, 1), a1 + hstep, voffA);
;             PG8_WAIT_V(8); PG8_WAIT_L(0); PG8_BAR; PG8_MMA(0, 0, At, B0); PG8_MMA(0, 1, At, B1); PG8_BAR; PG8_SCHED;
;             PG8_LDA(At, 0, 1); PG8_STAGE(PG8_SB(0, 0), b2, voffB); PG8_STAGE(PG8_SB(0, 1), b2 + hstep, voffB); PG8_STAGE(PG8_SA(0, 0), a2, voffA);
;             PG8_WAIT_V(8); PG8_WAIT_L(0); PG8_BAR; PG8_MMA(1, 0, At, B0); PG8_MMA(1, 1, At, B1); PG8_BAR; PG8_SCHED;
.LBB0_1218:
	s_ashr_i32 s17, s16, 31
	s_lshl_b64 s[18:19], s[16:17], 19
	s_add_u32 s18, s36, s18
	s_addc_u32 s19, s37, s19
	s_and_b64 s[20:21], s[0:1], exec
	s_cselect_b32 s17, s19, s25
	s_cselect_b32 s50, s18, s24
	s_ashr_i32 s15, s14, 31
	s_lshl_b64 s[20:21], s[14:15], 19
	s_add_u32 s20, s34, s20
	s_addc_u32 s21, s35, s21
	s_and_b64 s[28:29], s[0:1], exec
	s_cselect_b32 s15, s21, s27
	s_cselect_b32 s51, s20, s26
	s_add_u32 s24, s24, 0x40080
	s_addc_u32 s25, s25, 0
	s_add_u32 s52, s26, 0x100
	s_addc_u32 s53, s27, 0
	s_mov_b32 s54, -2
	s_add_u32 s26, s24, 0xfffc0080
	s_addc_u32 s27, s25, -1
	s_cmp_eq_u32 s54, 12
	s_cselect_b32 s29, s17, s27
	s_cselect_b32 s28, s50, s26
	s_cselect_b32 s27, s15, s53
	s_cselect_b32 s26, s51, s52
	s_add_i32 m0, s23, 0xc000
	s_nop 0
	global_load_lds_dwordx4 v136, s[24:25]
	s_add_i32 m0, s23, 0xe000
	s_nop 0
	global_load_lds_dwordx4 v138, s[24:25]
	s_waitcnt vmcnt(8)
	s_waitcnt lgkmcnt(0)
	s_setprio 1
	s_barrier
	v_mfma_f32_16x16x32_bf16 v[124:127], v[152:155], v[184:187], 0
	v_mfma_f32_16x16x32_bf16 v[120:123], v[160:163], v[184:187], 0
	v_mfma_f32_16x16x32_bf16 v[108:111], v[152:155], v[192:195], 0
	v_mfma_f32_16x16x32_bf16 v[104:107], v[160:163], v[192:195], 0
	v_mfma_f32_16x16x32_bf16 v[92:95], v[152:155], v[200:203], 0
	v_mfma_f32_16x16x32_bf16 v[88:91], v[160:163], v[200:203], 0
	v_mfma_f32_16x16x32_bf16 v[76:79], v[152:155], v[208:211], 0
	v_mfma_f32_16x16x32_bf16 v[72:75], v[160:163], v[208:211], 0
	v_mfma_f32_16x16x32_bf16 v[124:127], v[156:159], v[188:191], v[124:127]
	v_mfma_f32_16x16x32_bf16 v[120:123], v[164:167], v[188:191], v[120:123]
	v_mfma_f32_16x16x32_bf16 v[108:111], v[156:159], v[196:199], v[108:111]
	v_mfma_f32_16x16x32_bf16 v[104:107], v[164:167], v[196:199], v[104:107]
	v_mfma_f32_16x16x32_bf16 v[92:95], v[156:159], v[204:207], v[92:95]
	v_mfma_f32_16x16x32_bf16 v[88:91], v[164:167], v[204:207], v[88:91]
	v_mfma_f32_16x16x32_bf16 v[76:79], v[156:159], v[212:215], v[76:79]
	v_mfma_f32_16x16x32_bf16 v[72:75], v[164:167], v[212:215], v[72:75]
	v_mfma_f32_16x16x32_bf16 v[116:119], v[168:171], v[184:187], 0
	v_mfma_f32_16x16x32_bf16 v[112:115], v[176:179], v[184:187], 0
	v_mfma_f32_16x16x32_bf16 v[100:103], v[168:171], v[192:195], 0
	v_mfma_f32_16x16x32_bf16 v[96:99], v[176:179], v[192:195], 0
	v_mfma_f32_16x16x32_bf16 v[84:87], v[168:171], v[200:203], 0
	v_mfma_f32_16x16x32_bf16 v[80:83], v[176:179], v[200:203], 0
	v_mfma_f32_16x16x32_bf16 v[68:71], v[168:171], v[208:211], 0
	v_mfma_f32_16x16x32_bf16 v[64:67], v[176:179], v[208:211], 0
	v_mfma_f32_16x16x32_bf16 v[116:119], v[172:175], v[188:191], v[116:119]
	v_mfma_f32_16x16x32_bf16 v[112:115], v[180:183], v[188:191], v[112:115]
	v_mfma_f32_16x16x32_bf16 v[100:103], v[172:175], v[196:199], v[100:103]
	v_mfma_f32_16x16x32_bf16 v[96:99], v[180:183], v[196:199], v[96:99]
	v_mfma_f32_16x16x32_bf16 v[84:87], v[172:175], v[204:207], v[84:87]
	v_mfma_f32_16x16x32_bf16 v[80:83], v[180:183], v[204:207], v[80:83]
	v_mfma_f32_16x16x32_bf16 v[68:71], v[172:175], v[212:215], v[68:71]
	v_mfma_f32_16x16x32_bf16 v[64:67], v[180:183], v[212:215], v[64:67]
	s_barrier
	s_setprio 0
	s_add_i32 s55, s44, s33
	v_lshl_add_u64 v[216:217], s[26:27], 0, v[132:133]
	s_mov_b32 m0, s55
	ds_read_b128 v[184:187], v150 offset:16384
	ds_read_b128 v[188:191], v150 offset:17408
	ds_read_b128 v[192:195], v150 offset:18432
	ds_read_b128 v[196:199], v150 offset:19456
	ds_read_b128 v[200:203], v150 offset:20480
	ds_read_b128 v[204:207], v150 offset:21504
	ds_read_b128 v[208:211], v150 offset:22528
	ds_read_b128 v[212:215], v150 offset:23552
	global_load_lds_dwordx4 v[216:217], off
	s_add_i32 m0, s55, 0x2000
	s_add_u32 s56, s26, 0x40000
	v_lshl_add_u64 v[218:219], s[26:27], 0, v[128:129]
	s_addc_u32 s57, s27, 0
	s_add_i32 s55, s45, s33
	global_load_lds_dwordx4 v[218:219], off
	s_mov_b32 m0, s55
	v_lshl_add_u64 v[222:223], s[28:29], 0, v[130:131]
	global_load_lds_dwordx4 v132, s[56:57]
	s_add_i32 m0, s55, 0x2000
	s_nop 0
	global_load_lds_dwordx4 v128, s[56:57]
	v_lshl_add_u64 v[220:221], s[28:29], 0, v[134:135]
	s_mov_b32 m0, s23
	s_nop 0
	global_load_lds_dwordx4 v[220:221], off
	s_mov_b32 m0, s39
	s_nop 0
	global_load_lds_dwordx4 v[222:223], off
	s_waitcnt vmcnt(8)
	s_waitcnt lgkmcnt(0)
	s_setprio 1
	s_barrier
	v_mfma_f32_16x16x32_bf16 v[60:63], v[152:155], v[184:187], 0
	v_mfma_f32_16x16x32_bf16 v[56:59], v[160:163], v[184:187], 0
	v_mfma_f32_16x16x32_bf16 v[44:47], v[152:155], v[192:195], 0
	v_mfma_f32_16x16x32_bf16 v[40:43], v[160:163], v[192:195], 0
	v_mfma_f32_16x16x32_bf16 v[28:31], v[152:155], v[200:203], 0
	v_mfma_f32_16x16x32_bf16 v[24:27], v[160:163], v[200:203], 0
	v_mfma_f32_16x16x32_bf16 v[12:15], v[152:155], v[208:211], 0
	v_mfma_f32_16x16x32_bf16 v[8:11], v[160:163], v[208:211], 0
	v_mfma_f32_16x16x32_bf16 v[60:63], v[156:159], v[188:191], v[60:63]
	v_mfma_f32_16x16x32_bf16 v[56:59], v[164:167], v[188:191], v[56:59]
	v_mfma_f32_16x16x32_bf16 v[44:47], v[156:159], v[196:199], v[44:47]
	v_mfma_f32_16x16x32_bf16 v[40:43], v[164:167], v[196:199], v[40:43]
	v_mfma_f32_16x16x32_bf16 v[28:31], v[156:159], v[204:207], v[28:31]
	v_mfma_f32_16x16x32_bf16 v[24:27], v[164:167], v[204:207], v[24:27]
	v_mfma_f32_16x16x32_bf16 v[12:15], v[156:159], v[212:215], v[12:15]
	v_mfma_f32_16x16x32_bf16 v[8:11], v[164:167], v[212:215], v[8:11]
	v_mfma_f32_16x16x32_bf16 v[52:55], v[168:171], v[184:187], 0
	v_mfma_f32_16x16x32_bf16 v[48:51], v[176:179], v[184:187], 0
	v_mfma_f32_16x16x32_bf16 v[36:39], v[168:171], v[192:195], 0
	v_mfma_f32_16x16x32_bf16 v[32:35], v[176:179], v[192:195], 0
	v_mfma_f32_16x16x32_bf16 v[20:23], v[168:171], v[200:203], 0
	v_mfma_f32_16x16x32_bf16 v[16:19], v[176:179], v[200:203], 0
	v_mfma_f32_16x16x32_bf16 v[4:7], v[168:171], v[208:211], 0
	v_mfma_f32_16x16x32_bf16 v[0:3], v[176:179], v[208:211], 0
	v_mfma_f32_16x16x32_bf16 v[52:55], v[172:175], v[188:191], v[52:55]
	v_mfma_f32_16x16x32_bf16 v[48:51], v[180:183], v[188:191], v[48:51]
	v_mfma_f32_16x16x32_bf16 v[36:39], v[172:175], v[196:199], v[36:39]
	v_mfma_f32_16x16x32_bf16 v[32:35], v[180:183], v[196:199], v[32:35]
	v_mfma_f32_16x16x32_bf16 v[20:23], v[172:175], v[204:207], v[20:23]
	v_mfma_f32_16x16x32_bf16 v[16:19], v[180:183], v[204:207], v[16:19]
	v_mfma_f32_16x16x32_bf16 v[4:7], v[172:175], v[212:215], v[4:7]
	v_mfma_f32_16x16x32_bf16 v[0:3], v[180:183], v[212:215], v[0:3]
	s_barrier
; #define PG8_STAGE(bufoff, gbase, voff) do { _Pragma("unroll") for (int _i = 0; _i < 2; ++_i) \
;         __builtin_amdgcn_global_load_lds((const unsigned*)((const char*)(gbase) + (voff)[_i]), (PG8_LAS unsigned*)(lds + (bufoff) + ldsw + _i * 8192), 16, 0, 0); } while (0)
; #define PG8_LDA(dst, b, h) do { _Pragma("unroll") for (int m = 0; m < 4; ++m) _Pragma("unroll") for (int k = 0; k < 2; ++k) dst[m][k] = *(const PG8_LAS bf16x8*)(lds + PG8_SA(b, h) + aoff + m * 2048 + k * 1024); } while (0)
; #define PG8_LDB(dst, b, h) do { _Pragma("unroll") for (int n = 0; n < 2; ++n) _Pragma("unroll") for (int k = 0; k < 2; ++k) dst[n][k] = *(const PG8_LAS bf16x8*)(lds + PG8_SB(b, h) + boff + n * 2048 + k * 1024); } while (0)
; #define PG8_MMA(ai, bj, At, Bt) do { __builtin_amdgcn_s_setprio(1); _Pragma("unroll") for (int m = 0; m < 4; ++m) _Pragma("unroll") for (int n = 0; n < 2; ++n) _Pragma("unroll") for (int k = 0; k < 2; ++k) \
;         acc[ai][bj][m][n] = __builtin_amdgcn_mfma_f32_16x16x32_bf16(Bt[n][k], At[m][k], acc[ai][bj][m][n], 0, 0, 0); __builtin_amdgcn_s_setprio(0); } while (0)
; #define PG8_WAIT_V(n) asm volatile("s_waitcnt vmcnt(" #n ")" ::: "memory")
; #define PG8_WAIT_L(n) asm volatile("s_waitcnt lgkmcnt(" #n ")" ::: "memory")
; #define PG8_BAR __builtin_amdgcn_s_barrier()
; #define PG8_SCHED __builtin_amdgcn_sched_barrier(0)
; template <class Epi, class Sched, bool ALIGN_EPI = false, bool SP2 = false>
; __device__ __forceinline__ void gemm_phase(PG8_LAS unsigned char* lds, const Gemm g, const Sched& S, const Epi& E) {
;     ...
;             PG8_LDB(B0, 1, 0); PG8_LDB(B1, 1, 1); PG8_SCHED; PG8_LDA(At, 1, 0); PG8_STAGE(PG8_SA(0, 1), a2 + hstep, voffA);
;             PG8_WAIT_V(8); PG8_WAIT_L(0); PG8_BAR; PG8_MMA(0, 0, At, B0); PG8_MMA(0, 1, At, B1); PG8_BAR; PG8_SCHED;
;             PG8_LDA(At, 1, 1); PG8_STAGE(PG8_SB(1, 0), b3, voffB); PG8_STAGE(PG8_SB(1, 1), b3 + hstep, voffB); PG8_STAGE(PG8_SA(1, 0), a3, voffA);
;             PG8_WAIT_V(8); PG8_WAIT_L(0); PG8_BAR; PG8_MMA(1, 0, At, B0); PG8_MMA(1, 1, At, B1); PG8_BAR; PG8_SCHED;
	s_setprio 0
	s_add_i32 s55, 0, 0x18000
	v_add_u32_e32 v151, s55, v145
	s_add_i32 s56, 0, 0x1c000
	ds_read_b128 v[152:155], v151
	ds_read_b128 v[156:159], v151 offset:1024
	ds_read_b128 v[160:163], v151 offset:2048
	ds_read_b128 v[164:167], v151 offset:3072
	v_add_u32_e32 v151, s56, v145
	ds_read_b128 v[168:171], v151
	ds_read_b128 v[172:175], v151 offset:1024
	ds_read_b128 v[176:179], v151 offset:2048
	ds_read_b128 v[180:183], v151 offset:3072
	s_add_u32 s28, s28, 0x40000
	s_addc_u32 s29, s29, 0
	s_mov_b32 m0, s40
	ds_read_b128 v[184:187], v150 offset:32768
	ds_read_b128 v[188:191], v150 offset:33792
	ds_read_b128 v[192:195], v150 offset:34816
	ds_read_b128 v[196:199], v150 offset:35840
	ds_read_b128 v[200:203], v150 offset:36864
	ds_read_b128 v[204:207], v150 offset:37888
	ds_read_b128 v[208:211], v150 offset:38912
	ds_read_b128 v[212:215], v150 offset:39936
	global_load_lds_dwordx4 v134, s[28:29]
	s_mov_b32 m0, s41
	s_nop 0
	global_load_lds_dwordx4 v130, s[28:29]
	s_waitcnt vmcnt(8)
	s_waitcnt lgkmcnt(0)
	s_setprio 1
	s_barrier
	v_mfma_f32_16x16x32_bf16 v[124:127], v[152:155], v[184:187], v[124:127]
	v_mfma_f32_16x16x32_bf16 v[120:123], v[160:163], v[184:187], v[120:123]
	v_mfma_f32_16x16x32_bf16 v[108:111], v[152:155], v[192:195], v[108:111]
	v_mfma_f32_16x16x32_bf16 v[104:107], v[160:163], v[192:195], v[104:107]
	v_mfma_f32_16x16x32_bf16 v[92:95], v[152:155], v[200:203], v[92:95]
	v_mfma_f32_16x16x32_bf16 v[88:91], v[160:163], v[200:203], v[88:91]
	v_mfma_f32_16x16x32_bf16 v[76:79], v[152:155], v[208:211], v[76:79]
	v_mfma_f32_16x16x32_bf16 v[72:75], v[160:163], v[208:211], v[72:75]
	v_mfma_f32_16x16x32_bf16 v[124:127], v[156:159], v[188:191], v[124:127]
	v_mfma_f32_16x16x32_bf16 v[120:123], v[164:167], v[188:191], v[120:123]
	v_mfma_f32_16x16x32_bf16 v[108:111], v[156:159], v[196:199], v[108:111]
	v_mfma_f32_16x16x32_bf16 v[104:107], v[164:167], v[196:199], v[104:107]
	v_mfma_f32_16x16x32_bf16 v[92:95], v[156:159], v[204:207], v[92:95]
	v_mfma_f32_16x16x32_bf16 v[88:91], v[164:167], v[204:207], v[88:91]
	v_mfma_f32_16x16x32_bf16 v[76:79], v[156:159], v[212:215], v[76:79]
	v_mfma_f32_16x16x32_bf16 v[72:75], v[164:167], v[212:215], v[72:75]
	v_mfma_f32_16x16x32_bf16 v[116:119], v[168:171], v[184:187], v[116:119]
	v_mfma_f32_16x16x32_bf16 v[112:115], v[176:179], v[184:187], v[112:115]
	v_mfma_f32_16x16x32_bf16 v[100:103], v[168:171], v[192:195], v[100:103]
	v_mfma_f32_16x16x32_bf16 v[96:99], v[176:179], v[192:195], v[96:99]
	v_mfma_f32_16x16x32_bf16 v[84:87], v[168:171], v[200:203], v[84:87]
	v_mfma_f32_16x16x32_bf16 v[80:83], v[176:179], v[200:203], v[80:83]
	v_mfma_f32_16x16x32_bf16 v[68:71], v[168:171], v[208:211], v[68:71]
	v_mfma_f32_16x16x32_bf16 v[64:67], v[176:179], v[208:211], v[64:67]
	v_mfma_f32_16x16x32_bf16 v[116:119], v[172:175], v[188:191], v[116:119]
	v_mfma_f32_16x16x32_bf16 v[112:115], v[180:183], v[188:191], v[112:115]
	v_mfma_f32_16x16x32_bf16 v[100:103], v[172:175], v[196:199], v[100:103]
	v_mfma_f32_16x16x32_bf16 v[96:99], v[180:183], v[196:199], v[96:99]
	v_mfma_f32_16x16x32_bf16 v[84:87], v[172:175], v[204:207], v[84:87]
	v_mfma_f32_16x16x32_bf16 v[80:83], v[180:183], v[204:207], v[80:83]
	v_mfma_f32_16x16x32_bf16 v[68:71], v[172:175], v[212:215], v[68:71]
	v_mfma_f32_16x16x32_bf16 v[64:67], v[180:183], v[212:215], v[64:67]
	s_barrier
	s_setprio 0
	s_add_i32 s28, s55, s33
	v_lshl_add_u64 v[216:217], v[216:217], 0, s[10:11]
	s_mov_b32 m0, s28
	ds_read_b128 v[184:187], v150 offset:49152
	ds_read_b128 v[188:191], v150 offset:50176
	ds_read_b128 v[192:195], v150 offset:51200
	ds_read_b128 v[196:199], v150 offset:52224
	ds_read_b128 v[200:203], v150 offset:53248
	ds_read_b128 v[204:207], v150 offset:54272
	ds_read_b128 v[208:211], v150 offset:55296
	ds_read_b128 v[212:215], v150 offset:56320
	global_load_lds_dwordx4 v[216:217], off
	s_add_i32 m0, s28, 0x2000
	s_add_u32 s26, s26, 0x40080
	v_lshl_add_u64 v[216:217], v[218:219], 0, s[10:11]
	s_addc_u32 s27, s27, 0
	s_add_i32 s28, s56, s33
	global_load_lds_dwordx4 v[216:217], off
	s_mov_b32 m0, s28
	s_nop 0
	global_load_lds_dwordx4 v132, s[26:27]
	s_add_i32 m0, s28, 0x2000
	s_nop 0
	global_load_lds_dwordx4 v128, s[26:27]
	v_lshl_add_u64 v[216:217], v[220:221], 0, s[10:11]
	s_mov_b32 m0, s42
	s_nop 0
	global_load_lds_dwordx4 v[216:217], off
	v_lshl_add_u64 v[216:217], v[222:223], 0, s[10:11]
	s_mov_b32 m0, s43
	s_nop 0
	global_load_lds_dwordx4 v[216:217], off
	s_waitcnt vmcnt(8)
	s_waitcnt lgkmcnt(0)
	s_setprio 1
	s_barrier
	v_mfma_f32_16x16x32_bf16 v[60:63], v[152:155], v[184:187], v[60:63]
	v_mfma_f32_16x16x32_bf16 v[56:59], v[160:163], v[184:187], v[56:59]
	v_mfma_f32_16x16x32_bf16 v[44:47], v[152:155], v[192:195], v[44:47]
	v_mfma_f32_16x16x32_bf16 v[40:43], v[160:163], v[192:195], v[40:43]
	v_mfma_f32_16x16x32_bf16 v[28:31], v[152:155], v[200:203], v[28:31]
	v_mfma_f32_16x16x32_bf16 v[24:27], v[160:163], v[200:203], v[24:27]
	v_mfma_f32_16x16x32_bf16 v[12:15], v[152:155], v[208:211], v[12:15]
	v_mfma_f32_16x16x32_bf16 v[8:11], v[160:163], v[208:211], v[8:11]
	v_mfma_f32_16x16x32_bf16 v[60:63], v[156:159], v[188:191], v[60:63]
	v_mfma_f32_16x16x32_bf16 v[56:59], v[164:167], v[188:191], v[56:59]
	v_mfma_f32_16x16x32_bf16 v[44:47], v[156:159], v[196:199], v[44:47]
	v_mfma_f32_16x16x32_bf16 v[40:43], v[164:167], v[196:199], v[40:43]
	v_mfma_f32_16x16x32_bf16 v[28:31], v[156:159], v[204:207], v[28:31]
	v_mfma_f32_16x16x32_bf16 v[24:27], v[164:167], v[204:207], v[24:27]
	v_mfma_f32_16x16x32_bf16 v[12:15], v[156:159], v[212:215], v[12:15]
	v_mfma_f32_16x16x32_bf16 v[8:11], v[164:167], v[212:215], v[8:11]
	v_mfma_f32_16x16x32_bf16 v[52:55], v[168:171], v[184:187], v[52:55]
	v_mfma_f32_16x16x32_bf16 v[48:51], v[176:179], v[184:187], v[48:51]
	v_mfma_f32_16x16x32_bf16 v[36:39], v[168:171], v[192:195], v[36:39]
	v_mfma_f32_16x16x32_bf16 v[32:35], v[176:179], v[192:195], v[32:35]
	v_mfma_f32_16x16x32_bf16 v[20:23], v[168:171], v[200:203], v[20:23]
	v_mfma_f32_16x16x32_bf16 v[16:19], v[176:179], v[200:203], v[16:19]
	v_mfma_f32_16x16x32_bf16 v[4:7], v[168:171], v[208:211], v[4:7]
	v_mfma_f32_16x16x32_bf16 v[0:3], v[176:179], v[208:211], v[0:3]
	v_mfma_f32_16x16x32_bf16 v[52:55], v[172:175], v[188:191], v[52:55]
	v_mfma_f32_16x16x32_bf16 v[48:51], v[180:183], v[188:191], v[48:51]
	v_mfma_f32_16x16x32_bf16 v[36:39], v[172:175], v[196:199], v[36:39]
	v_mfma_f32_16x16x32_bf16 v[32:35], v[180:183], v[196:199], v[32:35]
	v_mfma_f32_16x16x32_bf16 v[20:23], v[172:175], v[204:207], v[20:23]
	v_mfma_f32_16x16x32_bf16 v[16:19], v[180:183], v[204:207], v[16:19]
	v_mfma_f32_16x16x32_bf16 v[4:7], v[172:175], v[212:215], v[4:7]
	v_mfma_f32_16x16x32_bf16 v[0:3], v[180:183], v[212:215], v[0:3]
	s_barrier
	s_setprio 0
	s_add_i32 s54, s54, 2
	s_add_u32 s24, s24, 0x100
	s_addc_u32 s25, s25, 0
	s_add_u32 s52, s52, 0x100
	s_addc_u32 s53, s53, 0
	s_cmp_gt_u32 s54, 13
	.p2align 6
